# stack14: GEMM loop-control and head pointer SALU hoisted from the post-barrier path into the end of the preceding DMA-heavy load segment (on top of stack12)
# speedup vs baseline: 1.0040x; 1.0040x over previous
; #define PG8_STAGE(bufoff, gbase, voff) do { _Pragma("unroll") for (int _i = 0; _i < 2; ++_i) \
;         __builtin_amdgcn_global_load_lds((const unsigned*)((const char*)(gbase) + (voff)[_i]), (PG8_LAS unsigned*)(lds + (bufoff) + ldsw + _i * 8192), 16, 0, 0); } while (0)
; #define PG8_LDA(dst, b, h) do { _Pragma("unroll") for (int m = 0; m < 4; ++m) _Pragma("unroll") for (int k = 0; k < 2; ++k) dst[m][k] = *(const PG8_LAS bf16x8*)(lds + PG8_SA(b, h) + aoff + m * 2048 + k * 1024); } while (0)
; #define PG8_LDB(dst, b, h) do { _Pragma("unroll") for (int n = 0; n < 2; ++n) _Pragma("unroll") for (int k = 0; k < 2; ++k) dst[n][k] = *(const PG8_LAS bf16x8*)(lds + PG8_SB(b, h) + boff + n * 2048 + k * 1024); } while (0)
; #define PG8_MMA(ai, bj, At, Bt) do { __builtin_amdgcn_s_setprio(1); _Pragma("unroll") for (int m = 0; m < 4; ++m) _Pragma("unroll") for (int n = 0; n < 2; ++n) _Pragma("unroll") for (int k = 0; k < 2; ++k) \
;         acc[ai][bj][m][n] = __builtin_amdgcn_mfma_f32_16x16x32_bf16(Bt[n][k], At[m][k], acc[ai][bj][m][n], 0, 0, 0); __builtin_amdgcn_s_setprio(0); } while (0)
; #define PG8_WAIT_V(n) asm volatile("s_waitcnt vmcnt(" #n ")" ::: "memory")
; #define PG8_BAR __builtin_amdgcn_s_barrier()
; template <class Epi, class Sched, bool ALIGN_EPI = false, bool SP2 = false>
; __device__ __forceinline__ void gemm_phase(PG8_LAS unsigned char* lds, const Gemm g, const Sched& S, const Epi& E, const int wid_in) {
;     ...
;         for (int t = 0; t < nt; t += 2) {
;             const bool last = (t == nt - 2);
;             const char* a1 = cA + (size_t)(t + 1) * kstep;
;             const char* a2 = last ? nA : cA + (size_t)(t + 2) * kstep; const char* b2 = last ? nB : cB + (size_t)(t + 2) * kstep;
;             const char* a3 = a2 + kstep; const char* b3 = b2 + kstep;
;             if (last && has_next) S.a_ready(nxt);
;             if constexpr (SP2) {
;             PG8_LDB(B0, 0, 0); PG8_LDB(B1, 0, 1); PG8_SCHED; PG8_LDA(At, 0, 0); PG8_STAGE(PG8_SA(1, 1), a1 + hstep, voffA);
;             PG8_WAIT_V(8); PG8_WAIT_L(0); PG8_BAR; PG8_MMA(0, 0, At, B0); PG8_MMA(0, 1, At, B1); PG8_BAR; PG8_SCHED;
;             PG8_LDA(At, 0, 1); PG8_STAGE(PG8_SB(0, 0), b2, voffB); PG8_STAGE(PG8_SB(0, 1), b2 + hstep, voffB); PG8_STAGE(PG8_SA(0, 0), a2, voffA);
;             PG8_WAIT_V(8); PG8_WAIT_L(0); PG8_BAR; PG8_MMA(1, 0, At, B0); PG8_MMA(1, 1, At, B1); PG8_BAR; PG8_SCHED;
.Lprio_done_105:
	s_add_u32 s2, s48, 0xfffc0080
	s_addc_u32 s8, s49, -1
	s_add_i32 s22, 0, 0x10000
	s_cmp_eq_u32 s60, 12
	s_cselect_b32 s53, s43, s8
	s_cselect_b32 s52, s57, s2
	s_cselect_b32 s51, s16, s59
	s_cselect_b32 s50, s41, s58
	s_add_i32 s2, 0, 0x14000
	v_add_u32_e32 v154, s22, v144
	v_add_u32_e32 v170, s2, v144
	ds_read_b128 v[140:143], v154
	ds_read_b128 v[146:149], v154 offset:1024
	ds_read_b128 v[150:153], v154 offset:2048
	ds_read_b128 v[154:157], v154 offset:3072
	ds_read_b128 v[158:161], v170
	ds_read_b128 v[162:165], v170 offset:1024
	ds_read_b128 v[166:169], v170 offset:2048
	ds_read_b128 v[170:173], v170 offset:3072
	v_lshl_add_u64 v[228:229], s[48:49], 0, v[136:137]
	s_add_i32 m0, s4, 0xc000
	ds_read_b128 v[174:177], v145
	ds_read_b128 v[190:193], v145 offset:1024
	ds_read_b128 v[194:197], v145 offset:2048
	ds_read_b128 v[198:201], v145 offset:3072
	ds_read_b128 v[212:215], v145 offset:4096
	ds_read_b128 v[216:219], v145 offset:5120
	ds_read_b128 v[220:223], v145 offset:6144
	ds_read_b128 v[224:227], v145 offset:7168
	global_load_lds_dwordx4 v[228:229], off
	v_lshl_add_u64 v[228:229], s[48:49], 0, v[138:139]
	s_add_i32 m0, s4, 0xe000
	s_nop 0
	global_load_lds_dwordx4 v[228:229], off
	s_waitcnt vmcnt(8)
	s_waitcnt lgkmcnt(0)
	s_barrier
	s_waitcnt lgkmcnt(0)
	v_mfma_f32_16x16x32_bf16 v[126:129], v[140:143], v[174:177], 0
	v_mfma_f32_16x16x32_bf16 v[122:125], v[150:153], v[174:177], 0
	v_mfma_f32_16x16x32_bf16 v[114:117], v[140:143], v[194:197], 0
	v_mfma_f32_16x16x32_bf16 v[110:113], v[150:153], v[194:197], 0
	v_mfma_f32_16x16x32_bf16 v[98:101], v[140:143], v[212:215], 0
	v_mfma_f32_16x16x32_bf16 v[94:97], v[150:153], v[212:215], 0
	v_mfma_f32_16x16x32_bf16 v[82:85], v[140:143], v[220:223], 0
	v_mfma_f32_16x16x32_bf16 v[78:81], v[150:153], v[220:223], 0
	v_mfma_f32_16x16x32_bf16 v[126:129], v[146:149], v[190:193], v[126:129]
	v_mfma_f32_16x16x32_bf16 v[122:125], v[154:157], v[190:193], v[122:125]
	v_mfma_f32_16x16x32_bf16 v[114:117], v[146:149], v[198:201], v[114:117]
	v_mfma_f32_16x16x32_bf16 v[110:113], v[154:157], v[198:201], v[110:113]
	v_mfma_f32_16x16x32_bf16 v[98:101], v[146:149], v[216:219], v[98:101]
	v_mfma_f32_16x16x32_bf16 v[94:97], v[154:157], v[216:219], v[94:97]
	v_mfma_f32_16x16x32_bf16 v[82:85], v[146:149], v[224:227], v[82:85]
	v_mfma_f32_16x16x32_bf16 v[78:81], v[154:157], v[224:227], v[78:81]
	v_mfma_f32_16x16x32_bf16 v[106:109], v[158:161], v[174:177], 0
	v_mfma_f32_16x16x32_bf16 v[118:121], v[166:169], v[174:177], 0
	v_mfma_f32_16x16x32_bf16 v[90:93], v[158:161], v[194:197], 0
	v_mfma_f32_16x16x32_bf16 v[102:105], v[166:169], v[194:197], 0
	v_mfma_f32_16x16x32_bf16 v[74:77], v[158:161], v[212:215], 0
	v_mfma_f32_16x16x32_bf16 v[86:89], v[166:169], v[212:215], 0
	v_mfma_f32_16x16x32_bf16 v[66:69], v[158:161], v[220:223], 0
	v_mfma_f32_16x16x32_bf16 v[70:73], v[166:169], v[220:223], 0
	v_mfma_f32_16x16x32_bf16 v[106:109], v[162:165], v[190:193], v[106:109]
	v_mfma_f32_16x16x32_bf16 v[118:121], v[170:173], v[190:193], v[118:121]
	v_mfma_f32_16x16x32_bf16 v[90:93], v[162:165], v[198:201], v[90:93]
	v_mfma_f32_16x16x32_bf16 v[102:105], v[170:173], v[198:201], v[102:105]
	v_mfma_f32_16x16x32_bf16 v[74:77], v[162:165], v[216:219], v[74:77]
	v_mfma_f32_16x16x32_bf16 v[86:89], v[170:173], v[216:219], v[86:89]
	v_mfma_f32_16x16x32_bf16 v[66:69], v[162:165], v[224:227], v[66:69]
	v_mfma_f32_16x16x32_bf16 v[70:73], v[170:173], v[224:227], v[70:73]
	s_barrier
	s_add_i32 s8, s22, s3
	v_lshl_add_u64 v[228:229], s[50:51], 0, v[0:1]
	s_mov_b32 m0, s8
	ds_read_b128 v[174:177], v145 offset:16384
	ds_read_b128 v[190:193], v145 offset:17408
	ds_read_b128 v[194:197], v145 offset:18432
	ds_read_b128 v[198:201], v145 offset:19456
	ds_read_b128 v[212:215], v145 offset:20480
	ds_read_b128 v[216:219], v145 offset:21504
	ds_read_b128 v[220:223], v145 offset:22528
	ds_read_b128 v[224:227], v145 offset:23552
	global_load_lds_dwordx4 v[228:229], off
	s_add_i32 m0, s8, 0x2000
	s_add_u32 s22, s50, 0x40000
	v_lshl_add_u64 v[230:231], s[50:51], 0, v[130:131]
	s_addc_u32 s23, s51, 0
	s_add_i32 s2, s2, s3
	global_load_lds_dwordx4 v[230:231], off
	v_lshl_add_u64 v[232:233], s[22:23], 0, v[0:1]
	s_mov_b32 m0, s2
	v_lshl_add_u64 v[234:235], s[52:53], 0, v[132:133]
	global_load_lds_dwordx4 v[232:233], off
	v_lshl_add_u64 v[232:233], s[22:23], 0, v[130:131]
	s_add_i32 m0, s2, 0x2000
	s_nop 0
	global_load_lds_dwordx4 v[232:233], off
	v_lshl_add_u64 v[232:233], s[52:53], 0, v[134:135]
	s_mov_b32 m0, s4
	s_nop 0
	global_load_lds_dwordx4 v[232:233], off
	s_mov_b32 m0, s5
	s_nop 0
	global_load_lds_dwordx4 v[234:235], off
	s_waitcnt vmcnt(8)
	s_waitcnt lgkmcnt(0)
	s_barrier
; #define PG8_STAGE(bufoff, gbase, voff) do { _Pragma("unroll") for (int _i = 0; _i < 2; ++_i) \
;         __builtin_amdgcn_global_load_lds((const unsigned*)((const char*)(gbase) + (voff)[_i]), (PG8_LAS unsigned*)(lds + (bufoff) + ldsw + _i * 8192), 16, 0, 0); } while (0)
; #define PG8_LDA(dst, b, h) do { _Pragma("unroll") for (int m = 0; m < 4; ++m) _Pragma("unroll") for (int k = 0; k < 2; ++k) dst[m][k] = *(const PG8_LAS bf16x8*)(lds + PG8_SA(b, h) + aoff + m * 2048 + k * 1024); } while (0)
; #define PG8_LDB(dst, b, h) do { _Pragma("unroll") for (int n = 0; n < 2; ++n) _Pragma("unroll") for (int k = 0; k < 2; ++k) dst[n][k] = *(const PG8_LAS bf16x8*)(lds + PG8_SB(b, h) + boff + n * 2048 + k * 1024); } while (0)
; #define PG8_MMA(ai, bj, At, Bt) do { __builtin_amdgcn_s_setprio(1); _Pragma("unroll") for (int m = 0; m < 4; ++m) _Pragma("unroll") for (int n = 0; n < 2; ++n) _Pragma("unroll") for (int k = 0; k < 2; ++k) \
;         acc[ai][bj][m][n] = __builtin_amdgcn_mfma_f32_16x16x32_bf16(Bt[n][k], At[m][k], acc[ai][bj][m][n], 0, 0, 0); __builtin_amdgcn_s_setprio(0); } while (0)
; #define PG8_WAIT_V(n) asm volatile("s_waitcnt vmcnt(" #n ")" ::: "memory")
; #define PG8_WAIT_L(n) asm volatile("s_waitcnt lgkmcnt(" #n ")" ::: "memory")
; #define PG8_BAR __builtin_amdgcn_s_barrier()
; #define PG8_SCHED __builtin_amdgcn_sched_barrier(0)
; template <class Epi, class Sched, bool ALIGN_EPI = false, bool SP2 = false>
; __device__ __forceinline__ void gemm_phase(PG8_LAS unsigned char* lds, const Gemm g, const Sched& S, const Epi& E, const int wid_in) {
;     ...
;             PG8_LDA(At, 0, 1); PG8_STAGE(PG8_SB(0, 0), b2, voffB); PG8_STAGE(PG8_SB(0, 1), b2 + hstep, voffB); PG8_STAGE(PG8_SA(0, 0), a2, voffA);
;             PG8_WAIT_V(8); PG8_WAIT_L(0); PG8_BAR; PG8_MMA(1, 0, At, B0); PG8_MMA(1, 1, At, B1); PG8_BAR; PG8_SCHED;
;             PG8_LDB(B0, 1, 0); PG8_LDB(B1, 1, 1); PG8_SCHED; PG8_LDA(At, 1, 0); PG8_STAGE(PG8_SA(0, 1), a2 + hstep, voffA);
;             PG8_WAIT_V(8); PG8_WAIT_L(0); PG8_BAR; PG8_MMA(0, 0, At, B0); PG8_MMA(0, 1, At, B1); PG8_BAR; PG8_SCHED;
	s_waitcnt lgkmcnt(0)
	v_mfma_f32_16x16x32_bf16 v[62:65], v[140:143], v[174:177], 0
	v_mfma_f32_16x16x32_bf16 v[58:61], v[150:153], v[174:177], 0
	v_mfma_f32_16x16x32_bf16 v[50:53], v[140:143], v[194:197], 0
	v_mfma_f32_16x16x32_bf16 v[46:49], v[150:153], v[194:197], 0
	v_mfma_f32_16x16x32_bf16 v[34:37], v[140:143], v[212:215], 0
	v_mfma_f32_16x16x32_bf16 v[30:33], v[150:153], v[212:215], 0
	v_mfma_f32_16x16x32_bf16 v[18:21], v[140:143], v[220:223], 0
	v_mfma_f32_16x16x32_bf16 v[14:17], v[150:153], v[220:223], 0
	v_mfma_f32_16x16x32_bf16 v[62:65], v[146:149], v[190:193], v[62:65]
	v_mfma_f32_16x16x32_bf16 v[58:61], v[154:157], v[190:193], v[58:61]
	v_mfma_f32_16x16x32_bf16 v[50:53], v[146:149], v[198:201], v[50:53]
	v_mfma_f32_16x16x32_bf16 v[46:49], v[154:157], v[198:201], v[46:49]
	v_mfma_f32_16x16x32_bf16 v[34:37], v[146:149], v[216:219], v[34:37]
	v_mfma_f32_16x16x32_bf16 v[30:33], v[154:157], v[216:219], v[30:33]
	v_mfma_f32_16x16x32_bf16 v[18:21], v[146:149], v[224:227], v[18:21]
	v_mfma_f32_16x16x32_bf16 v[14:17], v[154:157], v[224:227], v[14:17]
	v_mfma_f32_16x16x32_bf16 v[42:45], v[158:161], v[174:177], 0
	v_mfma_f32_16x16x32_bf16 v[54:57], v[166:169], v[174:177], 0
	v_mfma_f32_16x16x32_bf16 v[26:29], v[158:161], v[194:197], 0
	v_mfma_f32_16x16x32_bf16 v[38:41], v[166:169], v[194:197], 0
	v_mfma_f32_16x16x32_bf16 v[10:13], v[158:161], v[212:215], 0
	v_mfma_f32_16x16x32_bf16 v[22:25], v[166:169], v[212:215], 0
	v_mfma_f32_16x16x32_bf16 v[2:5], v[158:161], v[220:223], 0
	v_mfma_f32_16x16x32_bf16 v[6:9], v[166:169], v[220:223], 0
	v_mfma_f32_16x16x32_bf16 v[42:45], v[162:165], v[190:193], v[42:45]
	v_mfma_f32_16x16x32_bf16 v[54:57], v[170:173], v[190:193], v[54:57]
	v_mfma_f32_16x16x32_bf16 v[26:29], v[162:165], v[198:201], v[26:29]
	v_mfma_f32_16x16x32_bf16 v[38:41], v[170:173], v[198:201], v[38:41]
	v_mfma_f32_16x16x32_bf16 v[10:13], v[162:165], v[216:219], v[10:13]
	v_mfma_f32_16x16x32_bf16 v[22:25], v[170:173], v[216:219], v[22:25]
	v_mfma_f32_16x16x32_bf16 v[2:5], v[162:165], v[224:227], v[2:5]
	v_mfma_f32_16x16x32_bf16 v[6:9], v[170:173], v[224:227], v[6:9]
	s_barrier
	s_add_i32 s2, 0, 0x18000
	s_add_i32 s8, 0, 0x1c000
	v_add_u32_e32 v154, s2, v144
	v_add_u32_e32 v170, s8, v144
	ds_read_b128 v[140:143], v154
	ds_read_b128 v[146:149], v154 offset:1024
	ds_read_b128 v[150:153], v154 offset:2048
	ds_read_b128 v[154:157], v154 offset:3072
	ds_read_b128 v[158:161], v170
	ds_read_b128 v[162:165], v170 offset:1024
	ds_read_b128 v[166:169], v170 offset:2048
	ds_read_b128 v[170:173], v170 offset:3072
	s_add_u32 s22, s52, 0x40000
	s_addc_u32 s23, s53, 0
	s_mov_b32 m0, s12
	v_lshl_add_u64 v[236:237], s[22:23], 0, v[134:135]
	ds_read_b128 v[174:177], v145 offset:32768
	ds_read_b128 v[190:193], v145 offset:33792
	ds_read_b128 v[194:197], v145 offset:34816
	ds_read_b128 v[198:201], v145 offset:35840
	ds_read_b128 v[212:215], v145 offset:36864
	ds_read_b128 v[216:219], v145 offset:37888
	ds_read_b128 v[220:223], v145 offset:38912
	ds_read_b128 v[224:227], v145 offset:39936
	global_load_lds_dwordx4 v[236:237], off
	v_lshl_add_u64 v[236:237], s[22:23], 0, v[132:133]
	s_mov_b32 m0, s13
	s_nop 0
	global_load_lds_dwordx4 v[236:237], off
	s_waitcnt vmcnt(8)
	s_waitcnt lgkmcnt(0)
	s_barrier
	s_waitcnt lgkmcnt(0)
	v_mfma_f32_16x16x32_bf16 v[126:129], v[140:143], v[174:177], v[126:129]
	v_mfma_f32_16x16x32_bf16 v[122:125], v[150:153], v[174:177], v[122:125]
	v_mfma_f32_16x16x32_bf16 v[114:117], v[140:143], v[194:197], v[114:117]
	v_mfma_f32_16x16x32_bf16 v[110:113], v[150:153], v[194:197], v[110:113]
	v_mfma_f32_16x16x32_bf16 v[98:101], v[140:143], v[212:215], v[98:101]
	v_mfma_f32_16x16x32_bf16 v[94:97], v[150:153], v[212:215], v[94:97]
	v_mfma_f32_16x16x32_bf16 v[82:85], v[140:143], v[220:223], v[82:85]
	v_mfma_f32_16x16x32_bf16 v[78:81], v[150:153], v[220:223], v[78:81]
	v_mfma_f32_16x16x32_bf16 v[126:129], v[146:149], v[190:193], v[126:129]
	v_mfma_f32_16x16x32_bf16 v[122:125], v[154:157], v[190:193], v[122:125]
	v_mfma_f32_16x16x32_bf16 v[114:117], v[146:149], v[198:201], v[114:117]
	v_mfma_f32_16x16x32_bf16 v[110:113], v[154:157], v[198:201], v[110:113]
	v_mfma_f32_16x16x32_bf16 v[98:101], v[146:149], v[216:219], v[98:101]
	v_mfma_f32_16x16x32_bf16 v[94:97], v[154:157], v[216:219], v[94:97]
	v_mfma_f32_16x16x32_bf16 v[82:85], v[146:149], v[224:227], v[82:85]
	v_mfma_f32_16x16x32_bf16 v[78:81], v[154:157], v[224:227], v[78:81]
	v_mfma_f32_16x16x32_bf16 v[106:109], v[158:161], v[174:177], v[106:109]
	v_mfma_f32_16x16x32_bf16 v[118:121], v[166:169], v[174:177], v[118:121]
	v_mfma_f32_16x16x32_bf16 v[90:93], v[158:161], v[194:197], v[90:93]
	v_mfma_f32_16x16x32_bf16 v[102:105], v[166:169], v[194:197], v[102:105]
	v_mfma_f32_16x16x32_bf16 v[74:77], v[158:161], v[212:215], v[74:77]
	v_mfma_f32_16x16x32_bf16 v[86:89], v[166:169], v[212:215], v[86:89]
	v_mfma_f32_16x16x32_bf16 v[66:69], v[158:161], v[220:223], v[66:69]
	v_mfma_f32_16x16x32_bf16 v[70:73], v[166:169], v[220:223], v[70:73]
	v_mfma_f32_16x16x32_bf16 v[106:109], v[162:165], v[190:193], v[106:109]
	v_mfma_f32_16x16x32_bf16 v[118:121], v[170:173], v[190:193], v[118:121]
	v_mfma_f32_16x16x32_bf16 v[90:93], v[162:165], v[198:201], v[90:93]
	v_mfma_f32_16x16x32_bf16 v[102:105], v[170:173], v[198:201], v[102:105]
	v_mfma_f32_16x16x32_bf16 v[74:77], v[162:165], v[216:219], v[74:77]
	v_mfma_f32_16x16x32_bf16 v[86:89], v[170:173], v[216:219], v[86:89]
	v_mfma_f32_16x16x32_bf16 v[66:69], v[162:165], v[224:227], v[66:69]
	v_mfma_f32_16x16x32_bf16 v[70:73], v[170:173], v[224:227], v[70:73]
	s_barrier
; #define PG8_STAGE(bufoff, gbase, voff) do { _Pragma("unroll") for (int _i = 0; _i < 2; ++_i) \
;         __builtin_amdgcn_global_load_lds((const unsigned*)((const char*)(gbase) + (voff)[_i]), (PG8_LAS unsigned*)(lds + (bufoff) + ldsw + _i * 8192), 16, 0, 0); } while (0)
; #define PG8_LDA(dst, b, h) do { _Pragma("unroll") for (int m = 0; m < 4; ++m) _Pragma("unroll") for (int k = 0; k < 2; ++k) dst[m][k] = *(const PG8_LAS bf16x8*)(lds + PG8_SA(b, h) + aoff + m * 2048 + k * 1024); } while (0)
; #define PG8_LDB(dst, b, h) do { _Pragma("unroll") for (int n = 0; n < 2; ++n) _Pragma("unroll") for (int k = 0; k < 2; ++k) dst[n][k] = *(const PG8_LAS bf16x8*)(lds + PG8_SB(b, h) + boff + n * 2048 + k * 1024); } while (0)
; #define PG8_MMA(ai, bj, At, Bt) do { __builtin_amdgcn_s_setprio(1); _Pragma("unroll") for (int m = 0; m < 4; ++m) _Pragma("unroll") for (int n = 0; n < 2; ++n) _Pragma("unroll") for (int k = 0; k < 2; ++k) \
;         acc[ai][bj][m][n] = __builtin_amdgcn_mfma_f32_16x16x32_bf16(Bt[n][k], At[m][k], acc[ai][bj][m][n], 0, 0, 0); __builtin_amdgcn_s_setprio(0); } while (0)
; #define PG8_WAIT_V(n) asm volatile("s_waitcnt vmcnt(" #n ")" ::: "memory")
; #define PG8_WAIT_L(n) asm volatile("s_waitcnt lgkmcnt(" #n ")" ::: "memory")
; #define PG8_BAR __builtin_amdgcn_s_barrier()
; template <class Epi, class Sched, bool ALIGN_EPI = false, bool SP2 = false>
; __device__ __forceinline__ void gemm_phase(PG8_LAS unsigned char* lds, const Gemm g, const Sched& S, const Epi& E, const int wid_in) {
;     ...
;         for (int t = 0; t < nt; t += 2) {
;             const bool last = (t == nt - 2);
;             const char* a1 = cA + (size_t)(t + 1) * kstep;
;             const char* a2 = last ? nA : cA + (size_t)(t + 2) * kstep; const char* b2 = last ? nB : cB + (size_t)(t + 2) * kstep;
;             const char* a3 = a2 + kstep; const char* b3 = b2 + kstep;
;     ...
;             PG8_LDB(B0, 1, 0); PG8_LDB(B1, 1, 1); PG8_SCHED; PG8_LDA(At, 1, 0); PG8_STAGE(PG8_SA(0, 1), a2 + hstep, voffA);
;             PG8_WAIT_V(8); PG8_WAIT_L(0); PG8_BAR; PG8_MMA(0, 0, At, B0); PG8_MMA(0, 1, At, B1); PG8_BAR; PG8_SCHED;
;             PG8_LDA(At, 1, 1); PG8_STAGE(PG8_SB(1, 0), b3, voffB); PG8_STAGE(PG8_SB(1, 1), b3 + hstep, voffB); PG8_STAGE(PG8_SA(1, 0), a3, voffA);
;             PG8_WAIT_V(8); PG8_WAIT_L(0); PG8_BAR; PG8_MMA(1, 0, At, B0); PG8_MMA(1, 1, At, B1); PG8_BAR; PG8_SCHED;
	s_add_i32 s2, s2, s3
	v_lshl_add_u64 v[228:229], v[228:229], 0, s[64:65]
	s_mov_b32 m0, s2
	ds_read_b128 v[174:177], v145 offset:49152
	ds_read_b128 v[190:193], v145 offset:50176
	ds_read_b128 v[194:197], v145 offset:51200
	ds_read_b128 v[198:201], v145 offset:52224
	ds_read_b128 v[212:215], v145 offset:53248
	ds_read_b128 v[216:219], v145 offset:54272
	ds_read_b128 v[220:223], v145 offset:55296
	ds_read_b128 v[224:227], v145 offset:56320
	global_load_lds_dwordx4 v[228:229], off
	s_add_i32 m0, s2, 0x2000
	s_add_u32 s22, s50, 0x40080
	v_lshl_add_u64 v[228:229], v[230:231], 0, s[64:65]
	s_addc_u32 s23, s51, 0
	s_add_i32 s2, s8, s3
	global_load_lds_dwordx4 v[228:229], off
	v_lshl_add_u64 v[228:229], s[22:23], 0, v[0:1]
	s_mov_b32 m0, s2
	s_nop 0
	global_load_lds_dwordx4 v[228:229], off
	v_lshl_add_u64 v[228:229], s[22:23], 0, v[130:131]
	s_add_i32 m0, s2, 0x2000
	s_nop 0
	global_load_lds_dwordx4 v[228:229], off
	v_lshl_add_u64 v[228:229], v[232:233], 0, s[64:65]
	s_mov_b32 m0, s36
	s_nop 0
	global_load_lds_dwordx4 v[228:229], off
	v_lshl_add_u64 v[228:229], v[234:235], 0, s[64:65]
	s_mov_b32 m0, s37
	s_nop 0
	global_load_lds_dwordx4 v[228:229], off
	s_add_i32 s60, s60, 2
	s_add_u32 s48, s48, 0x100
	s_addc_u32 s49, s49, 0
	s_add_u32 s58, s58, 0x100
	s_addc_u32 s59, s59, 0
	s_add_u32 s2, s48, 0xfffc0080
	s_addc_u32 s8, s49, -1
	s_add_i32 s22, 0, 0x10000
	s_cmp_eq_u32 s60, 12
	s_cselect_b32 s53, s43, s8
	s_cselect_b32 s52, s57, s2
	s_cselect_b32 s51, s16, s59
	s_cselect_b32 s50, s41, s58
	s_add_i32 s2, 0, 0x14000
	s_cmp_gt_u32 s60, 13
	s_waitcnt vmcnt(8)
	s_waitcnt lgkmcnt(0)
	s_barrier
	s_waitcnt lgkmcnt(0)
	v_mfma_f32_16x16x32_bf16 v[62:65], v[140:143], v[174:177], v[62:65]
	v_mfma_f32_16x16x32_bf16 v[58:61], v[150:153], v[174:177], v[58:61]
	v_mfma_f32_16x16x32_bf16 v[50:53], v[140:143], v[194:197], v[50:53]
	v_mfma_f32_16x16x32_bf16 v[46:49], v[150:153], v[194:197], v[46:49]
	v_mfma_f32_16x16x32_bf16 v[34:37], v[140:143], v[212:215], v[34:37]
	v_mfma_f32_16x16x32_bf16 v[30:33], v[150:153], v[212:215], v[30:33]
	v_mfma_f32_16x16x32_bf16 v[18:21], v[140:143], v[220:223], v[18:21]
	v_mfma_f32_16x16x32_bf16 v[14:17], v[150:153], v[220:223], v[14:17]
	v_mfma_f32_16x16x32_bf16 v[62:65], v[146:149], v[190:193], v[62:65]
	v_mfma_f32_16x16x32_bf16 v[58:61], v[154:157], v[190:193], v[58:61]
	v_mfma_f32_16x16x32_bf16 v[50:53], v[146:149], v[198:201], v[50:53]
	v_mfma_f32_16x16x32_bf16 v[46:49], v[154:157], v[198:201], v[46:49]
	v_mfma_f32_16x16x32_bf16 v[34:37], v[146:149], v[216:219], v[34:37]
	v_mfma_f32_16x16x32_bf16 v[30:33], v[154:157], v[216:219], v[30:33]
	v_mfma_f32_16x16x32_bf16 v[18:21], v[146:149], v[224:227], v[18:21]
	v_mfma_f32_16x16x32_bf16 v[14:17], v[154:157], v[224:227], v[14:17]
	v_mfma_f32_16x16x32_bf16 v[42:45], v[158:161], v[174:177], v[42:45]
	v_mfma_f32_16x16x32_bf16 v[54:57], v[166:169], v[174:177], v[54:57]
	v_mfma_f32_16x16x32_bf16 v[26:29], v[158:161], v[194:197], v[26:29]
	v_mfma_f32_16x16x32_bf16 v[38:41], v[166:169], v[194:197], v[38:41]
	v_mfma_f32_16x16x32_bf16 v[10:13], v[158:161], v[212:215], v[10:13]
	v_mfma_f32_16x16x32_bf16 v[22:25], v[166:169], v[212:215], v[22:25]
	v_mfma_f32_16x16x32_bf16 v[2:5], v[158:161], v[220:223], v[2:5]
	v_mfma_f32_16x16x32_bf16 v[6:9], v[166:169], v[220:223], v[6:9]
	v_mfma_f32_16x16x32_bf16 v[42:45], v[162:165], v[190:193], v[42:45]
	v_mfma_f32_16x16x32_bf16 v[54:57], v[170:173], v[190:193], v[54:57]
	v_mfma_f32_16x16x32_bf16 v[26:29], v[162:165], v[198:201], v[26:29]
	v_mfma_f32_16x16x32_bf16 v[38:41], v[170:173], v[198:201], v[38:41]
	v_mfma_f32_16x16x32_bf16 v[10:13], v[162:165], v[216:219], v[10:13]
	v_mfma_f32_16x16x32_bf16 v[22:25], v[170:173], v[216:219], v[22:25]
	v_mfma_f32_16x16x32_bf16 v[2:5], v[162:165], v[224:227], v[2:5]
	v_mfma_f32_16x16x32_bf16 v[6:9], v[170:173], v[224:227], v[6:9]
	s_barrier
.LBB0_105:
	v_add_u32_e32 v154, s22, v144
	v_add_u32_e32 v170, s2, v144
	ds_read_b128 v[140:143], v154
	ds_read_b128 v[146:149], v154 offset:1024
	ds_read_b128 v[150:153], v154 offset:2048
	ds_read_b128 v[154:157], v154 offset:3072
	ds_read_b128 v[158:161], v170
	ds_read_b128 v[162:165], v170 offset:1024
	ds_read_b128 v[166:169], v170 offset:2048
	ds_read_b128 v[170:173], v170 offset:3072
	v_lshl_add_u64 v[228:229], s[48:49], 0, v[136:137]
	s_add_i32 m0, s4, 0xc000
	ds_read_b128 v[174:177], v145
	ds_read_b128 v[190:193], v145 offset:1024
	ds_read_b128 v[194:197], v145 offset:2048
	ds_read_b128 v[198:201], v145 offset:3072
	ds_read_b128 v[212:215], v145 offset:4096
	ds_read_b128 v[216:219], v145 offset:5120
	ds_read_b128 v[220:223], v145 offset:6144
	ds_read_b128 v[224:227], v145 offset:7168
	global_load_lds_dwordx4 v[228:229], off
	v_lshl_add_u64 v[228:229], s[48:49], 0, v[138:139]
	s_add_i32 m0, s4, 0xe000
	s_nop 0
	global_load_lds_dwordx4 v[228:229], off
	s_waitcnt vmcnt(8)
	s_waitcnt lgkmcnt(0)
	s_barrier
; #define PG8_STAGE(bufoff, gbase, voff) do { _Pragma("unroll") for (int _i = 0; _i < 2; ++_i) \
;         __builtin_amdgcn_global_load_lds((const unsigned*)((const char*)(gbase) + (voff)[_i]), (PG8_LAS unsigned*)(lds + (bufoff) + ldsw + _i * 8192), 16, 0, 0); } while (0)
; #define PG8_LDA(dst, b, h) do { _Pragma("unroll") for (int m = 0; m < 4; ++m) _Pragma("unroll") for (int k = 0; k < 2; ++k) dst[m][k] = *(const PG8_LAS bf16x8*)(lds + PG8_SA(b, h) + aoff + m * 2048 + k * 1024); } while (0)
; #define PG8_LDB(dst, b, h) do { _Pragma("unroll") for (int n = 0; n < 2; ++n) _Pragma("unroll") for (int k = 0; k < 2; ++k) dst[n][k] = *(const PG8_LAS bf16x8*)(lds + PG8_SB(b, h) + boff + n * 2048 + k * 1024); } while (0)
; #define PG8_MMA(ai, bj, At, Bt) do { __builtin_amdgcn_s_setprio(1); _Pragma("unroll") for (int m = 0; m < 4; ++m) _Pragma("unroll") for (int n = 0; n < 2; ++n) _Pragma("unroll") for (int k = 0; k < 2; ++k) \
;         acc[ai][bj][m][n] = __builtin_amdgcn_mfma_f32_16x16x32_bf16(Bt[n][k], At[m][k], acc[ai][bj][m][n], 0, 0, 0); __builtin_amdgcn_s_setprio(0); } while (0)
; #define PG8_WAIT_V(n) asm volatile("s_waitcnt vmcnt(" #n ")" ::: "memory")
; #define PG8_WAIT_L(n) asm volatile("s_waitcnt lgkmcnt(" #n ")" ::: "memory")
; #define PG8_BAR __builtin_amdgcn_s_barrier()
; #define PG8_SCHED __builtin_amdgcn_sched_barrier(0)
; template <class Epi, class Sched, bool ALIGN_EPI = false, bool SP2 = false>
; __device__ __forceinline__ void gemm_phase(PG8_LAS unsigned char* lds, const Gemm g, const Sched& S, const Epi& E, const int wid_in) {
;     ...
;             PG8_LDB(B0, 0, 0); PG8_LDB(B1, 0, 1); PG8_SCHED; PG8_LDA(At, 0, 0); PG8_STAGE(PG8_SA(1, 1), a1 + hstep, voffA);
;             PG8_WAIT_V(8); PG8_WAIT_L(0); PG8_BAR; PG8_MMA(0, 0, At, B0); PG8_MMA(0, 1, At, B1); PG8_BAR; PG8_SCHED;
;             PG8_LDA(At, 0, 1); PG8_STAGE(PG8_SB(0, 0), b2, voffB); PG8_STAGE(PG8_SB(0, 1), b2 + hstep, voffB); PG8_STAGE(PG8_SA(0, 0), a2, voffA);
;             PG8_WAIT_V(8); PG8_WAIT_L(0); PG8_BAR; PG8_MMA(1, 0, At, B0); PG8_MMA(1, 1, At, B1); PG8_BAR; PG8_SCHED;
	s_waitcnt lgkmcnt(0)
	v_mfma_f32_16x16x32_bf16 v[126:129], v[140:143], v[174:177], v[126:129]
	v_mfma_f32_16x16x32_bf16 v[122:125], v[150:153], v[174:177], v[122:125]
	v_mfma_f32_16x16x32_bf16 v[114:117], v[140:143], v[194:197], v[114:117]
	v_mfma_f32_16x16x32_bf16 v[110:113], v[150:153], v[194:197], v[110:113]
	v_mfma_f32_16x16x32_bf16 v[98:101], v[140:143], v[212:215], v[98:101]
	v_mfma_f32_16x16x32_bf16 v[94:97], v[150:153], v[212:215], v[94:97]
	v_mfma_f32_16x16x32_bf16 v[82:85], v[140:143], v[220:223], v[82:85]
	v_mfma_f32_16x16x32_bf16 v[78:81], v[150:153], v[220:223], v[78:81]
	v_mfma_f32_16x16x32_bf16 v[126:129], v[146:149], v[190:193], v[126:129]
	v_mfma_f32_16x16x32_bf16 v[122:125], v[154:157], v[190:193], v[122:125]
	v_mfma_f32_16x16x32_bf16 v[114:117], v[146:149], v[198:201], v[114:117]
	v_mfma_f32_16x16x32_bf16 v[110:113], v[154:157], v[198:201], v[110:113]
	v_mfma_f32_16x16x32_bf16 v[98:101], v[146:149], v[216:219], v[98:101]
	v_mfma_f32_16x16x32_bf16 v[94:97], v[154:157], v[216:219], v[94:97]
	v_mfma_f32_16x16x32_bf16 v[82:85], v[146:149], v[224:227], v[82:85]
	v_mfma_f32_16x16x32_bf16 v[78:81], v[154:157], v[224:227], v[78:81]
	v_mfma_f32_16x16x32_bf16 v[106:109], v[158:161], v[174:177], v[106:109]
	v_mfma_f32_16x16x32_bf16 v[118:121], v[166:169], v[174:177], v[118:121]
	v_mfma_f32_16x16x32_bf16 v[90:93], v[158:161], v[194:197], v[90:93]
	v_mfma_f32_16x16x32_bf16 v[102:105], v[166:169], v[194:197], v[102:105]
	v_mfma_f32_16x16x32_bf16 v[74:77], v[158:161], v[212:215], v[74:77]
	v_mfma_f32_16x16x32_bf16 v[86:89], v[166:169], v[212:215], v[86:89]
	v_mfma_f32_16x16x32_bf16 v[66:69], v[158:161], v[220:223], v[66:69]
	v_mfma_f32_16x16x32_bf16 v[70:73], v[166:169], v[220:223], v[70:73]
	v_mfma_f32_16x16x32_bf16 v[106:109], v[162:165], v[190:193], v[106:109]
	v_mfma_f32_16x16x32_bf16 v[118:121], v[170:173], v[190:193], v[118:121]
	v_mfma_f32_16x16x32_bf16 v[90:93], v[162:165], v[198:201], v[90:93]
	v_mfma_f32_16x16x32_bf16 v[102:105], v[170:173], v[198:201], v[102:105]
	v_mfma_f32_16x16x32_bf16 v[74:77], v[162:165], v[216:219], v[74:77]
	v_mfma_f32_16x16x32_bf16 v[86:89], v[170:173], v[216:219], v[86:89]
	v_mfma_f32_16x16x32_bf16 v[66:69], v[162:165], v[224:227], v[66:69]
	v_mfma_f32_16x16x32_bf16 v[70:73], v[170:173], v[224:227], v[70:73]
	s_barrier
	s_add_i32 s8, s22, s3
	v_lshl_add_u64 v[228:229], s[50:51], 0, v[0:1]
	s_mov_b32 m0, s8
	ds_read_b128 v[174:177], v145 offset:16384
	ds_read_b128 v[190:193], v145 offset:17408
	ds_read_b128 v[194:197], v145 offset:18432
	ds_read_b128 v[198:201], v145 offset:19456
	ds_read_b128 v[212:215], v145 offset:20480
	ds_read_b128 v[216:219], v145 offset:21504
	ds_read_b128 v[220:223], v145 offset:22528
	ds_read_b128 v[224:227], v145 offset:23552
	global_load_lds_dwordx4 v[228:229], off
	s_add_i32 m0, s8, 0x2000
	s_add_u32 s22, s50, 0x40000
	v_lshl_add_u64 v[230:231], s[50:51], 0, v[130:131]
	s_addc_u32 s23, s51, 0
	s_add_i32 s2, s2, s3
	global_load_lds_dwordx4 v[230:231], off
	v_lshl_add_u64 v[232:233], s[22:23], 0, v[0:1]
	s_mov_b32 m0, s2
	v_lshl_add_u64 v[234:235], s[52:53], 0, v[132:133]
	global_load_lds_dwordx4 v[232:233], off
	v_lshl_add_u64 v[232:233], s[22:23], 0, v[130:131]
	s_add_i32 m0, s2, 0x2000
	s_nop 0
	global_load_lds_dwordx4 v[232:233], off
	v_lshl_add_u64 v[232:233], s[52:53], 0, v[134:135]
	s_mov_b32 m0, s4
	s_nop 0
	global_load_lds_dwordx4 v[232:233], off
	s_mov_b32 m0, s5
	s_nop 0
	global_load_lds_dwordx4 v[234:235], off
	s_waitcnt vmcnt(8)
	s_waitcnt lgkmcnt(0)
	s_barrier
	s_waitcnt lgkmcnt(0)
	v_mfma_f32_16x16x32_bf16 v[62:65], v[140:143], v[174:177], v[62:65]
	v_mfma_f32_16x16x32_bf16 v[58:61], v[150:153], v[174:177], v[58:61]
	v_mfma_f32_16x16x32_bf16 v[50:53], v[140:143], v[194:197], v[50:53]
	v_mfma_f32_16x16x32_bf16 v[46:49], v[150:153], v[194:197], v[46:49]
	v_mfma_f32_16x16x32_bf16 v[34:37], v[140:143], v[212:215], v[34:37]
	v_mfma_f32_16x16x32_bf16 v[30:33], v[150:153], v[212:215], v[30:33]
	v_mfma_f32_16x16x32_bf16 v[18:21], v[140:143], v[220:223], v[18:21]
	v_mfma_f32_16x16x32_bf16 v[14:17], v[150:153], v[220:223], v[14:17]
	v_mfma_f32_16x16x32_bf16 v[62:65], v[146:149], v[190:193], v[62:65]
	v_mfma_f32_16x16x32_bf16 v[58:61], v[154:157], v[190:193], v[58:61]
	v_mfma_f32_16x16x32_bf16 v[50:53], v[146:149], v[198:201], v[50:53]
	v_mfma_f32_16x16x32_bf16 v[46:49], v[154:157], v[198:201], v[46:49]
	v_mfma_f32_16x16x32_bf16 v[34:37], v[146:149], v[216:219], v[34:37]
	v_mfma_f32_16x16x32_bf16 v[30:33], v[154:157], v[216:219], v[30:33]
	v_mfma_f32_16x16x32_bf16 v[18:21], v[146:149], v[224:227], v[18:21]
	v_mfma_f32_16x16x32_bf16 v[14:17], v[154:157], v[224:227], v[14:17]
	v_mfma_f32_16x16x32_bf16 v[42:45], v[158:161], v[174:177], v[42:45]
	v_mfma_f32_16x16x32_bf16 v[54:57], v[166:169], v[174:177], v[54:57]
	v_mfma_f32_16x16x32_bf16 v[26:29], v[158:161], v[194:197], v[26:29]
	v_mfma_f32_16x16x32_bf16 v[38:41], v[166:169], v[194:197], v[38:41]
	v_mfma_f32_16x16x32_bf16 v[10:13], v[158:161], v[212:215], v[10:13]
	v_mfma_f32_16x16x32_bf16 v[22:25], v[166:169], v[212:215], v[22:25]
	v_mfma_f32_16x16x32_bf16 v[2:5], v[158:161], v[220:223], v[2:5]
	v_mfma_f32_16x16x32_bf16 v[6:9], v[166:169], v[220:223], v[6:9]
	v_mfma_f32_16x16x32_bf16 v[42:45], v[162:165], v[190:193], v[42:45]
	v_mfma_f32_16x16x32_bf16 v[54:57], v[170:173], v[190:193], v[54:57]
	v_mfma_f32_16x16x32_bf16 v[26:29], v[162:165], v[198:201], v[26:29]
	v_mfma_f32_16x16x32_bf16 v[38:41], v[170:173], v[198:201], v[38:41]
	v_mfma_f32_16x16x32_bf16 v[10:13], v[162:165], v[216:219], v[10:13]
	v_mfma_f32_16x16x32_bf16 v[22:25], v[170:173], v[216:219], v[22:25]
	v_mfma_f32_16x16x32_bf16 v[2:5], v[162:165], v[224:227], v[2:5]
	v_mfma_f32_16x16x32_bf16 v[6:9], v[170:173], v[224:227], v[6:9]
	s_barrier
; #define PG8_STAGE(bufoff, gbase, voff) do { _Pragma("unroll") for (int _i = 0; _i < 2; ++_i) \
;         __builtin_amdgcn_global_load_lds((const unsigned*)((const char*)(gbase) + (voff)[_i]), (PG8_LAS unsigned*)(lds + (bufoff) + ldsw + _i * 8192), 16, 0, 0); } while (0)
; #define PG8_LDA(dst, b, h) do { _Pragma("unroll") for (int m = 0; m < 4; ++m) _Pragma("unroll") for (int k = 0; k < 2; ++k) dst[m][k] = *(const PG8_LAS bf16x8*)(lds + PG8_SA(b, h) + aoff + m * 2048 + k * 1024); } while (0)
; #define PG8_LDB(dst, b, h) do { _Pragma("unroll") for (int n = 0; n < 2; ++n) _Pragma("unroll") for (int k = 0; k < 2; ++k) dst[n][k] = *(const PG8_LAS bf16x8*)(lds + PG8_SB(b, h) + boff + n * 2048 + k * 1024); } while (0)
; #define PG8_MMA(ai, bj, At, Bt) do { __builtin_amdgcn_s_setprio(1); _Pragma("unroll") for (int m = 0; m < 4; ++m) _Pragma("unroll") for (int n = 0; n < 2; ++n) _Pragma("unroll") for (int k = 0; k < 2; ++k) \
;         acc[ai][bj][m][n] = __builtin_amdgcn_mfma_f32_16x16x32_bf16(Bt[n][k], At[m][k], acc[ai][bj][m][n], 0, 0, 0); __builtin_amdgcn_s_setprio(0); } while (0)
; #define PG8_WAIT_V(n) asm volatile("s_waitcnt vmcnt(" #n ")" ::: "memory")
; #define PG8_WAIT_L(n) asm volatile("s_waitcnt lgkmcnt(" #n ")" ::: "memory")
; #define PG8_BAR __builtin_amdgcn_s_barrier()
; #define PG8_SCHED __builtin_amdgcn_sched_barrier(0)
; template <class Epi, class Sched, bool ALIGN_EPI = false, bool SP2 = false>
; __device__ __forceinline__ void gemm_phase(PG8_LAS unsigned char* lds, const Gemm g, const Sched& S, const Epi& E, const int wid_in) {
;     ...
;             PG8_LDB(B0, 1, 0); PG8_LDB(B1, 1, 1); PG8_SCHED; PG8_LDA(At, 1, 0); PG8_STAGE(PG8_SA(0, 1), a2 + hstep, voffA);
;             PG8_WAIT_V(8); PG8_WAIT_L(0); PG8_BAR; PG8_MMA(0, 0, At, B0); PG8_MMA(0, 1, At, B1); PG8_BAR; PG8_SCHED;
	s_add_i32 s2, 0, 0x18000
	s_add_i32 s8, 0, 0x1c000
	v_add_u32_e32 v154, s2, v144
	v_add_u32_e32 v170, s8, v144
	ds_read_b128 v[140:143], v154
	ds_read_b128 v[146:149], v154 offset:1024
	ds_read_b128 v[150:153], v154 offset:2048
	ds_read_b128 v[154:157], v154 offset:3072
	ds_read_b128 v[158:161], v170
	ds_read_b128 v[162:165], v170 offset:1024
	ds_read_b128 v[166:169], v170 offset:2048
	ds_read_b128 v[170:173], v170 offset:3072
	s_add_u32 s22, s52, 0x40000
	s_addc_u32 s23, s53, 0
	s_mov_b32 m0, s12
	v_lshl_add_u64 v[236:237], s[22:23], 0, v[134:135]
	ds_read_b128 v[174:177], v145 offset:32768
	ds_read_b128 v[190:193], v145 offset:33792
	ds_read_b128 v[194:197], v145 offset:34816
	ds_read_b128 v[198:201], v145 offset:35840
	ds_read_b128 v[212:215], v145 offset:36864
	ds_read_b128 v[216:219], v145 offset:37888
	ds_read_b128 v[220:223], v145 offset:38912
	ds_read_b128 v[224:227], v145 offset:39936
	global_load_lds_dwordx4 v[236:237], off
	v_lshl_add_u64 v[236:237], s[22:23], 0, v[132:133]
	s_mov_b32 m0, s13
	s_nop 0
	global_load_lds_dwordx4 v[236:237], off
	s_waitcnt vmcnt(8)
	s_waitcnt lgkmcnt(0)
	s_barrier
	s_waitcnt lgkmcnt(0)
	v_mfma_f32_16x16x32_bf16 v[126:129], v[140:143], v[174:177], v[126:129]
	v_mfma_f32_16x16x32_bf16 v[122:125], v[150:153], v[174:177], v[122:125]
	v_mfma_f32_16x16x32_bf16 v[114:117], v[140:143], v[194:197], v[114:117]
	v_mfma_f32_16x16x32_bf16 v[110:113], v[150:153], v[194:197], v[110:113]
	v_mfma_f32_16x16x32_bf16 v[98:101], v[140:143], v[212:215], v[98:101]
	v_mfma_f32_16x16x32_bf16 v[94:97], v[150:153], v[212:215], v[94:97]
	v_mfma_f32_16x16x32_bf16 v[82:85], v[140:143], v[220:223], v[82:85]
	v_mfma_f32_16x16x32_bf16 v[78:81], v[150:153], v[220:223], v[78:81]
	v_mfma_f32_16x16x32_bf16 v[126:129], v[146:149], v[190:193], v[126:129]
	v_mfma_f32_16x16x32_bf16 v[122:125], v[154:157], v[190:193], v[122:125]
	v_mfma_f32_16x16x32_bf16 v[114:117], v[146:149], v[198:201], v[114:117]
	v_mfma_f32_16x16x32_bf16 v[110:113], v[154:157], v[198:201], v[110:113]
	v_mfma_f32_16x16x32_bf16 v[98:101], v[146:149], v[216:219], v[98:101]
	v_mfma_f32_16x16x32_bf16 v[94:97], v[154:157], v[216:219], v[94:97]
	v_mfma_f32_16x16x32_bf16 v[82:85], v[146:149], v[224:227], v[82:85]
	v_mfma_f32_16x16x32_bf16 v[78:81], v[154:157], v[224:227], v[78:81]
	v_mfma_f32_16x16x32_bf16 v[106:109], v[158:161], v[174:177], v[106:109]
	v_mfma_f32_16x16x32_bf16 v[118:121], v[166:169], v[174:177], v[118:121]
	v_mfma_f32_16x16x32_bf16 v[90:93], v[158:161], v[194:197], v[90:93]
	v_mfma_f32_16x16x32_bf16 v[102:105], v[166:169], v[194:197], v[102:105]
	v_mfma_f32_16x16x32_bf16 v[74:77], v[158:161], v[212:215], v[74:77]
	v_mfma_f32_16x16x32_bf16 v[86:89], v[166:169], v[212:215], v[86:89]
	v_mfma_f32_16x16x32_bf16 v[66:69], v[158:161], v[220:223], v[66:69]
	v_mfma_f32_16x16x32_bf16 v[70:73], v[166:169], v[220:223], v[70:73]
	v_mfma_f32_16x16x32_bf16 v[106:109], v[162:165], v[190:193], v[106:109]
	v_mfma_f32_16x16x32_bf16 v[118:121], v[170:173], v[190:193], v[118:121]
	v_mfma_f32_16x16x32_bf16 v[90:93], v[162:165], v[198:201], v[90:93]
	v_mfma_f32_16x16x32_bf16 v[102:105], v[170:173], v[198:201], v[102:105]
	v_mfma_f32_16x16x32_bf16 v[74:77], v[162:165], v[216:219], v[74:77]
	v_mfma_f32_16x16x32_bf16 v[86:89], v[170:173], v[216:219], v[86:89]
	v_mfma_f32_16x16x32_bf16 v[66:69], v[162:165], v[224:227], v[66:69]
	v_mfma_f32_16x16x32_bf16 v[70:73], v[170:173], v[224:227], v[70:73]
	s_barrier
; #define PG8_STAGE(bufoff, gbase, voff) do { _Pragma("unroll") for (int _i = 0; _i < 2; ++_i) \
;         __builtin_amdgcn_global_load_lds((const unsigned*)((const char*)(gbase) + (voff)[_i]), (PG8_LAS unsigned*)(lds + (bufoff) + ldsw + _i * 8192), 16, 0, 0); } while (0)
; #define PG8_LDA(dst, b, h) do { _Pragma("unroll") for (int m = 0; m < 4; ++m) _Pragma("unroll") for (int k = 0; k < 2; ++k) dst[m][k] = *(const PG8_LAS bf16x8*)(lds + PG8_SA(b, h) + aoff + m * 2048 + k * 1024); } while (0)
; #define PG8_MMA(ai, bj, At, Bt) do { __builtin_amdgcn_s_setprio(1); _Pragma("unroll") for (int m = 0; m < 4; ++m) _Pragma("unroll") for (int n = 0; n < 2; ++n) _Pragma("unroll") for (int k = 0; k < 2; ++k) \
;         acc[ai][bj][m][n] = __builtin_amdgcn_mfma_f32_16x16x32_bf16(Bt[n][k], At[m][k], acc[ai][bj][m][n], 0, 0, 0); __builtin_amdgcn_s_setprio(0); } while (0)
; #define PG8_WAIT_V(n) asm volatile("s_waitcnt vmcnt(" #n ")" ::: "memory")
; #define PG8_WAIT_L(n) asm volatile("s_waitcnt lgkmcnt(" #n ")" ::: "memory")
; #define PG8_BAR __builtin_amdgcn_s_barrier()
; #define PG8_SCHED __builtin_amdgcn_sched_barrier(0)
; template <class Epi, class Sched, bool ALIGN_EPI = false, bool SP2 = false>
; __device__ __forceinline__ void gemm_phase(PG8_LAS unsigned char* lds, const Gemm g, const Sched& S, const Epi& E, const int wid_in) {
;     ...
;         for (int t = 0; t < nt; t += 2) {
;             const bool last = (t == nt - 2);
;             const char* a1 = cA + (size_t)(t + 1) * kstep;
;             const char* a2 = last ? nA : cA + (size_t)(t + 2) * kstep; const char* b2 = last ? nB : cB + (size_t)(t + 2) * kstep;
;             const char* a3 = a2 + kstep; const char* b3 = b2 + kstep;
;     ...
;             PG8_LDA(At, 1, 1); PG8_STAGE(PG8_SB(1, 0), b3, voffB); PG8_STAGE(PG8_SB(1, 1), b3 + hstep, voffB); PG8_STAGE(PG8_SA(1, 0), a3, voffA);
;             PG8_WAIT_V(8); PG8_WAIT_L(0); PG8_BAR; PG8_MMA(1, 0, At, B0); PG8_MMA(1, 1, At, B1); PG8_BAR; PG8_SCHED;
	s_add_i32 s2, s2, s3
	v_lshl_add_u64 v[228:229], v[228:229], 0, s[64:65]
	s_mov_b32 m0, s2
	ds_read_b128 v[174:177], v145 offset:49152
	ds_read_b128 v[190:193], v145 offset:50176
	ds_read_b128 v[194:197], v145 offset:51200
	ds_read_b128 v[198:201], v145 offset:52224
	ds_read_b128 v[212:215], v145 offset:53248
	ds_read_b128 v[216:219], v145 offset:54272
	ds_read_b128 v[220:223], v145 offset:55296
	ds_read_b128 v[224:227], v145 offset:56320
	global_load_lds_dwordx4 v[228:229], off
	s_add_i32 m0, s2, 0x2000
	s_add_u32 s22, s50, 0x40080
	v_lshl_add_u64 v[228:229], v[230:231], 0, s[64:65]
	s_addc_u32 s23, s51, 0
	s_add_i32 s2, s8, s3
	global_load_lds_dwordx4 v[228:229], off
	v_lshl_add_u64 v[228:229], s[22:23], 0, v[0:1]
	s_mov_b32 m0, s2
	s_nop 0
	global_load_lds_dwordx4 v[228:229], off
	v_lshl_add_u64 v[228:229], s[22:23], 0, v[130:131]
	s_add_i32 m0, s2, 0x2000
	s_nop 0
	global_load_lds_dwordx4 v[228:229], off
	v_lshl_add_u64 v[228:229], v[232:233], 0, s[64:65]
	s_mov_b32 m0, s36
	s_nop 0
	global_load_lds_dwordx4 v[228:229], off
	v_lshl_add_u64 v[228:229], v[234:235], 0, s[64:65]
	s_mov_b32 m0, s37
	s_nop 0
	global_load_lds_dwordx4 v[228:229], off
	s_add_i32 s60, s60, 2
	s_add_u32 s48, s48, 0x100
	s_addc_u32 s49, s49, 0
	s_add_u32 s58, s58, 0x100
	s_addc_u32 s59, s59, 0
	s_add_u32 s2, s48, 0xfffc0080
	s_addc_u32 s8, s49, -1
	s_add_i32 s22, 0, 0x10000
	s_cmp_eq_u32 s60, 12
	s_cselect_b32 s53, s43, s8
	s_cselect_b32 s52, s57, s2
	s_cselect_b32 s51, s16, s59
	s_cselect_b32 s50, s41, s58
	s_add_i32 s2, 0, 0x14000
	s_cmp_gt_u32 s60, 13
	s_waitcnt vmcnt(8)
	s_waitcnt lgkmcnt(0)
	s_barrier
	s_waitcnt lgkmcnt(0)
	v_mfma_f32_16x16x32_bf16 v[62:65], v[140:143], v[174:177], v[62:65]
	v_mfma_f32_16x16x32_bf16 v[58:61], v[150:153], v[174:177], v[58:61]
	v_mfma_f32_16x16x32_bf16 v[50:53], v[140:143], v[194:197], v[50:53]
	v_mfma_f32_16x16x32_bf16 v[46:49], v[150:153], v[194:197], v[46:49]
	v_mfma_f32_16x16x32_bf16 v[34:37], v[140:143], v[212:215], v[34:37]
	v_mfma_f32_16x16x32_bf16 v[30:33], v[150:153], v[212:215], v[30:33]
	v_mfma_f32_16x16x32_bf16 v[18:21], v[140:143], v[220:223], v[18:21]
	v_mfma_f32_16x16x32_bf16 v[14:17], v[150:153], v[220:223], v[14:17]
	v_mfma_f32_16x16x32_bf16 v[62:65], v[146:149], v[190:193], v[62:65]
	v_mfma_f32_16x16x32_bf16 v[58:61], v[154:157], v[190:193], v[58:61]
	v_mfma_f32_16x16x32_bf16 v[50:53], v[146:149], v[198:201], v[50:53]
	v_mfma_f32_16x16x32_bf16 v[46:49], v[154:157], v[198:201], v[46:49]
	v_mfma_f32_16x16x32_bf16 v[34:37], v[146:149], v[216:219], v[34:37]
	v_mfma_f32_16x16x32_bf16 v[30:33], v[154:157], v[216:219], v[30:33]
	v_mfma_f32_16x16x32_bf16 v[18:21], v[146:149], v[224:227], v[18:21]
	v_mfma_f32_16x16x32_bf16 v[14:17], v[154:157], v[224:227], v[14:17]
	v_mfma_f32_16x16x32_bf16 v[42:45], v[158:161], v[174:177], v[42:45]
	v_mfma_f32_16x16x32_bf16 v[54:57], v[166:169], v[174:177], v[54:57]
	v_mfma_f32_16x16x32_bf16 v[26:29], v[158:161], v[194:197], v[26:29]
	v_mfma_f32_16x16x32_bf16 v[38:41], v[166:169], v[194:197], v[38:41]
	v_mfma_f32_16x16x32_bf16 v[10:13], v[158:161], v[212:215], v[10:13]
	v_mfma_f32_16x16x32_bf16 v[22:25], v[166:169], v[212:215], v[22:25]
	v_mfma_f32_16x16x32_bf16 v[2:5], v[158:161], v[220:223], v[2:5]
	v_mfma_f32_16x16x32_bf16 v[6:9], v[166:169], v[220:223], v[6:9]
	v_mfma_f32_16x16x32_bf16 v[42:45], v[162:165], v[190:193], v[42:45]
	v_mfma_f32_16x16x32_bf16 v[54:57], v[170:173], v[190:193], v[54:57]
	v_mfma_f32_16x16x32_bf16 v[26:29], v[162:165], v[198:201], v[26:29]
	v_mfma_f32_16x16x32_bf16 v[38:41], v[170:173], v[198:201], v[38:41]
	v_mfma_f32_16x16x32_bf16 v[10:13], v[162:165], v[216:219], v[10:13]
	v_mfma_f32_16x16x32_bf16 v[22:25], v[170:173], v[216:219], v[22:25]
	v_mfma_f32_16x16x32_bf16 v[2:5], v[162:165], v[224:227], v[2:5]
	v_mfma_f32_16x16x32_bf16 v[6:9], v[170:173], v[224:227], v[6:9]
	s_barrier
	s_cbranch_scc0 .LBB0_105
	s_setprio 0
	v_readlane_b32 s8, v243, 63
	v_readlane_b32 s9, v242, 0
	s_and_b64 vcc, exec, s[8:9]
	s_cbranch_vccz .LBB0_108
	s_barrier

; #define PG8_STAGE(bufoff, gbase, voff) do { _Pragma("unroll") for (int _i = 0; _i < 2; ++_i) \
;         __builtin_amdgcn_global_load_lds((const unsigned*)((const char*)(gbase) + (voff)[_i]), (PG8_LAS unsigned*)(lds + (bufoff) + ldsw + _i * 8192), 16, 0, 0); } while (0)
; #define PG8_LDA(dst, b, h) do { _Pragma("unroll") for (int m = 0; m < 4; ++m) _Pragma("unroll") for (int k = 0; k < 2; ++k) dst[m][k] = *(const PG8_LAS bf16x8*)(lds + PG8_SA(b, h) + aoff + m * 2048 + k * 1024); } while (0)
; #define PG8_LDB(dst, b, h) do { _Pragma("unroll") for (int n = 0; n < 2; ++n) _Pragma("unroll") for (int k = 0; k < 2; ++k) dst[n][k] = *(const PG8_LAS bf16x8*)(lds + PG8_SB(b, h) + boff + n * 2048 + k * 1024); } while (0)
; #define PG8_MMA(ai, bj, At, Bt) do { __builtin_amdgcn_s_setprio(1); _Pragma("unroll") for (int m = 0; m < 4; ++m) _Pragma("unroll") for (int n = 0; n < 2; ++n) _Pragma("unroll") for (int k = 0; k < 2; ++k) \
;         acc[ai][bj][m][n] = __builtin_amdgcn_mfma_f32_16x16x32_bf16(Bt[n][k], At[m][k], acc[ai][bj][m][n], 0, 0, 0); __builtin_amdgcn_s_setprio(0); } while (0)
; #define PG8_WAIT_V(n) asm volatile("s_waitcnt vmcnt(" #n ")" ::: "memory")
; #define PG8_BAR __builtin_amdgcn_s_barrier()
; template <class Epi, class Sched, bool ALIGN_EPI = false, bool SP2 = false>
; __device__ __forceinline__ void gemm_phase(PG8_LAS unsigned char* lds, const Gemm g, const Sched& S, const Epi& E, const int wid_in) {
;     ...
;         for (int t = 0; t < nt; t += 2) {
;             const bool last = (t == nt - 2);
;             const char* a1 = cA + (size_t)(t + 1) * kstep;
;             const char* a2 = last ? nA : cA + (size_t)(t + 2) * kstep; const char* b2 = last ? nB : cB + (size_t)(t + 2) * kstep;
;             const char* a3 = a2 + kstep; const char* b3 = b2 + kstep;
;             if (last && has_next) S.a_ready(nxt);
;             if constexpr (SP2) {
;             PG8_LDB(B0, 0, 0); PG8_LDB(B1, 0, 1); PG8_SCHED; PG8_LDA(At, 0, 0); PG8_STAGE(PG8_SA(1, 1), a1 + hstep, voffA);
;             PG8_WAIT_V(8); PG8_WAIT_L(0); PG8_BAR; PG8_MMA(0, 0, At, B0); PG8_MMA(0, 1, At, B1); PG8_BAR; PG8_SCHED;
;             PG8_LDA(At, 0, 1); PG8_STAGE(PG8_SB(0, 0), b2, voffB); PG8_STAGE(PG8_SB(0, 1), b2 + hstep, voffB); PG8_STAGE(PG8_SA(0, 0), a2, voffA);
;             PG8_WAIT_V(8); PG8_WAIT_L(0); PG8_BAR; PG8_MMA(1, 0, At, B0); PG8_MMA(1, 1, At, B1); PG8_BAR; PG8_SCHED;
.Lprio_done_537:
	s_add_u32 s2, s48, 0xfffc0080
	s_addc_u32 s8, s49, -1
	s_add_i32 s9, 0, 0x10000
	s_cmp_eq_u32 s60, 12
	s_cselect_b32 s53, s43, s8
	s_cselect_b32 s52, s57, s2
	v_add_u32_e32 v140, s9, v142
	s_cselect_b32 s51, s16, s59
	s_cselect_b32 s50, s39, s58
	s_add_i32 s2, 0, 0x14000
	ds_read_b128 v[144:147], v140
	ds_read_b128 v[148:151], v140 offset:1024
	ds_read_b128 v[152:155], v140 offset:2048
	ds_read_b128 v[156:159], v140 offset:3072
	v_add_u32_e32 v140, s2, v142
	ds_read_b128 v[160:163], v140
	ds_read_b128 v[164:167], v140 offset:1024
	ds_read_b128 v[168:171], v140 offset:2048
	ds_read_b128 v[172:175], v140 offset:3072
	v_lshl_add_u64 v[140:141], s[48:49], 0, v[136:137]
	s_add_i32 m0, s4, 0xc000
	ds_read_b128 v[190:193], v143
	ds_read_b128 v[194:197], v143 offset:1024
	ds_read_b128 v[198:201], v143 offset:2048
	ds_read_b128 v[212:215], v143 offset:3072
	ds_read_b128 v[216:219], v143 offset:4096
	ds_read_b128 v[220:223], v143 offset:5120
	ds_read_b128 v[224:227], v143 offset:6144
	ds_read_b128 v[228:231], v143 offset:7168
	global_load_lds_dwordx4 v[140:141], off
	v_lshl_add_u64 v[140:141], s[48:49], 0, v[138:139]
	s_add_i32 m0, s4, 0xe000
	s_nop 0
	global_load_lds_dwordx4 v[140:141], off
	s_waitcnt vmcnt(8)
	s_waitcnt lgkmcnt(0)
	s_barrier
	s_waitcnt lgkmcnt(0)
	v_mfma_f32_16x16x32_bf16 v[126:129], v[144:147], v[190:193], 0
	v_mfma_f32_16x16x32_bf16 v[122:125], v[152:155], v[190:193], 0
	v_mfma_f32_16x16x32_bf16 v[118:121], v[144:147], v[198:201], 0
	v_mfma_f32_16x16x32_bf16 v[110:113], v[152:155], v[198:201], 0
	v_mfma_f32_16x16x32_bf16 v[102:105], v[144:147], v[216:219], 0
	v_mfma_f32_16x16x32_bf16 v[94:97], v[152:155], v[216:219], 0
	v_mfma_f32_16x16x32_bf16 v[82:85], v[144:147], v[224:227], 0
	v_mfma_f32_16x16x32_bf16 v[74:77], v[152:155], v[224:227], 0
	v_mfma_f32_16x16x32_bf16 v[126:129], v[148:151], v[194:197], v[126:129]
	v_mfma_f32_16x16x32_bf16 v[122:125], v[156:159], v[194:197], v[122:125]
	v_mfma_f32_16x16x32_bf16 v[118:121], v[148:151], v[212:215], v[118:121]
	v_mfma_f32_16x16x32_bf16 v[110:113], v[156:159], v[212:215], v[110:113]
	v_mfma_f32_16x16x32_bf16 v[102:105], v[148:151], v[220:223], v[102:105]
	v_mfma_f32_16x16x32_bf16 v[94:97], v[156:159], v[220:223], v[94:97]
	v_mfma_f32_16x16x32_bf16 v[82:85], v[148:151], v[228:231], v[82:85]
	v_mfma_f32_16x16x32_bf16 v[74:77], v[156:159], v[228:231], v[74:77]
	v_mfma_f32_16x16x32_bf16 v[114:117], v[160:163], v[190:193], 0
	v_mfma_f32_16x16x32_bf16 v[106:109], v[168:171], v[190:193], 0
	v_mfma_f32_16x16x32_bf16 v[98:101], v[160:163], v[198:201], 0
	v_mfma_f32_16x16x32_bf16 v[90:93], v[168:171], v[198:201], 0
	v_mfma_f32_16x16x32_bf16 v[86:89], v[160:163], v[216:219], 0
	v_mfma_f32_16x16x32_bf16 v[78:81], v[168:171], v[216:219], 0
	v_mfma_f32_16x16x32_bf16 v[70:73], v[160:163], v[224:227], 0
	v_mfma_f32_16x16x32_bf16 v[66:69], v[168:171], v[224:227], 0
	v_mfma_f32_16x16x32_bf16 v[114:117], v[164:167], v[194:197], v[114:117]
	v_mfma_f32_16x16x32_bf16 v[106:109], v[172:175], v[194:197], v[106:109]
	v_mfma_f32_16x16x32_bf16 v[98:101], v[164:167], v[212:215], v[98:101]
	v_mfma_f32_16x16x32_bf16 v[90:93], v[172:175], v[212:215], v[90:93]
	v_mfma_f32_16x16x32_bf16 v[86:89], v[164:167], v[220:223], v[86:89]
	v_mfma_f32_16x16x32_bf16 v[78:81], v[172:175], v[220:223], v[78:81]
	v_mfma_f32_16x16x32_bf16 v[70:73], v[164:167], v[228:231], v[70:73]
	v_mfma_f32_16x16x32_bf16 v[66:69], v[172:175], v[228:231], v[66:69]
	s_barrier
	s_add_i32 s8, s9, s3
	v_lshl_add_u64 v[140:141], s[50:51], 0, v[0:1]
	s_mov_b32 m0, s8
	ds_read_b128 v[190:193], v143 offset:16384
	ds_read_b128 v[194:197], v143 offset:17408
	ds_read_b128 v[198:201], v143 offset:18432
	ds_read_b128 v[212:215], v143 offset:19456
	ds_read_b128 v[216:219], v143 offset:20480
	ds_read_b128 v[220:223], v143 offset:21504
	ds_read_b128 v[224:227], v143 offset:22528
	ds_read_b128 v[228:231], v143 offset:23552
	global_load_lds_dwordx4 v[140:141], off
	s_add_i32 m0, s8, 0x2000
	s_add_u32 s22, s50, 0x40000
	v_lshl_add_u64 v[176:177], s[50:51], 0, v[130:131]
	s_addc_u32 s23, s51, 0
	s_add_i32 s2, s2, s3
	global_load_lds_dwordx4 v[176:177], off
	v_lshl_add_u64 v[232:233], s[22:23], 0, v[0:1]
	s_mov_b32 m0, s2
	v_lshl_add_u64 v[234:235], s[52:53], 0, v[132:133]
	global_load_lds_dwordx4 v[232:233], off
	v_lshl_add_u64 v[232:233], s[22:23], 0, v[130:131]
	s_add_i32 m0, s2, 0x2000
	s_nop 0
	global_load_lds_dwordx4 v[232:233], off
	v_lshl_add_u64 v[232:233], s[52:53], 0, v[134:135]
	s_mov_b32 m0, s4
	s_nop 0
	global_load_lds_dwordx4 v[232:233], off
	s_mov_b32 m0, s5
	s_nop 0
	global_load_lds_dwordx4 v[234:235], off
	s_waitcnt vmcnt(8)
	s_waitcnt lgkmcnt(0)
	s_barrier
; #define PG8_STAGE(bufoff, gbase, voff) do { _Pragma("unroll") for (int _i = 0; _i < 2; ++_i) \
;         __builtin_amdgcn_global_load_lds((const unsigned*)((const char*)(gbase) + (voff)[_i]), (PG8_LAS unsigned*)(lds + (bufoff) + ldsw + _i * 8192), 16, 0, 0); } while (0)
; #define PG8_LDA(dst, b, h) do { _Pragma("unroll") for (int m = 0; m < 4; ++m) _Pragma("unroll") for (int k = 0; k < 2; ++k) dst[m][k] = *(const PG8_LAS bf16x8*)(lds + PG8_SA(b, h) + aoff + m * 2048 + k * 1024); } while (0)
; #define PG8_LDB(dst, b, h) do { _Pragma("unroll") for (int n = 0; n < 2; ++n) _Pragma("unroll") for (int k = 0; k < 2; ++k) dst[n][k] = *(const PG8_LAS bf16x8*)(lds + PG8_SB(b, h) + boff + n * 2048 + k * 1024); } while (0)
; #define PG8_MMA(ai, bj, At, Bt) do { __builtin_amdgcn_s_setprio(1); _Pragma("unroll") for (int m = 0; m < 4; ++m) _Pragma("unroll") for (int n = 0; n < 2; ++n) _Pragma("unroll") for (int k = 0; k < 2; ++k) \
;         acc[ai][bj][m][n] = __builtin_amdgcn_mfma_f32_16x16x32_bf16(Bt[n][k], At[m][k], acc[ai][bj][m][n], 0, 0, 0); __builtin_amdgcn_s_setprio(0); } while (0)
; #define PG8_WAIT_V(n) asm volatile("s_waitcnt vmcnt(" #n ")" ::: "memory")
; #define PG8_WAIT_L(n) asm volatile("s_waitcnt lgkmcnt(" #n ")" ::: "memory")
; #define PG8_BAR __builtin_amdgcn_s_barrier()
; #define PG8_SCHED __builtin_amdgcn_sched_barrier(0)
; template <class Epi, class Sched, bool ALIGN_EPI = false, bool SP2 = false>
; __device__ __forceinline__ void gemm_phase(PG8_LAS unsigned char* lds, const Gemm g, const Sched& S, const Epi& E, const int wid_in) {
;     ...
;             PG8_LDA(At, 0, 1); PG8_STAGE(PG8_SB(0, 0), b2, voffB); PG8_STAGE(PG8_SB(0, 1), b2 + hstep, voffB); PG8_STAGE(PG8_SA(0, 0), a2, voffA);
;             PG8_WAIT_V(8); PG8_WAIT_L(0); PG8_BAR; PG8_MMA(1, 0, At, B0); PG8_MMA(1, 1, At, B1); PG8_BAR; PG8_SCHED;
;             PG8_LDB(B0, 1, 0); PG8_LDB(B1, 1, 1); PG8_SCHED; PG8_LDA(At, 1, 0); PG8_STAGE(PG8_SA(0, 1), a2 + hstep, voffA);
;             PG8_WAIT_V(8); PG8_WAIT_L(0); PG8_BAR; PG8_MMA(0, 0, At, B0); PG8_MMA(0, 1, At, B1); PG8_BAR; PG8_SCHED;
	s_waitcnt lgkmcnt(0)
	v_mfma_f32_16x16x32_bf16 v[62:65], v[144:147], v[190:193], 0
	v_mfma_f32_16x16x32_bf16 v[58:61], v[152:155], v[190:193], 0
	v_mfma_f32_16x16x32_bf16 v[54:57], v[144:147], v[198:201], 0
	v_mfma_f32_16x16x32_bf16 v[46:49], v[152:155], v[198:201], 0
	v_mfma_f32_16x16x32_bf16 v[38:41], v[144:147], v[216:219], 0
	v_mfma_f32_16x16x32_bf16 v[30:33], v[152:155], v[216:219], 0
	v_mfma_f32_16x16x32_bf16 v[22:25], v[144:147], v[224:227], 0
	v_mfma_f32_16x16x32_bf16 v[14:17], v[152:155], v[224:227], 0
	v_mfma_f32_16x16x32_bf16 v[62:65], v[148:151], v[194:197], v[62:65]
	v_mfma_f32_16x16x32_bf16 v[58:61], v[156:159], v[194:197], v[58:61]
	v_mfma_f32_16x16x32_bf16 v[54:57], v[148:151], v[212:215], v[54:57]
	v_mfma_f32_16x16x32_bf16 v[46:49], v[156:159], v[212:215], v[46:49]
	v_mfma_f32_16x16x32_bf16 v[38:41], v[148:151], v[220:223], v[38:41]
	v_mfma_f32_16x16x32_bf16 v[30:33], v[156:159], v[220:223], v[30:33]
	v_mfma_f32_16x16x32_bf16 v[22:25], v[148:151], v[228:231], v[22:25]
	v_mfma_f32_16x16x32_bf16 v[14:17], v[156:159], v[228:231], v[14:17]
	v_mfma_f32_16x16x32_bf16 v[50:53], v[160:163], v[190:193], 0
	v_mfma_f32_16x16x32_bf16 v[42:45], v[168:171], v[190:193], 0
	v_mfma_f32_16x16x32_bf16 v[34:37], v[160:163], v[198:201], 0
	v_mfma_f32_16x16x32_bf16 v[26:29], v[168:171], v[198:201], 0
	v_mfma_f32_16x16x32_bf16 v[18:21], v[160:163], v[216:219], 0
	v_mfma_f32_16x16x32_bf16 v[10:13], v[168:171], v[216:219], 0
	v_mfma_f32_16x16x32_bf16 v[6:9], v[160:163], v[224:227], 0
	v_mfma_f32_16x16x32_bf16 v[2:5], v[168:171], v[224:227], 0
	v_mfma_f32_16x16x32_bf16 v[50:53], v[164:167], v[194:197], v[50:53]
	v_mfma_f32_16x16x32_bf16 v[42:45], v[172:175], v[194:197], v[42:45]
	v_mfma_f32_16x16x32_bf16 v[34:37], v[164:167], v[212:215], v[34:37]
	v_mfma_f32_16x16x32_bf16 v[26:29], v[172:175], v[212:215], v[26:29]
	v_mfma_f32_16x16x32_bf16 v[18:21], v[164:167], v[220:223], v[18:21]
	v_mfma_f32_16x16x32_bf16 v[10:13], v[172:175], v[220:223], v[10:13]
	v_mfma_f32_16x16x32_bf16 v[6:9], v[164:167], v[228:231], v[6:9]
	v_mfma_f32_16x16x32_bf16 v[2:5], v[172:175], v[228:231], v[2:5]
	s_barrier
	s_add_i32 s2, 0, 0x18000
	s_add_i32 s8, 0, 0x1c000
	v_add_u32_e32 v156, s2, v142
	v_add_u32_e32 v172, s8, v142
	ds_read_b128 v[144:147], v156
	ds_read_b128 v[148:151], v156 offset:1024
	ds_read_b128 v[152:155], v156 offset:2048
	ds_read_b128 v[156:159], v156 offset:3072
	ds_read_b128 v[160:163], v172
	ds_read_b128 v[164:167], v172 offset:1024
	ds_read_b128 v[168:171], v172 offset:2048
	ds_read_b128 v[172:175], v172 offset:3072
	s_add_u32 s22, s52, 0x40000
	s_addc_u32 s23, s53, 0
	s_mov_b32 m0, s12
	v_lshl_add_u64 v[236:237], s[22:23], 0, v[134:135]
	ds_read_b128 v[190:193], v143 offset:32768
	ds_read_b128 v[194:197], v143 offset:33792
	ds_read_b128 v[198:201], v143 offset:34816
	ds_read_b128 v[212:215], v143 offset:35840
	ds_read_b128 v[216:219], v143 offset:36864
	ds_read_b128 v[220:223], v143 offset:37888
	ds_read_b128 v[224:227], v143 offset:38912
	ds_read_b128 v[228:231], v143 offset:39936
	global_load_lds_dwordx4 v[236:237], off
	v_lshl_add_u64 v[236:237], s[22:23], 0, v[132:133]
	s_mov_b32 m0, s13
	s_nop 0
	global_load_lds_dwordx4 v[236:237], off
	s_waitcnt vmcnt(8)
	s_waitcnt lgkmcnt(0)
	s_barrier
	s_waitcnt lgkmcnt(0)
	v_mfma_f32_16x16x32_bf16 v[126:129], v[144:147], v[190:193], v[126:129]
	v_mfma_f32_16x16x32_bf16 v[122:125], v[152:155], v[190:193], v[122:125]
	v_mfma_f32_16x16x32_bf16 v[118:121], v[144:147], v[198:201], v[118:121]
	v_mfma_f32_16x16x32_bf16 v[110:113], v[152:155], v[198:201], v[110:113]
	v_mfma_f32_16x16x32_bf16 v[102:105], v[144:147], v[216:219], v[102:105]
	v_mfma_f32_16x16x32_bf16 v[94:97], v[152:155], v[216:219], v[94:97]
	v_mfma_f32_16x16x32_bf16 v[82:85], v[144:147], v[224:227], v[82:85]
	v_mfma_f32_16x16x32_bf16 v[74:77], v[152:155], v[224:227], v[74:77]
	v_mfma_f32_16x16x32_bf16 v[126:129], v[148:151], v[194:197], v[126:129]
	v_mfma_f32_16x16x32_bf16 v[122:125], v[156:159], v[194:197], v[122:125]
	v_mfma_f32_16x16x32_bf16 v[118:121], v[148:151], v[212:215], v[118:121]
	v_mfma_f32_16x16x32_bf16 v[110:113], v[156:159], v[212:215], v[110:113]
	v_mfma_f32_16x16x32_bf16 v[102:105], v[148:151], v[220:223], v[102:105]
	v_mfma_f32_16x16x32_bf16 v[94:97], v[156:159], v[220:223], v[94:97]
	v_mfma_f32_16x16x32_bf16 v[82:85], v[148:151], v[228:231], v[82:85]
	v_mfma_f32_16x16x32_bf16 v[74:77], v[156:159], v[228:231], v[74:77]
	v_mfma_f32_16x16x32_bf16 v[114:117], v[160:163], v[190:193], v[114:117]
	v_mfma_f32_16x16x32_bf16 v[106:109], v[168:171], v[190:193], v[106:109]
	v_mfma_f32_16x16x32_bf16 v[98:101], v[160:163], v[198:201], v[98:101]
	v_mfma_f32_16x16x32_bf16 v[90:93], v[168:171], v[198:201], v[90:93]
	v_mfma_f32_16x16x32_bf16 v[86:89], v[160:163], v[216:219], v[86:89]
	v_mfma_f32_16x16x32_bf16 v[78:81], v[168:171], v[216:219], v[78:81]
	v_mfma_f32_16x16x32_bf16 v[70:73], v[160:163], v[224:227], v[70:73]
	v_mfma_f32_16x16x32_bf16 v[66:69], v[168:171], v[224:227], v[66:69]
	v_mfma_f32_16x16x32_bf16 v[114:117], v[164:167], v[194:197], v[114:117]
	v_mfma_f32_16x16x32_bf16 v[106:109], v[172:175], v[194:197], v[106:109]
	v_mfma_f32_16x16x32_bf16 v[98:101], v[164:167], v[212:215], v[98:101]
	v_mfma_f32_16x16x32_bf16 v[90:93], v[172:175], v[212:215], v[90:93]
	v_mfma_f32_16x16x32_bf16 v[86:89], v[164:167], v[220:223], v[86:89]
	v_mfma_f32_16x16x32_bf16 v[78:81], v[172:175], v[220:223], v[78:81]
	v_mfma_f32_16x16x32_bf16 v[70:73], v[164:167], v[228:231], v[70:73]
	v_mfma_f32_16x16x32_bf16 v[66:69], v[172:175], v[228:231], v[66:69]
	s_barrier
; #define PG8_STAGE(bufoff, gbase, voff) do { _Pragma("unroll") for (int _i = 0; _i < 2; ++_i) \
;         __builtin_amdgcn_global_load_lds((const unsigned*)((const char*)(gbase) + (voff)[_i]), (PG8_LAS unsigned*)(lds + (bufoff) + ldsw + _i * 8192), 16, 0, 0); } while (0)
; #define PG8_LDA(dst, b, h) do { _Pragma("unroll") for (int m = 0; m < 4; ++m) _Pragma("unroll") for (int k = 0; k < 2; ++k) dst[m][k] = *(const PG8_LAS bf16x8*)(lds + PG8_SA(b, h) + aoff + m * 2048 + k * 1024); } while (0)
; #define PG8_LDB(dst, b, h) do { _Pragma("unroll") for (int n = 0; n < 2; ++n) _Pragma("unroll") for (int k = 0; k < 2; ++k) dst[n][k] = *(const PG8_LAS bf16x8*)(lds + PG8_SB(b, h) + boff + n * 2048 + k * 1024); } while (0)
; #define PG8_MMA(ai, bj, At, Bt) do { __builtin_amdgcn_s_setprio(1); _Pragma("unroll") for (int m = 0; m < 4; ++m) _Pragma("unroll") for (int n = 0; n < 2; ++n) _Pragma("unroll") for (int k = 0; k < 2; ++k) \
;         acc[ai][bj][m][n] = __builtin_amdgcn_mfma_f32_16x16x32_bf16(Bt[n][k], At[m][k], acc[ai][bj][m][n], 0, 0, 0); __builtin_amdgcn_s_setprio(0); } while (0)
; #define PG8_WAIT_V(n) asm volatile("s_waitcnt vmcnt(" #n ")" ::: "memory")
; #define PG8_WAIT_L(n) asm volatile("s_waitcnt lgkmcnt(" #n ")" ::: "memory")
; #define PG8_BAR __builtin_amdgcn_s_barrier()
; template <class Epi, class Sched, bool ALIGN_EPI = false, bool SP2 = false>
; __device__ __forceinline__ void gemm_phase(PG8_LAS unsigned char* lds, const Gemm g, const Sched& S, const Epi& E, const int wid_in) {
;     ...
;         for (int t = 0; t < nt; t += 2) {
;             const bool last = (t == nt - 2);
;             const char* a1 = cA + (size_t)(t + 1) * kstep;
;             const char* a2 = last ? nA : cA + (size_t)(t + 2) * kstep; const char* b2 = last ? nB : cB + (size_t)(t + 2) * kstep;
;             const char* a3 = a2 + kstep; const char* b3 = b2 + kstep;
;     ...
;             PG8_LDB(B0, 1, 0); PG8_LDB(B1, 1, 1); PG8_SCHED; PG8_LDA(At, 1, 0); PG8_STAGE(PG8_SA(0, 1), a2 + hstep, voffA);
;             PG8_WAIT_V(8); PG8_WAIT_L(0); PG8_BAR; PG8_MMA(0, 0, At, B0); PG8_MMA(0, 1, At, B1); PG8_BAR; PG8_SCHED;
;             PG8_LDA(At, 1, 1); PG8_STAGE(PG8_SB(1, 0), b3, voffB); PG8_STAGE(PG8_SB(1, 1), b3 + hstep, voffB); PG8_STAGE(PG8_SA(1, 0), a3, voffA);
;             PG8_WAIT_V(8); PG8_WAIT_L(0); PG8_BAR; PG8_MMA(1, 0, At, B0); PG8_MMA(1, 1, At, B1); PG8_BAR; PG8_SCHED;
	s_add_i32 s2, s2, s3
	v_lshl_add_u64 v[140:141], v[140:141], 0, s[64:65]
	s_mov_b32 m0, s2
	ds_read_b128 v[190:193], v143 offset:49152
	ds_read_b128 v[194:197], v143 offset:50176
	ds_read_b128 v[198:201], v143 offset:51200
	ds_read_b128 v[212:215], v143 offset:52224
	ds_read_b128 v[216:219], v143 offset:53248
	ds_read_b128 v[220:223], v143 offset:54272
	ds_read_b128 v[224:227], v143 offset:55296
	ds_read_b128 v[228:231], v143 offset:56320
	global_load_lds_dwordx4 v[140:141], off
	s_add_i32 m0, s2, 0x2000
	s_add_u32 s22, s50, 0x40080
	v_lshl_add_u64 v[140:141], v[176:177], 0, s[64:65]
	s_addc_u32 s23, s51, 0
	s_add_i32 s2, s8, s3
	global_load_lds_dwordx4 v[140:141], off
	v_lshl_add_u64 v[140:141], s[22:23], 0, v[0:1]
	s_mov_b32 m0, s2
	s_nop 0
	global_load_lds_dwordx4 v[140:141], off
	v_lshl_add_u64 v[140:141], s[22:23], 0, v[130:131]
	s_add_i32 m0, s2, 0x2000
	s_nop 0
	global_load_lds_dwordx4 v[140:141], off
	v_lshl_add_u64 v[140:141], v[232:233], 0, s[64:65]
	s_mov_b32 m0, s36
	s_nop 0
	global_load_lds_dwordx4 v[140:141], off
	v_lshl_add_u64 v[140:141], v[234:235], 0, s[64:65]
	s_mov_b32 m0, s37
	s_nop 0
	global_load_lds_dwordx4 v[140:141], off
	s_add_i32 s60, s60, 2
	s_add_u32 s48, s48, 0x100
	s_addc_u32 s49, s49, 0
	s_add_u32 s58, s58, 0x100
	s_addc_u32 s59, s59, 0
	s_add_u32 s2, s48, 0xfffc0080
	s_addc_u32 s8, s49, -1
	s_add_i32 s9, 0, 0x10000
	s_cmp_eq_u32 s60, 12
	s_cselect_b32 s53, s43, s8
	s_cselect_b32 s52, s57, s2
	s_cselect_b32 s51, s16, s59
	s_cselect_b32 s50, s39, s58
	s_add_i32 s2, 0, 0x14000
	s_cmp_gt_u32 s60, 13
	s_waitcnt vmcnt(8)
	s_waitcnt lgkmcnt(0)
	s_barrier
	s_waitcnt lgkmcnt(0)
	v_mfma_f32_16x16x32_bf16 v[62:65], v[144:147], v[190:193], v[62:65]
	v_mfma_f32_16x16x32_bf16 v[58:61], v[152:155], v[190:193], v[58:61]
	v_mfma_f32_16x16x32_bf16 v[54:57], v[144:147], v[198:201], v[54:57]
	v_mfma_f32_16x16x32_bf16 v[46:49], v[152:155], v[198:201], v[46:49]
	v_mfma_f32_16x16x32_bf16 v[38:41], v[144:147], v[216:219], v[38:41]
	v_mfma_f32_16x16x32_bf16 v[30:33], v[152:155], v[216:219], v[30:33]
	v_mfma_f32_16x16x32_bf16 v[22:25], v[144:147], v[224:227], v[22:25]
	v_mfma_f32_16x16x32_bf16 v[14:17], v[152:155], v[224:227], v[14:17]
	v_mfma_f32_16x16x32_bf16 v[62:65], v[148:151], v[194:197], v[62:65]
	v_mfma_f32_16x16x32_bf16 v[58:61], v[156:159], v[194:197], v[58:61]
	v_mfma_f32_16x16x32_bf16 v[54:57], v[148:151], v[212:215], v[54:57]
	v_mfma_f32_16x16x32_bf16 v[46:49], v[156:159], v[212:215], v[46:49]
	v_mfma_f32_16x16x32_bf16 v[38:41], v[148:151], v[220:223], v[38:41]
	v_mfma_f32_16x16x32_bf16 v[30:33], v[156:159], v[220:223], v[30:33]
	v_mfma_f32_16x16x32_bf16 v[22:25], v[148:151], v[228:231], v[22:25]
	v_mfma_f32_16x16x32_bf16 v[14:17], v[156:159], v[228:231], v[14:17]
	v_mfma_f32_16x16x32_bf16 v[50:53], v[160:163], v[190:193], v[50:53]
	v_mfma_f32_16x16x32_bf16 v[42:45], v[168:171], v[190:193], v[42:45]
	v_mfma_f32_16x16x32_bf16 v[34:37], v[160:163], v[198:201], v[34:37]
	v_mfma_f32_16x16x32_bf16 v[26:29], v[168:171], v[198:201], v[26:29]
	v_mfma_f32_16x16x32_bf16 v[18:21], v[160:163], v[216:219], v[18:21]
	v_mfma_f32_16x16x32_bf16 v[10:13], v[168:171], v[216:219], v[10:13]
	v_mfma_f32_16x16x32_bf16 v[6:9], v[160:163], v[224:227], v[6:9]
	v_mfma_f32_16x16x32_bf16 v[2:5], v[168:171], v[224:227], v[2:5]
	v_mfma_f32_16x16x32_bf16 v[50:53], v[164:167], v[194:197], v[50:53]
	v_mfma_f32_16x16x32_bf16 v[42:45], v[172:175], v[194:197], v[42:45]
	v_mfma_f32_16x16x32_bf16 v[34:37], v[164:167], v[212:215], v[34:37]
	v_mfma_f32_16x16x32_bf16 v[26:29], v[172:175], v[212:215], v[26:29]
	v_mfma_f32_16x16x32_bf16 v[18:21], v[164:167], v[220:223], v[18:21]
	v_mfma_f32_16x16x32_bf16 v[10:13], v[172:175], v[220:223], v[10:13]
	v_mfma_f32_16x16x32_bf16 v[6:9], v[164:167], v[228:231], v[6:9]
	v_mfma_f32_16x16x32_bf16 v[2:5], v[172:175], v[228:231], v[2:5]
	s_barrier
.LBB0_537:
	v_add_u32_e32 v140, s9, v142
	ds_read_b128 v[144:147], v140
	ds_read_b128 v[148:151], v140 offset:1024
	ds_read_b128 v[152:155], v140 offset:2048
	ds_read_b128 v[156:159], v140 offset:3072
	v_add_u32_e32 v140, s2, v142
	ds_read_b128 v[160:163], v140
	ds_read_b128 v[164:167], v140 offset:1024
	ds_read_b128 v[168:171], v140 offset:2048
	ds_read_b128 v[172:175], v140 offset:3072
	v_lshl_add_u64 v[140:141], s[48:49], 0, v[136:137]
	s_add_i32 m0, s4, 0xc000
	ds_read_b128 v[190:193], v143
	ds_read_b128 v[194:197], v143 offset:1024
	ds_read_b128 v[198:201], v143 offset:2048
	ds_read_b128 v[212:215], v143 offset:3072
	ds_read_b128 v[216:219], v143 offset:4096
	ds_read_b128 v[220:223], v143 offset:5120
	ds_read_b128 v[224:227], v143 offset:6144
	ds_read_b128 v[228:231], v143 offset:7168
	global_load_lds_dwordx4 v[140:141], off
	v_lshl_add_u64 v[140:141], s[48:49], 0, v[138:139]
	s_add_i32 m0, s4, 0xe000
	s_nop 0
	global_load_lds_dwordx4 v[140:141], off
	s_waitcnt vmcnt(8)
	s_waitcnt lgkmcnt(0)
	s_barrier
; #define PG8_STAGE(bufoff, gbase, voff) do { _Pragma("unroll") for (int _i = 0; _i < 2; ++_i) \
;         __builtin_amdgcn_global_load_lds((const unsigned*)((const char*)(gbase) + (voff)[_i]), (PG8_LAS unsigned*)(lds + (bufoff) + ldsw + _i * 8192), 16, 0, 0); } while (0)
; #define PG8_LDA(dst, b, h) do { _Pragma("unroll") for (int m = 0; m < 4; ++m) _Pragma("unroll") for (int k = 0; k < 2; ++k) dst[m][k] = *(const PG8_LAS bf16x8*)(lds + PG8_SA(b, h) + aoff + m * 2048 + k * 1024); } while (0)
; #define PG8_LDB(dst, b, h) do { _Pragma("unroll") for (int n = 0; n < 2; ++n) _Pragma("unroll") for (int k = 0; k < 2; ++k) dst[n][k] = *(const PG8_LAS bf16x8*)(lds + PG8_SB(b, h) + boff + n * 2048 + k * 1024); } while (0)
; #define PG8_MMA(ai, bj, At, Bt) do { __builtin_amdgcn_s_setprio(1); _Pragma("unroll") for (int m = 0; m < 4; ++m) _Pragma("unroll") for (int n = 0; n < 2; ++n) _Pragma("unroll") for (int k = 0; k < 2; ++k) \
;         acc[ai][bj][m][n] = __builtin_amdgcn_mfma_f32_16x16x32_bf16(Bt[n][k], At[m][k], acc[ai][bj][m][n], 0, 0, 0); __builtin_amdgcn_s_setprio(0); } while (0)
; #define PG8_WAIT_V(n) asm volatile("s_waitcnt vmcnt(" #n ")" ::: "memory")
; #define PG8_WAIT_L(n) asm volatile("s_waitcnt lgkmcnt(" #n ")" ::: "memory")
; #define PG8_BAR __builtin_amdgcn_s_barrier()
; #define PG8_SCHED __builtin_amdgcn_sched_barrier(0)
; template <class Epi, class Sched, bool ALIGN_EPI = false, bool SP2 = false>
; __device__ __forceinline__ void gemm_phase(PG8_LAS unsigned char* lds, const Gemm g, const Sched& S, const Epi& E, const int wid_in) {
;     ...
;             PG8_LDB(B0, 0, 0); PG8_LDB(B1, 0, 1); PG8_SCHED; PG8_LDA(At, 0, 0); PG8_STAGE(PG8_SA(1, 1), a1 + hstep, voffA);
;             PG8_WAIT_V(8); PG8_WAIT_L(0); PG8_BAR; PG8_MMA(0, 0, At, B0); PG8_MMA(0, 1, At, B1); PG8_BAR; PG8_SCHED;
;             PG8_LDA(At, 0, 1); PG8_STAGE(PG8_SB(0, 0), b2, voffB); PG8_STAGE(PG8_SB(0, 1), b2 + hstep, voffB); PG8_STAGE(PG8_SA(0, 0), a2, voffA);
;             PG8_WAIT_V(8); PG8_WAIT_L(0); PG8_BAR; PG8_MMA(1, 0, At, B0); PG8_MMA(1, 1, At, B1); PG8_BAR; PG8_SCHED;
	s_waitcnt lgkmcnt(0)
	v_mfma_f32_16x16x32_bf16 v[126:129], v[144:147], v[190:193], v[126:129]
	v_mfma_f32_16x16x32_bf16 v[122:125], v[152:155], v[190:193], v[122:125]
	v_mfma_f32_16x16x32_bf16 v[118:121], v[144:147], v[198:201], v[118:121]
	v_mfma_f32_16x16x32_bf16 v[110:113], v[152:155], v[198:201], v[110:113]
	v_mfma_f32_16x16x32_bf16 v[102:105], v[144:147], v[216:219], v[102:105]
	v_mfma_f32_16x16x32_bf16 v[94:97], v[152:155], v[216:219], v[94:97]
	v_mfma_f32_16x16x32_bf16 v[82:85], v[144:147], v[224:227], v[82:85]
	v_mfma_f32_16x16x32_bf16 v[74:77], v[152:155], v[224:227], v[74:77]
	v_mfma_f32_16x16x32_bf16 v[126:129], v[148:151], v[194:197], v[126:129]
	v_mfma_f32_16x16x32_bf16 v[122:125], v[156:159], v[194:197], v[122:125]
	v_mfma_f32_16x16x32_bf16 v[118:121], v[148:151], v[212:215], v[118:121]
	v_mfma_f32_16x16x32_bf16 v[110:113], v[156:159], v[212:215], v[110:113]
	v_mfma_f32_16x16x32_bf16 v[102:105], v[148:151], v[220:223], v[102:105]
	v_mfma_f32_16x16x32_bf16 v[94:97], v[156:159], v[220:223], v[94:97]
	v_mfma_f32_16x16x32_bf16 v[82:85], v[148:151], v[228:231], v[82:85]
	v_mfma_f32_16x16x32_bf16 v[74:77], v[156:159], v[228:231], v[74:77]
	v_mfma_f32_16x16x32_bf16 v[114:117], v[160:163], v[190:193], v[114:117]
	v_mfma_f32_16x16x32_bf16 v[106:109], v[168:171], v[190:193], v[106:109]
	v_mfma_f32_16x16x32_bf16 v[98:101], v[160:163], v[198:201], v[98:101]
	v_mfma_f32_16x16x32_bf16 v[90:93], v[168:171], v[198:201], v[90:93]
	v_mfma_f32_16x16x32_bf16 v[86:89], v[160:163], v[216:219], v[86:89]
	v_mfma_f32_16x16x32_bf16 v[78:81], v[168:171], v[216:219], v[78:81]
	v_mfma_f32_16x16x32_bf16 v[70:73], v[160:163], v[224:227], v[70:73]
	v_mfma_f32_16x16x32_bf16 v[66:69], v[168:171], v[224:227], v[66:69]
	v_mfma_f32_16x16x32_bf16 v[114:117], v[164:167], v[194:197], v[114:117]
	v_mfma_f32_16x16x32_bf16 v[106:109], v[172:175], v[194:197], v[106:109]
	v_mfma_f32_16x16x32_bf16 v[98:101], v[164:167], v[212:215], v[98:101]
	v_mfma_f32_16x16x32_bf16 v[90:93], v[172:175], v[212:215], v[90:93]
	v_mfma_f32_16x16x32_bf16 v[86:89], v[164:167], v[220:223], v[86:89]
	v_mfma_f32_16x16x32_bf16 v[78:81], v[172:175], v[220:223], v[78:81]
	v_mfma_f32_16x16x32_bf16 v[70:73], v[164:167], v[228:231], v[70:73]
	v_mfma_f32_16x16x32_bf16 v[66:69], v[172:175], v[228:231], v[66:69]
	s_barrier
	s_add_i32 s8, s9, s3
	v_lshl_add_u64 v[140:141], s[50:51], 0, v[0:1]
	s_mov_b32 m0, s8
	ds_read_b128 v[190:193], v143 offset:16384
	ds_read_b128 v[194:197], v143 offset:17408
	ds_read_b128 v[198:201], v143 offset:18432
	ds_read_b128 v[212:215], v143 offset:19456
	ds_read_b128 v[216:219], v143 offset:20480
	ds_read_b128 v[220:223], v143 offset:21504
	ds_read_b128 v[224:227], v143 offset:22528
	ds_read_b128 v[228:231], v143 offset:23552
	global_load_lds_dwordx4 v[140:141], off
	s_add_i32 m0, s8, 0x2000
	s_add_u32 s22, s50, 0x40000
	v_lshl_add_u64 v[176:177], s[50:51], 0, v[130:131]
	s_addc_u32 s23, s51, 0
	s_add_i32 s2, s2, s3
	global_load_lds_dwordx4 v[176:177], off
	v_lshl_add_u64 v[232:233], s[22:23], 0, v[0:1]
	s_mov_b32 m0, s2
	v_lshl_add_u64 v[234:235], s[52:53], 0, v[132:133]
	global_load_lds_dwordx4 v[232:233], off
	v_lshl_add_u64 v[232:233], s[22:23], 0, v[130:131]
	s_add_i32 m0, s2, 0x2000
	s_nop 0
	global_load_lds_dwordx4 v[232:233], off
	v_lshl_add_u64 v[232:233], s[52:53], 0, v[134:135]
	s_mov_b32 m0, s4
	s_nop 0
	global_load_lds_dwordx4 v[232:233], off
	s_mov_b32 m0, s5
	s_nop 0
	global_load_lds_dwordx4 v[234:235], off
	s_waitcnt vmcnt(8)
	s_waitcnt lgkmcnt(0)
	s_barrier
	s_waitcnt lgkmcnt(0)
	v_mfma_f32_16x16x32_bf16 v[62:65], v[144:147], v[190:193], v[62:65]
	v_mfma_f32_16x16x32_bf16 v[58:61], v[152:155], v[190:193], v[58:61]
	v_mfma_f32_16x16x32_bf16 v[54:57], v[144:147], v[198:201], v[54:57]
	v_mfma_f32_16x16x32_bf16 v[46:49], v[152:155], v[198:201], v[46:49]
	v_mfma_f32_16x16x32_bf16 v[38:41], v[144:147], v[216:219], v[38:41]
	v_mfma_f32_16x16x32_bf16 v[30:33], v[152:155], v[216:219], v[30:33]
	v_mfma_f32_16x16x32_bf16 v[22:25], v[144:147], v[224:227], v[22:25]
	v_mfma_f32_16x16x32_bf16 v[14:17], v[152:155], v[224:227], v[14:17]
	v_mfma_f32_16x16x32_bf16 v[62:65], v[148:151], v[194:197], v[62:65]
	v_mfma_f32_16x16x32_bf16 v[58:61], v[156:159], v[194:197], v[58:61]
	v_mfma_f32_16x16x32_bf16 v[54:57], v[148:151], v[212:215], v[54:57]
	v_mfma_f32_16x16x32_bf16 v[46:49], v[156:159], v[212:215], v[46:49]
	v_mfma_f32_16x16x32_bf16 v[38:41], v[148:151], v[220:223], v[38:41]
	v_mfma_f32_16x16x32_bf16 v[30:33], v[156:159], v[220:223], v[30:33]
	v_mfma_f32_16x16x32_bf16 v[22:25], v[148:151], v[228:231], v[22:25]
	v_mfma_f32_16x16x32_bf16 v[14:17], v[156:159], v[228:231], v[14:17]
	v_mfma_f32_16x16x32_bf16 v[50:53], v[160:163], v[190:193], v[50:53]
	v_mfma_f32_16x16x32_bf16 v[42:45], v[168:171], v[190:193], v[42:45]
	v_mfma_f32_16x16x32_bf16 v[34:37], v[160:163], v[198:201], v[34:37]
	v_mfma_f32_16x16x32_bf16 v[26:29], v[168:171], v[198:201], v[26:29]
	v_mfma_f32_16x16x32_bf16 v[18:21], v[160:163], v[216:219], v[18:21]
	v_mfma_f32_16x16x32_bf16 v[10:13], v[168:171], v[216:219], v[10:13]
	v_mfma_f32_16x16x32_bf16 v[6:9], v[160:163], v[224:227], v[6:9]
	v_mfma_f32_16x16x32_bf16 v[2:5], v[168:171], v[224:227], v[2:5]
	v_mfma_f32_16x16x32_bf16 v[50:53], v[164:167], v[194:197], v[50:53]
	v_mfma_f32_16x16x32_bf16 v[42:45], v[172:175], v[194:197], v[42:45]
	v_mfma_f32_16x16x32_bf16 v[34:37], v[164:167], v[212:215], v[34:37]
	v_mfma_f32_16x16x32_bf16 v[26:29], v[172:175], v[212:215], v[26:29]
	v_mfma_f32_16x16x32_bf16 v[18:21], v[164:167], v[220:223], v[18:21]
	v_mfma_f32_16x16x32_bf16 v[10:13], v[172:175], v[220:223], v[10:13]
	v_mfma_f32_16x16x32_bf16 v[6:9], v[164:167], v[228:231], v[6:9]
	v_mfma_f32_16x16x32_bf16 v[2:5], v[172:175], v[228:231], v[2:5]
	s_barrier
; #define PG8_STAGE(bufoff, gbase, voff) do { _Pragma("unroll") for (int _i = 0; _i < 2; ++_i) \
;         __builtin_amdgcn_global_load_lds((const unsigned*)((const char*)(gbase) + (voff)[_i]), (PG8_LAS unsigned*)(lds + (bufoff) + ldsw + _i * 8192), 16, 0, 0); } while (0)
; #define PG8_LDA(dst, b, h) do { _Pragma("unroll") for (int m = 0; m < 4; ++m) _Pragma("unroll") for (int k = 0; k < 2; ++k) dst[m][k] = *(const PG8_LAS bf16x8*)(lds + PG8_SA(b, h) + aoff + m * 2048 + k * 1024); } while (0)
; #define PG8_LDB(dst, b, h) do { _Pragma("unroll") for (int n = 0; n < 2; ++n) _Pragma("unroll") for (int k = 0; k < 2; ++k) dst[n][k] = *(const PG8_LAS bf16x8*)(lds + PG8_SB(b, h) + boff + n * 2048 + k * 1024); } while (0)
; #define PG8_MMA(ai, bj, At, Bt) do { __builtin_amdgcn_s_setprio(1); _Pragma("unroll") for (int m = 0; m < 4; ++m) _Pragma("unroll") for (int n = 0; n < 2; ++n) _Pragma("unroll") for (int k = 0; k < 2; ++k) \
;         acc[ai][bj][m][n] = __builtin_amdgcn_mfma_f32_16x16x32_bf16(Bt[n][k], At[m][k], acc[ai][bj][m][n], 0, 0, 0); __builtin_amdgcn_s_setprio(0); } while (0)
; #define PG8_WAIT_V(n) asm volatile("s_waitcnt vmcnt(" #n ")" ::: "memory")
; #define PG8_WAIT_L(n) asm volatile("s_waitcnt lgkmcnt(" #n ")" ::: "memory")
; #define PG8_BAR __builtin_amdgcn_s_barrier()
; #define PG8_SCHED __builtin_amdgcn_sched_barrier(0)
; template <class Epi, class Sched, bool ALIGN_EPI = false, bool SP2 = false>
; __device__ __forceinline__ void gemm_phase(PG8_LAS unsigned char* lds, const Gemm g, const Sched& S, const Epi& E, const int wid_in) {
;     ...
;             PG8_LDB(B0, 1, 0); PG8_LDB(B1, 1, 1); PG8_SCHED; PG8_LDA(At, 1, 0); PG8_STAGE(PG8_SA(0, 1), a2 + hstep, voffA);
;             PG8_WAIT_V(8); PG8_WAIT_L(0); PG8_BAR; PG8_MMA(0, 0, At, B0); PG8_MMA(0, 1, At, B1); PG8_BAR; PG8_SCHED;
	s_add_i32 s2, 0, 0x18000
	s_add_i32 s8, 0, 0x1c000
	v_add_u32_e32 v156, s2, v142
	v_add_u32_e32 v172, s8, v142
	ds_read_b128 v[144:147], v156
	ds_read_b128 v[148:151], v156 offset:1024
	ds_read_b128 v[152:155], v156 offset:2048
	ds_read_b128 v[156:159], v156 offset:3072
	ds_read_b128 v[160:163], v172
	ds_read_b128 v[164:167], v172 offset:1024
	ds_read_b128 v[168:171], v172 offset:2048
	ds_read_b128 v[172:175], v172 offset:3072
	s_add_u32 s22, s52, 0x40000
	s_addc_u32 s23, s53, 0
	s_mov_b32 m0, s12
	v_lshl_add_u64 v[236:237], s[22:23], 0, v[134:135]
	ds_read_b128 v[190:193], v143 offset:32768
	ds_read_b128 v[194:197], v143 offset:33792
	ds_read_b128 v[198:201], v143 offset:34816
	ds_read_b128 v[212:215], v143 offset:35840
	ds_read_b128 v[216:219], v143 offset:36864
	ds_read_b128 v[220:223], v143 offset:37888
	ds_read_b128 v[224:227], v143 offset:38912
	ds_read_b128 v[228:231], v143 offset:39936
	global_load_lds_dwordx4 v[236:237], off
	v_lshl_add_u64 v[236:237], s[22:23], 0, v[132:133]
	s_mov_b32 m0, s13
	s_nop 0
	global_load_lds_dwordx4 v[236:237], off
	s_waitcnt vmcnt(8)
	s_waitcnt lgkmcnt(0)
	s_barrier
	s_waitcnt lgkmcnt(0)
	v_mfma_f32_16x16x32_bf16 v[126:129], v[144:147], v[190:193], v[126:129]
	v_mfma_f32_16x16x32_bf16 v[122:125], v[152:155], v[190:193], v[122:125]
	v_mfma_f32_16x16x32_bf16 v[118:121], v[144:147], v[198:201], v[118:121]
	v_mfma_f32_16x16x32_bf16 v[110:113], v[152:155], v[198:201], v[110:113]
	v_mfma_f32_16x16x32_bf16 v[102:105], v[144:147], v[216:219], v[102:105]
	v_mfma_f32_16x16x32_bf16 v[94:97], v[152:155], v[216:219], v[94:97]
	v_mfma_f32_16x16x32_bf16 v[82:85], v[144:147], v[224:227], v[82:85]
	v_mfma_f32_16x16x32_bf16 v[74:77], v[152:155], v[224:227], v[74:77]
	v_mfma_f32_16x16x32_bf16 v[126:129], v[148:151], v[194:197], v[126:129]
	v_mfma_f32_16x16x32_bf16 v[122:125], v[156:159], v[194:197], v[122:125]
	v_mfma_f32_16x16x32_bf16 v[118:121], v[148:151], v[212:215], v[118:121]
	v_mfma_f32_16x16x32_bf16 v[110:113], v[156:159], v[212:215], v[110:113]
	v_mfma_f32_16x16x32_bf16 v[102:105], v[148:151], v[220:223], v[102:105]
	v_mfma_f32_16x16x32_bf16 v[94:97], v[156:159], v[220:223], v[94:97]
	v_mfma_f32_16x16x32_bf16 v[82:85], v[148:151], v[228:231], v[82:85]
	v_mfma_f32_16x16x32_bf16 v[74:77], v[156:159], v[228:231], v[74:77]
	v_mfma_f32_16x16x32_bf16 v[114:117], v[160:163], v[190:193], v[114:117]
	v_mfma_f32_16x16x32_bf16 v[106:109], v[168:171], v[190:193], v[106:109]
	v_mfma_f32_16x16x32_bf16 v[98:101], v[160:163], v[198:201], v[98:101]
	v_mfma_f32_16x16x32_bf16 v[90:93], v[168:171], v[198:201], v[90:93]
	v_mfma_f32_16x16x32_bf16 v[86:89], v[160:163], v[216:219], v[86:89]
	v_mfma_f32_16x16x32_bf16 v[78:81], v[168:171], v[216:219], v[78:81]
	v_mfma_f32_16x16x32_bf16 v[70:73], v[160:163], v[224:227], v[70:73]
	v_mfma_f32_16x16x32_bf16 v[66:69], v[168:171], v[224:227], v[66:69]
	v_mfma_f32_16x16x32_bf16 v[114:117], v[164:167], v[194:197], v[114:117]
	v_mfma_f32_16x16x32_bf16 v[106:109], v[172:175], v[194:197], v[106:109]
	v_mfma_f32_16x16x32_bf16 v[98:101], v[164:167], v[212:215], v[98:101]
	v_mfma_f32_16x16x32_bf16 v[90:93], v[172:175], v[212:215], v[90:93]
	v_mfma_f32_16x16x32_bf16 v[86:89], v[164:167], v[220:223], v[86:89]
	v_mfma_f32_16x16x32_bf16 v[78:81], v[172:175], v[220:223], v[78:81]
	v_mfma_f32_16x16x32_bf16 v[70:73], v[164:167], v[228:231], v[70:73]
	v_mfma_f32_16x16x32_bf16 v[66:69], v[172:175], v[228:231], v[66:69]
	s_barrier
; #define PG8_STAGE(bufoff, gbase, voff) do { _Pragma("unroll") for (int _i = 0; _i < 2; ++_i) \
;         __builtin_amdgcn_global_load_lds((const unsigned*)((const char*)(gbase) + (voff)[_i]), (PG8_LAS unsigned*)(lds + (bufoff) + ldsw + _i * 8192), 16, 0, 0); } while (0)
; #define PG8_LDA(dst, b, h) do { _Pragma("unroll") for (int m = 0; m < 4; ++m) _Pragma("unroll") for (int k = 0; k < 2; ++k) dst[m][k] = *(const PG8_LAS bf16x8*)(lds + PG8_SA(b, h) + aoff + m * 2048 + k * 1024); } while (0)
; #define PG8_MMA(ai, bj, At, Bt) do { __builtin_amdgcn_s_setprio(1); _Pragma("unroll") for (int m = 0; m < 4; ++m) _Pragma("unroll") for (int n = 0; n < 2; ++n) _Pragma("unroll") for (int k = 0; k < 2; ++k) \
;         acc[ai][bj][m][n] = __builtin_amdgcn_mfma_f32_16x16x32_bf16(Bt[n][k], At[m][k], acc[ai][bj][m][n], 0, 0, 0); __builtin_amdgcn_s_setprio(0); } while (0)
; #define PG8_WAIT_V(n) asm volatile("s_waitcnt vmcnt(" #n ")" ::: "memory")
; #define PG8_WAIT_L(n) asm volatile("s_waitcnt lgkmcnt(" #n ")" ::: "memory")
; #define PG8_BAR __builtin_amdgcn_s_barrier()
; #define PG8_SCHED __builtin_amdgcn_sched_barrier(0)
; template <class Epi, class Sched, bool ALIGN_EPI = false, bool SP2 = false>
; __device__ __forceinline__ void gemm_phase(PG8_LAS unsigned char* lds, const Gemm g, const Sched& S, const Epi& E, const int wid_in) {
;     ...
;         for (int t = 0; t < nt; t += 2) {
;             const bool last = (t == nt - 2);
;             const char* a1 = cA + (size_t)(t + 1) * kstep;
;             const char* a2 = last ? nA : cA + (size_t)(t + 2) * kstep; const char* b2 = last ? nB : cB + (size_t)(t + 2) * kstep;
;             const char* a3 = a2 + kstep; const char* b3 = b2 + kstep;
;     ...
;             PG8_LDA(At, 1, 1); PG8_STAGE(PG8_SB(1, 0), b3, voffB); PG8_STAGE(PG8_SB(1, 1), b3 + hstep, voffB); PG8_STAGE(PG8_SA(1, 0), a3, voffA);
;             PG8_WAIT_V(8); PG8_WAIT_L(0); PG8_BAR; PG8_MMA(1, 0, At, B0); PG8_MMA(1, 1, At, B1); PG8_BAR; PG8_SCHED;
	s_add_i32 s2, s2, s3
	v_lshl_add_u64 v[140:141], v[140:141], 0, s[64:65]
	s_mov_b32 m0, s2
	ds_read_b128 v[190:193], v143 offset:49152
	ds_read_b128 v[194:197], v143 offset:50176
	ds_read_b128 v[198:201], v143 offset:51200
	ds_read_b128 v[212:215], v143 offset:52224
	ds_read_b128 v[216:219], v143 offset:53248
	ds_read_b128 v[220:223], v143 offset:54272
	ds_read_b128 v[224:227], v143 offset:55296
	ds_read_b128 v[228:231], v143 offset:56320
	global_load_lds_dwordx4 v[140:141], off
	s_add_i32 m0, s2, 0x2000
	s_add_u32 s22, s50, 0x40080
	v_lshl_add_u64 v[140:141], v[176:177], 0, s[64:65]
	s_addc_u32 s23, s51, 0
	s_add_i32 s2, s8, s3
	global_load_lds_dwordx4 v[140:141], off
	v_lshl_add_u64 v[140:141], s[22:23], 0, v[0:1]
	s_mov_b32 m0, s2
	s_nop 0
	global_load_lds_dwordx4 v[140:141], off
	v_lshl_add_u64 v[140:141], s[22:23], 0, v[130:131]
	s_add_i32 m0, s2, 0x2000
	s_nop 0
	global_load_lds_dwordx4 v[140:141], off
	v_lshl_add_u64 v[140:141], v[232:233], 0, s[64:65]
	s_mov_b32 m0, s36
	s_nop 0
	global_load_lds_dwordx4 v[140:141], off
	v_lshl_add_u64 v[140:141], v[234:235], 0, s[64:65]
	s_mov_b32 m0, s37
	s_nop 0
	global_load_lds_dwordx4 v[140:141], off
	s_add_i32 s60, s60, 2
	s_add_u32 s48, s48, 0x100
	s_addc_u32 s49, s49, 0
	s_add_u32 s58, s58, 0x100
	s_addc_u32 s59, s59, 0
	s_add_u32 s2, s48, 0xfffc0080
	s_addc_u32 s8, s49, -1
	s_add_i32 s9, 0, 0x10000
	s_cmp_eq_u32 s60, 12
	s_cselect_b32 s53, s43, s8
	s_cselect_b32 s52, s57, s2
	s_cselect_b32 s51, s16, s59
	s_cselect_b32 s50, s39, s58
	s_add_i32 s2, 0, 0x14000
	s_cmp_gt_u32 s60, 13
	s_waitcnt vmcnt(8)
	s_waitcnt lgkmcnt(0)
	s_barrier
	s_waitcnt lgkmcnt(0)
	v_mfma_f32_16x16x32_bf16 v[62:65], v[144:147], v[190:193], v[62:65]
	v_mfma_f32_16x16x32_bf16 v[58:61], v[152:155], v[190:193], v[58:61]
	v_mfma_f32_16x16x32_bf16 v[54:57], v[144:147], v[198:201], v[54:57]
	v_mfma_f32_16x16x32_bf16 v[46:49], v[152:155], v[198:201], v[46:49]
	v_mfma_f32_16x16x32_bf16 v[38:41], v[144:147], v[216:219], v[38:41]
	v_mfma_f32_16x16x32_bf16 v[30:33], v[152:155], v[216:219], v[30:33]
	v_mfma_f32_16x16x32_bf16 v[22:25], v[144:147], v[224:227], v[22:25]
	v_mfma_f32_16x16x32_bf16 v[14:17], v[152:155], v[224:227], v[14:17]
	v_mfma_f32_16x16x32_bf16 v[62:65], v[148:151], v[194:197], v[62:65]
	v_mfma_f32_16x16x32_bf16 v[58:61], v[156:159], v[194:197], v[58:61]
	v_mfma_f32_16x16x32_bf16 v[54:57], v[148:151], v[212:215], v[54:57]
	v_mfma_f32_16x16x32_bf16 v[46:49], v[156:159], v[212:215], v[46:49]
	v_mfma_f32_16x16x32_bf16 v[38:41], v[148:151], v[220:223], v[38:41]
	v_mfma_f32_16x16x32_bf16 v[30:33], v[156:159], v[220:223], v[30:33]
	v_mfma_f32_16x16x32_bf16 v[22:25], v[148:151], v[228:231], v[22:25]
	v_mfma_f32_16x16x32_bf16 v[14:17], v[156:159], v[228:231], v[14:17]
	v_mfma_f32_16x16x32_bf16 v[50:53], v[160:163], v[190:193], v[50:53]
	v_mfma_f32_16x16x32_bf16 v[42:45], v[168:171], v[190:193], v[42:45]
	v_mfma_f32_16x16x32_bf16 v[34:37], v[160:163], v[198:201], v[34:37]
	v_mfma_f32_16x16x32_bf16 v[26:29], v[168:171], v[198:201], v[26:29]
	v_mfma_f32_16x16x32_bf16 v[18:21], v[160:163], v[216:219], v[18:21]
	v_mfma_f32_16x16x32_bf16 v[10:13], v[168:171], v[216:219], v[10:13]
	v_mfma_f32_16x16x32_bf16 v[6:9], v[160:163], v[224:227], v[6:9]
	v_mfma_f32_16x16x32_bf16 v[2:5], v[168:171], v[224:227], v[2:5]
	v_mfma_f32_16x16x32_bf16 v[50:53], v[164:167], v[194:197], v[50:53]
	v_mfma_f32_16x16x32_bf16 v[42:45], v[172:175], v[194:197], v[42:45]
	v_mfma_f32_16x16x32_bf16 v[34:37], v[164:167], v[212:215], v[34:37]
	v_mfma_f32_16x16x32_bf16 v[26:29], v[172:175], v[212:215], v[26:29]
	v_mfma_f32_16x16x32_bf16 v[18:21], v[164:167], v[220:223], v[18:21]
	v_mfma_f32_16x16x32_bf16 v[10:13], v[172:175], v[220:223], v[10:13]
	v_mfma_f32_16x16x32_bf16 v[6:9], v[164:167], v[228:231], v[6:9]
	v_mfma_f32_16x16x32_bf16 v[2:5], v[172:175], v[228:231], v[2:5]
	s_barrier
	s_cbranch_scc0 .LBB0_537
	s_setprio 0
	v_readlane_b32 s8, v243, 63
	v_readlane_b32 s9, v242, 0
	s_and_b64 vcc, exec, s[8:9]
	s_cbranch_vccz .LBB0_540
	s_barrier

; #define PG8_STAGE(bufoff, gbase, voff) do { _Pragma("unroll") for (int _i = 0; _i < 2; ++_i) \
;         __builtin_amdgcn_global_load_lds((const unsigned*)((const char*)(gbase) + (voff)[_i]), (PG8_LAS unsigned*)(lds + (bufoff) + ldsw + _i * 8192), 16, 0, 0); } while (0)
; #define PG8_LDA(dst, b, h) do { _Pragma("unroll") for (int m = 0; m < 4; ++m) _Pragma("unroll") for (int k = 0; k < 2; ++k) dst[m][k] = *(const PG8_LAS bf16x8*)(lds + PG8_SA(b, h) + aoff + m * 2048 + k * 1024); } while (0)
; #define PG8_LDB(dst, b, h) do { _Pragma("unroll") for (int n = 0; n < 2; ++n) _Pragma("unroll") for (int k = 0; k < 2; ++k) dst[n][k] = *(const PG8_LAS bf16x8*)(lds + PG8_SB(b, h) + boff + n * 2048 + k * 1024); } while (0)
; #define PG8_MMA(ai, bj, At, Bt) do { __builtin_amdgcn_s_setprio(1); _Pragma("unroll") for (int m = 0; m < 4; ++m) _Pragma("unroll") for (int n = 0; n < 2; ++n) _Pragma("unroll") for (int k = 0; k < 2; ++k) \
;         acc[ai][bj][m][n] = __builtin_amdgcn_mfma_f32_16x16x32_bf16(Bt[n][k], At[m][k], acc[ai][bj][m][n], 0, 0, 0); __builtin_amdgcn_s_setprio(0); } while (0)
; #define PG8_WAIT_V(n) asm volatile("s_waitcnt vmcnt(" #n ")" ::: "memory")
; #define PG8_BAR __builtin_amdgcn_s_barrier()
; template <class Epi, class Sched, bool ALIGN_EPI = false, bool SP2 = false>
; __device__ __forceinline__ void gemm_phase(PG8_LAS unsigned char* lds, const Gemm g, const Sched& S, const Epi& E, const int wid_in) {
;     ...
;         for (int t = 0; t < nt; t += 2) {
;             const bool last = (t == nt - 2);
;             const char* a1 = cA + (size_t)(t + 1) * kstep;
;             const char* a2 = last ? nA : cA + (size_t)(t + 2) * kstep; const char* b2 = last ? nB : cB + (size_t)(t + 2) * kstep;
;             const char* a3 = a2 + kstep; const char* b3 = b2 + kstep;
;             if (last && has_next) S.a_ready(nxt);
;             if constexpr (SP2) {
;             PG8_LDB(B0, 0, 0); PG8_LDB(B1, 0, 1); PG8_SCHED; PG8_LDA(At, 0, 0); PG8_STAGE(PG8_SA(1, 1), a1 + hstep, voffA);
;             PG8_WAIT_V(8); PG8_WAIT_L(0); PG8_BAR; PG8_MMA(0, 0, At, B0); PG8_MMA(0, 1, At, B1); PG8_BAR; PG8_SCHED;
;             PG8_LDA(At, 0, 1); PG8_STAGE(PG8_SB(0, 0), b2, voffB); PG8_STAGE(PG8_SB(0, 1), b2 + hstep, voffB); PG8_STAGE(PG8_SA(0, 0), a2, voffA);
;             PG8_WAIT_V(8); PG8_WAIT_L(0); PG8_BAR; PG8_MMA(1, 0, At, B0); PG8_MMA(1, 1, At, B1); PG8_BAR; PG8_SCHED;
.Lprio_done_705:
	s_add_u32 s2, s42, 0xfffc0080
	s_addc_u32 s8, s43, -1
	s_add_i32 s9, 0, 0x10000
	s_cmp_eq_u32 vcc_lo, 12
	s_cselect_b32 s47, s48, s8
	s_cselect_b32 s46, s49, s2
	s_cselect_b32 s45, s16, s62
	s_cselect_b32 s44, s59, s61
	s_add_i32 s2, 0, 0x14000
	v_add_u32_e32 v142, s9, v211
	v_add_u32_e32 v158, s2, v211
	ds_read_b128 v[130:133], v142
	ds_read_b128 v[134:137], v142 offset:1024
	ds_read_b128 v[138:141], v142 offset:2048
	ds_read_b128 v[142:145], v142 offset:3072
	ds_read_b128 v[146:149], v158
	ds_read_b128 v[150:153], v158 offset:1024
	ds_read_b128 v[154:157], v158 offset:2048
	ds_read_b128 v[158:161], v158 offset:3072
	v_lshl_add_u64 v[200:201], s[42:43], 0, v[196:197]
	s_add_i32 m0, s12, 0xc000
	ds_read_b128 v[162:165], v212
	ds_read_b128 v[166:169], v212 offset:1024
	ds_read_b128 v[170:173], v212 offset:2048
	ds_read_b128 v[174:177], v212 offset:3072
	ds_read_b128 v[214:217], v212 offset:4096
	ds_read_b128 v[218:221], v212 offset:5120
	ds_read_b128 v[222:225], v212 offset:6144
	ds_read_b128 v[226:229], v212 offset:7168
	global_load_lds_dwordx4 v[200:201], off
	v_lshl_add_u64 v[200:201], s[42:43], 0, v[198:199]
	s_add_i32 m0, s12, 0xe000
	s_nop 0
	global_load_lds_dwordx4 v[200:201], off
	s_waitcnt vmcnt(8)
	s_waitcnt lgkmcnt(0)
	s_barrier
	s_waitcnt lgkmcnt(0)
	v_mfma_f32_16x16x32_bf16 v[126:129], v[130:133], v[162:165], 0
	v_mfma_f32_16x16x32_bf16 v[94:97], v[138:141], v[162:165], 0
	v_mfma_f32_16x16x32_bf16 v[118:121], v[130:133], v[170:173], 0
	v_mfma_f32_16x16x32_bf16 v[86:89], v[138:141], v[170:173], 0
	v_mfma_f32_16x16x32_bf16 v[110:113], v[130:133], v[214:217], 0
	v_mfma_f32_16x16x32_bf16 v[78:81], v[138:141], v[214:217], 0
	v_mfma_f32_16x16x32_bf16 v[102:105], v[130:133], v[222:225], 0
	v_mfma_f32_16x16x32_bf16 v[70:73], v[138:141], v[222:225], 0
	v_mfma_f32_16x16x32_bf16 v[126:129], v[134:137], v[166:169], v[126:129]
	v_mfma_f32_16x16x32_bf16 v[94:97], v[142:145], v[166:169], v[94:97]
	v_mfma_f32_16x16x32_bf16 v[118:121], v[134:137], v[174:177], v[118:121]
	v_mfma_f32_16x16x32_bf16 v[86:89], v[142:145], v[174:177], v[86:89]
	v_mfma_f32_16x16x32_bf16 v[110:113], v[134:137], v[218:221], v[110:113]
	v_mfma_f32_16x16x32_bf16 v[78:81], v[142:145], v[218:221], v[78:81]
	v_mfma_f32_16x16x32_bf16 v[102:105], v[134:137], v[226:229], v[102:105]
	v_mfma_f32_16x16x32_bf16 v[70:73], v[142:145], v[226:229], v[70:73]
	v_mfma_f32_16x16x32_bf16 v[122:125], v[146:149], v[162:165], 0
	v_mfma_f32_16x16x32_bf16 v[90:93], v[154:157], v[162:165], 0
	v_mfma_f32_16x16x32_bf16 v[114:117], v[146:149], v[170:173], 0
	v_mfma_f32_16x16x32_bf16 v[82:85], v[154:157], v[170:173], 0
	v_mfma_f32_16x16x32_bf16 v[106:109], v[146:149], v[214:217], 0
	v_mfma_f32_16x16x32_bf16 v[74:77], v[154:157], v[214:217], 0
	v_mfma_f32_16x16x32_bf16 v[98:101], v[146:149], v[222:225], 0
	v_mfma_f32_16x16x32_bf16 v[66:69], v[154:157], v[222:225], 0
	v_mfma_f32_16x16x32_bf16 v[122:125], v[150:153], v[166:169], v[122:125]
	v_mfma_f32_16x16x32_bf16 v[90:93], v[158:161], v[166:169], v[90:93]
	v_mfma_f32_16x16x32_bf16 v[114:117], v[150:153], v[174:177], v[114:117]
	v_mfma_f32_16x16x32_bf16 v[82:85], v[158:161], v[174:177], v[82:85]
	v_mfma_f32_16x16x32_bf16 v[106:109], v[150:153], v[218:221], v[106:109]
	v_mfma_f32_16x16x32_bf16 v[74:77], v[158:161], v[218:221], v[74:77]
	v_mfma_f32_16x16x32_bf16 v[98:101], v[150:153], v[226:229], v[98:101]
	v_mfma_f32_16x16x32_bf16 v[66:69], v[158:161], v[226:229], v[66:69]
	s_barrier
	s_add_i32 s8, s9, s3
	v_lshl_add_u64 v[200:201], s[44:45], 0, v[0:1]
	s_mov_b32 m0, s8
	ds_read_b128 v[162:165], v212 offset:16384
	ds_read_b128 v[166:169], v212 offset:17408
	ds_read_b128 v[170:173], v212 offset:18432
	ds_read_b128 v[174:177], v212 offset:19456
	ds_read_b128 v[214:217], v212 offset:20480
	ds_read_b128 v[218:221], v212 offset:21504
	ds_read_b128 v[222:225], v212 offset:22528
	ds_read_b128 v[226:229], v212 offset:23552
	global_load_lds_dwordx4 v[200:201], off
	s_add_i32 m0, s8, 0x2000
	s_add_u32 s22, s44, 0x40000
	v_lshl_add_u64 v[230:231], s[44:45], 0, v[194:195]
	s_addc_u32 s23, s45, 0
	s_add_i32 s2, s2, s3
	global_load_lds_dwordx4 v[230:231], off
	v_lshl_add_u64 v[232:233], s[22:23], 0, v[0:1]
	s_mov_b32 m0, s2
	v_lshl_add_u64 v[234:235], s[46:47], 0, v[192:193]
	global_load_lds_dwordx4 v[232:233], off
	v_lshl_add_u64 v[232:233], s[22:23], 0, v[194:195]
	s_add_i32 m0, s2, 0x2000
	s_nop 0
	global_load_lds_dwordx4 v[232:233], off
	v_lshl_add_u64 v[232:233], s[46:47], 0, v[190:191]
	s_mov_b32 m0, s12
	s_nop 0
	global_load_lds_dwordx4 v[232:233], off
	s_mov_b32 m0, s13
	s_nop 0
	global_load_lds_dwordx4 v[234:235], off
	s_waitcnt vmcnt(8)
	s_waitcnt lgkmcnt(0)
	s_barrier
; #define PG8_STAGE(bufoff, gbase, voff) do { _Pragma("unroll") for (int _i = 0; _i < 2; ++_i) \
;         __builtin_amdgcn_global_load_lds((const unsigned*)((const char*)(gbase) + (voff)[_i]), (PG8_LAS unsigned*)(lds + (bufoff) + ldsw + _i * 8192), 16, 0, 0); } while (0)
; #define PG8_LDA(dst, b, h) do { _Pragma("unroll") for (int m = 0; m < 4; ++m) _Pragma("unroll") for (int k = 0; k < 2; ++k) dst[m][k] = *(const PG8_LAS bf16x8*)(lds + PG8_SA(b, h) + aoff + m * 2048 + k * 1024); } while (0)
; #define PG8_LDB(dst, b, h) do { _Pragma("unroll") for (int n = 0; n < 2; ++n) _Pragma("unroll") for (int k = 0; k < 2; ++k) dst[n][k] = *(const PG8_LAS bf16x8*)(lds + PG8_SB(b, h) + boff + n * 2048 + k * 1024); } while (0)
; #define PG8_MMA(ai, bj, At, Bt) do { __builtin_amdgcn_s_setprio(1); _Pragma("unroll") for (int m = 0; m < 4; ++m) _Pragma("unroll") for (int n = 0; n < 2; ++n) _Pragma("unroll") for (int k = 0; k < 2; ++k) \
;         acc[ai][bj][m][n] = __builtin_amdgcn_mfma_f32_16x16x32_bf16(Bt[n][k], At[m][k], acc[ai][bj][m][n], 0, 0, 0); __builtin_amdgcn_s_setprio(0); } while (0)
; #define PG8_WAIT_V(n) asm volatile("s_waitcnt vmcnt(" #n ")" ::: "memory")
; #define PG8_WAIT_L(n) asm volatile("s_waitcnt lgkmcnt(" #n ")" ::: "memory")
; #define PG8_BAR __builtin_amdgcn_s_barrier()
; #define PG8_SCHED __builtin_amdgcn_sched_barrier(0)
; template <class Epi, class Sched, bool ALIGN_EPI = false, bool SP2 = false>
; __device__ __forceinline__ void gemm_phase(PG8_LAS unsigned char* lds, const Gemm g, const Sched& S, const Epi& E, const int wid_in) {
;     ...
;             PG8_LDA(At, 0, 1); PG8_STAGE(PG8_SB(0, 0), b2, voffB); PG8_STAGE(PG8_SB(0, 1), b2 + hstep, voffB); PG8_STAGE(PG8_SA(0, 0), a2, voffA);
;             PG8_WAIT_V(8); PG8_WAIT_L(0); PG8_BAR; PG8_MMA(1, 0, At, B0); PG8_MMA(1, 1, At, B1); PG8_BAR; PG8_SCHED;
;             PG8_LDB(B0, 1, 0); PG8_LDB(B1, 1, 1); PG8_SCHED; PG8_LDA(At, 1, 0); PG8_STAGE(PG8_SA(0, 1), a2 + hstep, voffA);
;             PG8_WAIT_V(8); PG8_WAIT_L(0); PG8_BAR; PG8_MMA(0, 0, At, B0); PG8_MMA(0, 1, At, B1); PG8_BAR; PG8_SCHED;
	s_waitcnt lgkmcnt(0)
	v_mfma_f32_16x16x32_bf16 v[62:65], v[130:133], v[162:165], 0
	v_mfma_f32_16x16x32_bf16 v[30:33], v[138:141], v[162:165], 0
	v_mfma_f32_16x16x32_bf16 v[54:57], v[130:133], v[170:173], 0
	v_mfma_f32_16x16x32_bf16 v[22:25], v[138:141], v[170:173], 0
	v_mfma_f32_16x16x32_bf16 v[46:49], v[130:133], v[214:217], 0
	v_mfma_f32_16x16x32_bf16 v[14:17], v[138:141], v[214:217], 0
	v_mfma_f32_16x16x32_bf16 v[38:41], v[130:133], v[222:225], 0
	v_mfma_f32_16x16x32_bf16 v[6:9], v[138:141], v[222:225], 0
	v_mfma_f32_16x16x32_bf16 v[62:65], v[134:137], v[166:169], v[62:65]
	v_mfma_f32_16x16x32_bf16 v[30:33], v[142:145], v[166:169], v[30:33]
	v_mfma_f32_16x16x32_bf16 v[54:57], v[134:137], v[174:177], v[54:57]
	v_mfma_f32_16x16x32_bf16 v[22:25], v[142:145], v[174:177], v[22:25]
	v_mfma_f32_16x16x32_bf16 v[46:49], v[134:137], v[218:221], v[46:49]
	v_mfma_f32_16x16x32_bf16 v[14:17], v[142:145], v[218:221], v[14:17]
	v_mfma_f32_16x16x32_bf16 v[38:41], v[134:137], v[226:229], v[38:41]
	v_mfma_f32_16x16x32_bf16 v[6:9], v[142:145], v[226:229], v[6:9]
	v_mfma_f32_16x16x32_bf16 v[58:61], v[146:149], v[162:165], 0
	v_mfma_f32_16x16x32_bf16 v[26:29], v[154:157], v[162:165], 0
	v_mfma_f32_16x16x32_bf16 v[50:53], v[146:149], v[170:173], 0
	v_mfma_f32_16x16x32_bf16 v[18:21], v[154:157], v[170:173], 0
	v_mfma_f32_16x16x32_bf16 v[42:45], v[146:149], v[214:217], 0
	v_mfma_f32_16x16x32_bf16 v[10:13], v[154:157], v[214:217], 0
	v_mfma_f32_16x16x32_bf16 v[34:37], v[146:149], v[222:225], 0
	v_mfma_f32_16x16x32_bf16 v[2:5], v[154:157], v[222:225], 0
	v_mfma_f32_16x16x32_bf16 v[58:61], v[150:153], v[166:169], v[58:61]
	v_mfma_f32_16x16x32_bf16 v[26:29], v[158:161], v[166:169], v[26:29]
	v_mfma_f32_16x16x32_bf16 v[50:53], v[150:153], v[174:177], v[50:53]
	v_mfma_f32_16x16x32_bf16 v[18:21], v[158:161], v[174:177], v[18:21]
	v_mfma_f32_16x16x32_bf16 v[42:45], v[150:153], v[218:221], v[42:45]
	v_mfma_f32_16x16x32_bf16 v[10:13], v[158:161], v[218:221], v[10:13]
	v_mfma_f32_16x16x32_bf16 v[34:37], v[150:153], v[226:229], v[34:37]
	v_mfma_f32_16x16x32_bf16 v[2:5], v[158:161], v[226:229], v[2:5]
	s_barrier
	s_add_i32 s2, 0, 0x18000
	s_add_i32 s8, 0, 0x1c000
	v_add_u32_e32 v142, s2, v211
	v_add_u32_e32 v158, s8, v211
	ds_read_b128 v[130:133], v142
	ds_read_b128 v[134:137], v142 offset:1024
	ds_read_b128 v[138:141], v142 offset:2048
	ds_read_b128 v[142:145], v142 offset:3072
	ds_read_b128 v[146:149], v158
	ds_read_b128 v[150:153], v158 offset:1024
	ds_read_b128 v[154:157], v158 offset:2048
	ds_read_b128 v[158:161], v158 offset:3072
	s_add_u32 s22, s46, 0x40000
	s_addc_u32 s23, s47, 0
	s_mov_b32 m0, s36
	v_lshl_add_u64 v[236:237], s[22:23], 0, v[190:191]
	ds_read_b128 v[162:165], v212 offset:32768
	ds_read_b128 v[166:169], v212 offset:33792
	ds_read_b128 v[170:173], v212 offset:34816
	ds_read_b128 v[174:177], v212 offset:35840
	ds_read_b128 v[214:217], v212 offset:36864
	ds_read_b128 v[218:221], v212 offset:37888
	ds_read_b128 v[222:225], v212 offset:38912
	ds_read_b128 v[226:229], v212 offset:39936
	global_load_lds_dwordx4 v[236:237], off
	v_lshl_add_u64 v[236:237], s[22:23], 0, v[192:193]
	s_mov_b32 m0, s37
	s_nop 0
	global_load_lds_dwordx4 v[236:237], off
	s_waitcnt vmcnt(8)
	s_waitcnt lgkmcnt(0)
	s_barrier
	s_waitcnt lgkmcnt(0)
	v_mfma_f32_16x16x32_bf16 v[126:129], v[130:133], v[162:165], v[126:129]
	v_mfma_f32_16x16x32_bf16 v[94:97], v[138:141], v[162:165], v[94:97]
	v_mfma_f32_16x16x32_bf16 v[118:121], v[130:133], v[170:173], v[118:121]
	v_mfma_f32_16x16x32_bf16 v[86:89], v[138:141], v[170:173], v[86:89]
	v_mfma_f32_16x16x32_bf16 v[110:113], v[130:133], v[214:217], v[110:113]
	v_mfma_f32_16x16x32_bf16 v[78:81], v[138:141], v[214:217], v[78:81]
	v_mfma_f32_16x16x32_bf16 v[102:105], v[130:133], v[222:225], v[102:105]
	v_mfma_f32_16x16x32_bf16 v[70:73], v[138:141], v[222:225], v[70:73]
	v_mfma_f32_16x16x32_bf16 v[126:129], v[134:137], v[166:169], v[126:129]
	v_mfma_f32_16x16x32_bf16 v[94:97], v[142:145], v[166:169], v[94:97]
	v_mfma_f32_16x16x32_bf16 v[118:121], v[134:137], v[174:177], v[118:121]
	v_mfma_f32_16x16x32_bf16 v[86:89], v[142:145], v[174:177], v[86:89]
	v_mfma_f32_16x16x32_bf16 v[110:113], v[134:137], v[218:221], v[110:113]
	v_mfma_f32_16x16x32_bf16 v[78:81], v[142:145], v[218:221], v[78:81]
	v_mfma_f32_16x16x32_bf16 v[102:105], v[134:137], v[226:229], v[102:105]
	v_mfma_f32_16x16x32_bf16 v[70:73], v[142:145], v[226:229], v[70:73]
	v_mfma_f32_16x16x32_bf16 v[122:125], v[146:149], v[162:165], v[122:125]
	v_mfma_f32_16x16x32_bf16 v[90:93], v[154:157], v[162:165], v[90:93]
	v_mfma_f32_16x16x32_bf16 v[114:117], v[146:149], v[170:173], v[114:117]
	v_mfma_f32_16x16x32_bf16 v[82:85], v[154:157], v[170:173], v[82:85]
	v_mfma_f32_16x16x32_bf16 v[106:109], v[146:149], v[214:217], v[106:109]
	v_mfma_f32_16x16x32_bf16 v[74:77], v[154:157], v[214:217], v[74:77]
	v_mfma_f32_16x16x32_bf16 v[98:101], v[146:149], v[222:225], v[98:101]
	v_mfma_f32_16x16x32_bf16 v[66:69], v[154:157], v[222:225], v[66:69]
	v_mfma_f32_16x16x32_bf16 v[122:125], v[150:153], v[166:169], v[122:125]
	v_mfma_f32_16x16x32_bf16 v[90:93], v[158:161], v[166:169], v[90:93]
	v_mfma_f32_16x16x32_bf16 v[114:117], v[150:153], v[174:177], v[114:117]
	v_mfma_f32_16x16x32_bf16 v[82:85], v[158:161], v[174:177], v[82:85]
	v_mfma_f32_16x16x32_bf16 v[106:109], v[150:153], v[218:221], v[106:109]
	v_mfma_f32_16x16x32_bf16 v[74:77], v[158:161], v[218:221], v[74:77]
	v_mfma_f32_16x16x32_bf16 v[98:101], v[150:153], v[226:229], v[98:101]
	v_mfma_f32_16x16x32_bf16 v[66:69], v[158:161], v[226:229], v[66:69]
	s_barrier
; #define PG8_STAGE(bufoff, gbase, voff) do { _Pragma("unroll") for (int _i = 0; _i < 2; ++_i) \
;         __builtin_amdgcn_global_load_lds((const unsigned*)((const char*)(gbase) + (voff)[_i]), (PG8_LAS unsigned*)(lds + (bufoff) + ldsw + _i * 8192), 16, 0, 0); } while (0)
; #define PG8_LDA(dst, b, h) do { _Pragma("unroll") for (int m = 0; m < 4; ++m) _Pragma("unroll") for (int k = 0; k < 2; ++k) dst[m][k] = *(const PG8_LAS bf16x8*)(lds + PG8_SA(b, h) + aoff + m * 2048 + k * 1024); } while (0)
; #define PG8_WAIT_V(n) asm volatile("s_waitcnt vmcnt(" #n ")" ::: "memory")
; #define PG8_WAIT_L(n) asm volatile("s_waitcnt lgkmcnt(" #n ")" ::: "memory")
; #define PG8_BAR __builtin_amdgcn_s_barrier()
; template <class Epi, class Sched, bool ALIGN_EPI = false, bool SP2 = false>
; __device__ __forceinline__ void gemm_phase(PG8_LAS unsigned char* lds, const Gemm g, const Sched& S, const Epi& E, const int wid_in) {
;     ...
;         for (int t = 0; t < nt; t += 2) {
;             const bool last = (t == nt - 2);
;             const char* a1 = cA + (size_t)(t + 1) * kstep;
;             const char* a2 = last ? nA : cA + (size_t)(t + 2) * kstep; const char* b2 = last ? nB : cB + (size_t)(t + 2) * kstep;
;             const char* a3 = a2 + kstep; const char* b3 = b2 + kstep;
;             if (last && has_next) S.a_ready(nxt);
;             if constexpr (SP2) {
;             PG8_LDB(B0, 0, 0); PG8_LDB(B1, 0, 1); PG8_SCHED; PG8_LDA(At, 0, 0); PG8_STAGE(PG8_SA(1, 1), a1 + hstep, voffA);
;             PG8_WAIT_V(8); PG8_WAIT_L(0); PG8_BAR; PG8_MMA(0, 0, At, B0); PG8_MMA(0, 1, At, B1); PG8_BAR; PG8_SCHED;
;             PG8_LDA(At, 0, 1); PG8_STAGE(PG8_SB(0, 0), b2, voffB); PG8_STAGE(PG8_SB(0, 1), b2 + hstep, voffB); PG8_STAGE(PG8_SA(0, 0), a2, voffA);
;             PG8_WAIT_V(8); PG8_WAIT_L(0); PG8_BAR; PG8_MMA(1, 0, At, B0); PG8_MMA(1, 1, At, B1); PG8_BAR; PG8_SCHED;
;             PG8_LDB(B0, 1, 0); PG8_LDB(B1, 1, 1); PG8_SCHED; PG8_LDA(At, 1, 0); PG8_STAGE(PG8_SA(0, 1), a2 + hstep, voffA);
;             PG8_WAIT_V(8); PG8_WAIT_L(0); PG8_BAR; PG8_MMA(0, 0, At, B0); PG8_MMA(0, 1, At, B1); PG8_BAR; PG8_SCHED;
;             PG8_LDA(At, 1, 1); PG8_STAGE(PG8_SB(1, 0), b3, voffB); PG8_STAGE(PG8_SB(1, 1), b3 + hstep, voffB); PG8_STAGE(PG8_SA(1, 0), a3, voffA);
;             PG8_WAIT_V(8); PG8_WAIT_L(0); PG8_BAR; PG8_MMA(1, 0, At, B0); PG8_MMA(1, 1, At, B1); PG8_BAR; PG8_SCHED;
	s_add_i32 s2, s2, s3
	v_lshl_add_u64 v[200:201], v[200:201], 0, s[64:65]
	s_mov_b32 m0, s2
	ds_read_b128 v[162:165], v212 offset:49152
	ds_read_b128 v[166:169], v212 offset:50176
	ds_read_b128 v[170:173], v212 offset:51200
	ds_read_b128 v[174:177], v212 offset:52224
	ds_read_b128 v[214:217], v212 offset:53248
	ds_read_b128 v[218:221], v212 offset:54272
	ds_read_b128 v[222:225], v212 offset:55296
	ds_read_b128 v[226:229], v212 offset:56320
	global_load_lds_dwordx4 v[200:201], off
	s_add_i32 m0, s2, 0x2000
	s_add_u32 s22, s44, 0x40080
	v_lshl_add_u64 v[200:201], v[230:231], 0, s[64:65]
	s_addc_u32 s23, s45, 0
	s_add_i32 s2, s8, s3
	global_load_lds_dwordx4 v[200:201], off
	v_lshl_add_u64 v[200:201], s[22:23], 0, v[0:1]
	s_mov_b32 m0, s2
	s_nop 0
	global_load_lds_dwordx4 v[200:201], off
	v_lshl_add_u64 v[200:201], s[22:23], 0, v[194:195]
	s_add_i32 m0, s2, 0x2000
	s_nop 0
	global_load_lds_dwordx4 v[200:201], off
	v_lshl_add_u64 v[200:201], v[232:233], 0, s[64:65]
	s_mov_b32 m0, s78
	s_nop 0
	global_load_lds_dwordx4 v[200:201], off
	v_lshl_add_u64 v[200:201], v[234:235], 0, s[64:65]
	s_mov_b32 m0, s79
	s_nop 0
	global_load_lds_dwordx4 v[200:201], off
	s_add_i32 vcc_lo, vcc_lo, 2
	s_add_u32 s42, s42, 0x100
	s_addc_u32 s43, s43, 0
	s_add_u32 s61, s61, 0x100
	s_addc_u32 s62, s62, 0
	s_add_u32 s2, s42, 0xfffc0080
	s_addc_u32 s8, s43, -1
	s_add_i32 s9, 0, 0x10000
	s_cmp_eq_u32 vcc_lo, 12
	s_cselect_b32 s47, s48, s8
	s_cselect_b32 s46, s49, s2
	s_cselect_b32 s45, s16, s62
	s_cselect_b32 s44, s59, s61
	s_add_i32 s2, 0, 0x14000
	s_cmp_gt_u32 vcc_lo, 13
	s_waitcnt vmcnt(8)
	s_waitcnt lgkmcnt(0)
	s_barrier
	s_waitcnt lgkmcnt(0)
	v_mfma_f32_16x16x32_bf16 v[62:65], v[130:133], v[162:165], v[62:65]
	v_mfma_f32_16x16x32_bf16 v[30:33], v[138:141], v[162:165], v[30:33]
	v_mfma_f32_16x16x32_bf16 v[54:57], v[130:133], v[170:173], v[54:57]
	v_mfma_f32_16x16x32_bf16 v[22:25], v[138:141], v[170:173], v[22:25]
	v_mfma_f32_16x16x32_bf16 v[46:49], v[130:133], v[214:217], v[46:49]
	v_mfma_f32_16x16x32_bf16 v[14:17], v[138:141], v[214:217], v[14:17]
	v_mfma_f32_16x16x32_bf16 v[38:41], v[130:133], v[222:225], v[38:41]
	v_mfma_f32_16x16x32_bf16 v[6:9], v[138:141], v[222:225], v[6:9]
	v_mfma_f32_16x16x32_bf16 v[62:65], v[134:137], v[166:169], v[62:65]
	v_mfma_f32_16x16x32_bf16 v[30:33], v[142:145], v[166:169], v[30:33]
	v_mfma_f32_16x16x32_bf16 v[54:57], v[134:137], v[174:177], v[54:57]
	v_mfma_f32_16x16x32_bf16 v[22:25], v[142:145], v[174:177], v[22:25]
	v_mfma_f32_16x16x32_bf16 v[46:49], v[134:137], v[218:221], v[46:49]
	v_mfma_f32_16x16x32_bf16 v[14:17], v[142:145], v[218:221], v[14:17]
	v_mfma_f32_16x16x32_bf16 v[38:41], v[134:137], v[226:229], v[38:41]
	v_mfma_f32_16x16x32_bf16 v[6:9], v[142:145], v[226:229], v[6:9]
	v_mfma_f32_16x16x32_bf16 v[58:61], v[146:149], v[162:165], v[58:61]
	v_mfma_f32_16x16x32_bf16 v[26:29], v[154:157], v[162:165], v[26:29]
	v_mfma_f32_16x16x32_bf16 v[50:53], v[146:149], v[170:173], v[50:53]
	v_mfma_f32_16x16x32_bf16 v[18:21], v[154:157], v[170:173], v[18:21]
	v_mfma_f32_16x16x32_bf16 v[42:45], v[146:149], v[214:217], v[42:45]
	v_mfma_f32_16x16x32_bf16 v[10:13], v[154:157], v[214:217], v[10:13]
	v_mfma_f32_16x16x32_bf16 v[34:37], v[146:149], v[222:225], v[34:37]
	v_mfma_f32_16x16x32_bf16 v[2:5], v[154:157], v[222:225], v[2:5]
	v_mfma_f32_16x16x32_bf16 v[58:61], v[150:153], v[166:169], v[58:61]
	v_mfma_f32_16x16x32_bf16 v[26:29], v[158:161], v[166:169], v[26:29]
	v_mfma_f32_16x16x32_bf16 v[50:53], v[150:153], v[174:177], v[50:53]
	v_mfma_f32_16x16x32_bf16 v[18:21], v[158:161], v[174:177], v[18:21]
	v_mfma_f32_16x16x32_bf16 v[42:45], v[150:153], v[218:221], v[42:45]
	v_mfma_f32_16x16x32_bf16 v[10:13], v[158:161], v[218:221], v[10:13]
	v_mfma_f32_16x16x32_bf16 v[34:37], v[150:153], v[226:229], v[34:37]
	v_mfma_f32_16x16x32_bf16 v[2:5], v[158:161], v[226:229], v[2:5]
	s_barrier
.LBB0_705:
	v_add_u32_e32 v142, s9, v211
	v_add_u32_e32 v158, s2, v211
	ds_read_b128 v[130:133], v142
	ds_read_b128 v[134:137], v142 offset:1024
	ds_read_b128 v[138:141], v142 offset:2048
	ds_read_b128 v[142:145], v142 offset:3072
	ds_read_b128 v[146:149], v158
	ds_read_b128 v[150:153], v158 offset:1024
	ds_read_b128 v[154:157], v158 offset:2048
	ds_read_b128 v[158:161], v158 offset:3072
	v_lshl_add_u64 v[200:201], s[42:43], 0, v[196:197]
	s_add_i32 m0, s12, 0xc000
	ds_read_b128 v[162:165], v212
	ds_read_b128 v[166:169], v212 offset:1024
	ds_read_b128 v[170:173], v212 offset:2048
	ds_read_b128 v[174:177], v212 offset:3072
	ds_read_b128 v[214:217], v212 offset:4096
	ds_read_b128 v[218:221], v212 offset:5120
	ds_read_b128 v[222:225], v212 offset:6144
	ds_read_b128 v[226:229], v212 offset:7168
	global_load_lds_dwordx4 v[200:201], off
	v_lshl_add_u64 v[200:201], s[42:43], 0, v[198:199]
	s_add_i32 m0, s12, 0xe000
	s_nop 0
	global_load_lds_dwordx4 v[200:201], off
	s_waitcnt vmcnt(8)
	s_waitcnt lgkmcnt(0)
	s_barrier
; #define PG8_STAGE(bufoff, gbase, voff) do { _Pragma("unroll") for (int _i = 0; _i < 2; ++_i) \
;         __builtin_amdgcn_global_load_lds((const unsigned*)((const char*)(gbase) + (voff)[_i]), (PG8_LAS unsigned*)(lds + (bufoff) + ldsw + _i * 8192), 16, 0, 0); } while (0)
; #define PG8_LDA(dst, b, h) do { _Pragma("unroll") for (int m = 0; m < 4; ++m) _Pragma("unroll") for (int k = 0; k < 2; ++k) dst[m][k] = *(const PG8_LAS bf16x8*)(lds + PG8_SA(b, h) + aoff + m * 2048 + k * 1024); } while (0)
; #define PG8_MMA(ai, bj, At, Bt) do { __builtin_amdgcn_s_setprio(1); _Pragma("unroll") for (int m = 0; m < 4; ++m) _Pragma("unroll") for (int n = 0; n < 2; ++n) _Pragma("unroll") for (int k = 0; k < 2; ++k) \
;         acc[ai][bj][m][n] = __builtin_amdgcn_mfma_f32_16x16x32_bf16(Bt[n][k], At[m][k], acc[ai][bj][m][n], 0, 0, 0); __builtin_amdgcn_s_setprio(0); } while (0)
; #define PG8_WAIT_V(n) asm volatile("s_waitcnt vmcnt(" #n ")" ::: "memory")
; #define PG8_WAIT_L(n) asm volatile("s_waitcnt lgkmcnt(" #n ")" ::: "memory")
; #define PG8_BAR __builtin_amdgcn_s_barrier()
; #define PG8_SCHED __builtin_amdgcn_sched_barrier(0)
; template <class Epi, class Sched, bool ALIGN_EPI = false, bool SP2 = false>
; __device__ __forceinline__ void gemm_phase(PG8_LAS unsigned char* lds, const Gemm g, const Sched& S, const Epi& E, const int wid_in) {
;     ...
;             PG8_WAIT_V(8); PG8_WAIT_L(0); PG8_BAR; PG8_MMA(0, 0, At, B0); PG8_MMA(0, 1, At, B1); PG8_BAR; PG8_SCHED;
;             PG8_LDA(At, 0, 1); PG8_STAGE(PG8_SB(0, 0), b2, voffB); PG8_STAGE(PG8_SB(0, 1), b2 + hstep, voffB); PG8_STAGE(PG8_SA(0, 0), a2, voffA);
;             PG8_WAIT_V(8); PG8_WAIT_L(0); PG8_BAR; PG8_MMA(1, 0, At, B0); PG8_MMA(1, 1, At, B1); PG8_BAR; PG8_SCHED;
	s_waitcnt lgkmcnt(0)
	v_mfma_f32_16x16x32_bf16 v[126:129], v[130:133], v[162:165], v[126:129]
	v_mfma_f32_16x16x32_bf16 v[94:97], v[138:141], v[162:165], v[94:97]
	v_mfma_f32_16x16x32_bf16 v[118:121], v[130:133], v[170:173], v[118:121]
	v_mfma_f32_16x16x32_bf16 v[86:89], v[138:141], v[170:173], v[86:89]
	v_mfma_f32_16x16x32_bf16 v[110:113], v[130:133], v[214:217], v[110:113]
	v_mfma_f32_16x16x32_bf16 v[78:81], v[138:141], v[214:217], v[78:81]
	v_mfma_f32_16x16x32_bf16 v[102:105], v[130:133], v[222:225], v[102:105]
	v_mfma_f32_16x16x32_bf16 v[70:73], v[138:141], v[222:225], v[70:73]
	v_mfma_f32_16x16x32_bf16 v[126:129], v[134:137], v[166:169], v[126:129]
	v_mfma_f32_16x16x32_bf16 v[94:97], v[142:145], v[166:169], v[94:97]
	v_mfma_f32_16x16x32_bf16 v[118:121], v[134:137], v[174:177], v[118:121]
	v_mfma_f32_16x16x32_bf16 v[86:89], v[142:145], v[174:177], v[86:89]
	v_mfma_f32_16x16x32_bf16 v[110:113], v[134:137], v[218:221], v[110:113]
	v_mfma_f32_16x16x32_bf16 v[78:81], v[142:145], v[218:221], v[78:81]
	v_mfma_f32_16x16x32_bf16 v[102:105], v[134:137], v[226:229], v[102:105]
	v_mfma_f32_16x16x32_bf16 v[70:73], v[142:145], v[226:229], v[70:73]
	v_mfma_f32_16x16x32_bf16 v[122:125], v[146:149], v[162:165], v[122:125]
	v_mfma_f32_16x16x32_bf16 v[90:93], v[154:157], v[162:165], v[90:93]
	v_mfma_f32_16x16x32_bf16 v[114:117], v[146:149], v[170:173], v[114:117]
	v_mfma_f32_16x16x32_bf16 v[82:85], v[154:157], v[170:173], v[82:85]
	v_mfma_f32_16x16x32_bf16 v[106:109], v[146:149], v[214:217], v[106:109]
	v_mfma_f32_16x16x32_bf16 v[74:77], v[154:157], v[214:217], v[74:77]
	v_mfma_f32_16x16x32_bf16 v[98:101], v[146:149], v[222:225], v[98:101]
	v_mfma_f32_16x16x32_bf16 v[66:69], v[154:157], v[222:225], v[66:69]
	v_mfma_f32_16x16x32_bf16 v[122:125], v[150:153], v[166:169], v[122:125]
	v_mfma_f32_16x16x32_bf16 v[90:93], v[158:161], v[166:169], v[90:93]
	v_mfma_f32_16x16x32_bf16 v[114:117], v[150:153], v[174:177], v[114:117]
	v_mfma_f32_16x16x32_bf16 v[82:85], v[158:161], v[174:177], v[82:85]
	v_mfma_f32_16x16x32_bf16 v[106:109], v[150:153], v[218:221], v[106:109]
	v_mfma_f32_16x16x32_bf16 v[74:77], v[158:161], v[218:221], v[74:77]
	v_mfma_f32_16x16x32_bf16 v[98:101], v[150:153], v[226:229], v[98:101]
	v_mfma_f32_16x16x32_bf16 v[66:69], v[158:161], v[226:229], v[66:69]
	s_barrier
	s_add_i32 s8, s9, s3
	v_lshl_add_u64 v[200:201], s[44:45], 0, v[0:1]
	s_mov_b32 m0, s8
	ds_read_b128 v[162:165], v212 offset:16384
	ds_read_b128 v[166:169], v212 offset:17408
	ds_read_b128 v[170:173], v212 offset:18432
	ds_read_b128 v[174:177], v212 offset:19456
	ds_read_b128 v[214:217], v212 offset:20480
	ds_read_b128 v[218:221], v212 offset:21504
	ds_read_b128 v[222:225], v212 offset:22528
	ds_read_b128 v[226:229], v212 offset:23552
	global_load_lds_dwordx4 v[200:201], off
	s_add_i32 m0, s8, 0x2000
	s_add_u32 s22, s44, 0x40000
	v_lshl_add_u64 v[230:231], s[44:45], 0, v[194:195]
	s_addc_u32 s23, s45, 0
	s_add_i32 s2, s2, s3
	global_load_lds_dwordx4 v[230:231], off
	v_lshl_add_u64 v[232:233], s[22:23], 0, v[0:1]
	s_mov_b32 m0, s2
	v_lshl_add_u64 v[234:235], s[46:47], 0, v[192:193]
	global_load_lds_dwordx4 v[232:233], off
	v_lshl_add_u64 v[232:233], s[22:23], 0, v[194:195]
	s_add_i32 m0, s2, 0x2000
	s_nop 0
	global_load_lds_dwordx4 v[232:233], off
	v_lshl_add_u64 v[232:233], s[46:47], 0, v[190:191]
	s_mov_b32 m0, s12
	s_nop 0
	global_load_lds_dwordx4 v[232:233], off
	s_mov_b32 m0, s13
	s_nop 0
	global_load_lds_dwordx4 v[234:235], off
	s_waitcnt vmcnt(8)
	s_waitcnt lgkmcnt(0)
	s_barrier
	s_waitcnt lgkmcnt(0)
	v_mfma_f32_16x16x32_bf16 v[62:65], v[130:133], v[162:165], v[62:65]
	v_mfma_f32_16x16x32_bf16 v[30:33], v[138:141], v[162:165], v[30:33]
	v_mfma_f32_16x16x32_bf16 v[54:57], v[130:133], v[170:173], v[54:57]
	v_mfma_f32_16x16x32_bf16 v[22:25], v[138:141], v[170:173], v[22:25]
	v_mfma_f32_16x16x32_bf16 v[46:49], v[130:133], v[214:217], v[46:49]
	v_mfma_f32_16x16x32_bf16 v[14:17], v[138:141], v[214:217], v[14:17]
	v_mfma_f32_16x16x32_bf16 v[38:41], v[130:133], v[222:225], v[38:41]
	v_mfma_f32_16x16x32_bf16 v[6:9], v[138:141], v[222:225], v[6:9]
	v_mfma_f32_16x16x32_bf16 v[62:65], v[134:137], v[166:169], v[62:65]
	v_mfma_f32_16x16x32_bf16 v[30:33], v[142:145], v[166:169], v[30:33]
	v_mfma_f32_16x16x32_bf16 v[54:57], v[134:137], v[174:177], v[54:57]
	v_mfma_f32_16x16x32_bf16 v[22:25], v[142:145], v[174:177], v[22:25]
	v_mfma_f32_16x16x32_bf16 v[46:49], v[134:137], v[218:221], v[46:49]
	v_mfma_f32_16x16x32_bf16 v[14:17], v[142:145], v[218:221], v[14:17]
	v_mfma_f32_16x16x32_bf16 v[38:41], v[134:137], v[226:229], v[38:41]
	v_mfma_f32_16x16x32_bf16 v[6:9], v[142:145], v[226:229], v[6:9]
	v_mfma_f32_16x16x32_bf16 v[58:61], v[146:149], v[162:165], v[58:61]
	v_mfma_f32_16x16x32_bf16 v[26:29], v[154:157], v[162:165], v[26:29]
	v_mfma_f32_16x16x32_bf16 v[50:53], v[146:149], v[170:173], v[50:53]
	v_mfma_f32_16x16x32_bf16 v[18:21], v[154:157], v[170:173], v[18:21]
	v_mfma_f32_16x16x32_bf16 v[42:45], v[146:149], v[214:217], v[42:45]
	v_mfma_f32_16x16x32_bf16 v[10:13], v[154:157], v[214:217], v[10:13]
	v_mfma_f32_16x16x32_bf16 v[34:37], v[146:149], v[222:225], v[34:37]
	v_mfma_f32_16x16x32_bf16 v[2:5], v[154:157], v[222:225], v[2:5]
	v_mfma_f32_16x16x32_bf16 v[58:61], v[150:153], v[166:169], v[58:61]
	v_mfma_f32_16x16x32_bf16 v[26:29], v[158:161], v[166:169], v[26:29]
	v_mfma_f32_16x16x32_bf16 v[50:53], v[150:153], v[174:177], v[50:53]
	v_mfma_f32_16x16x32_bf16 v[18:21], v[158:161], v[174:177], v[18:21]
	v_mfma_f32_16x16x32_bf16 v[42:45], v[150:153], v[218:221], v[42:45]
	v_mfma_f32_16x16x32_bf16 v[10:13], v[158:161], v[218:221], v[10:13]
	v_mfma_f32_16x16x32_bf16 v[34:37], v[150:153], v[226:229], v[34:37]
	v_mfma_f32_16x16x32_bf16 v[2:5], v[158:161], v[226:229], v[2:5]
	s_barrier
; #define PG8_STAGE(bufoff, gbase, voff) do { _Pragma("unroll") for (int _i = 0; _i < 2; ++_i) \
;         __builtin_amdgcn_global_load_lds((const unsigned*)((const char*)(gbase) + (voff)[_i]), (PG8_LAS unsigned*)(lds + (bufoff) + ldsw + _i * 8192), 16, 0, 0); } while (0)
; #define PG8_LDA(dst, b, h) do { _Pragma("unroll") for (int m = 0; m < 4; ++m) _Pragma("unroll") for (int k = 0; k < 2; ++k) dst[m][k] = *(const PG8_LAS bf16x8*)(lds + PG8_SA(b, h) + aoff + m * 2048 + k * 1024); } while (0)
; #define PG8_LDB(dst, b, h) do { _Pragma("unroll") for (int n = 0; n < 2; ++n) _Pragma("unroll") for (int k = 0; k < 2; ++k) dst[n][k] = *(const PG8_LAS bf16x8*)(lds + PG8_SB(b, h) + boff + n * 2048 + k * 1024); } while (0)
; #define PG8_MMA(ai, bj, At, Bt) do { __builtin_amdgcn_s_setprio(1); _Pragma("unroll") for (int m = 0; m < 4; ++m) _Pragma("unroll") for (int n = 0; n < 2; ++n) _Pragma("unroll") for (int k = 0; k < 2; ++k) \
;         acc[ai][bj][m][n] = __builtin_amdgcn_mfma_f32_16x16x32_bf16(Bt[n][k], At[m][k], acc[ai][bj][m][n], 0, 0, 0); __builtin_amdgcn_s_setprio(0); } while (0)
; #define PG8_WAIT_V(n) asm volatile("s_waitcnt vmcnt(" #n ")" ::: "memory")
; #define PG8_WAIT_L(n) asm volatile("s_waitcnt lgkmcnt(" #n ")" ::: "memory")
; #define PG8_BAR __builtin_amdgcn_s_barrier()
; #define PG8_SCHED __builtin_amdgcn_sched_barrier(0)
; template <class Epi, class Sched, bool ALIGN_EPI = false, bool SP2 = false>
; __device__ __forceinline__ void gemm_phase(PG8_LAS unsigned char* lds, const Gemm g, const Sched& S, const Epi& E, const int wid_in) {
;     ...
;             PG8_LDB(B0, 1, 0); PG8_LDB(B1, 1, 1); PG8_SCHED; PG8_LDA(At, 1, 0); PG8_STAGE(PG8_SA(0, 1), a2 + hstep, voffA);
;             PG8_WAIT_V(8); PG8_WAIT_L(0); PG8_BAR; PG8_MMA(0, 0, At, B0); PG8_MMA(0, 1, At, B1); PG8_BAR; PG8_SCHED;
	s_add_i32 s2, 0, 0x18000
	s_add_i32 s8, 0, 0x1c000
	v_add_u32_e32 v142, s2, v211
	v_add_u32_e32 v158, s8, v211
	ds_read_b128 v[130:133], v142
	ds_read_b128 v[134:137], v142 offset:1024
	ds_read_b128 v[138:141], v142 offset:2048
	ds_read_b128 v[142:145], v142 offset:3072
	ds_read_b128 v[146:149], v158
	ds_read_b128 v[150:153], v158 offset:1024
	ds_read_b128 v[154:157], v158 offset:2048
	ds_read_b128 v[158:161], v158 offset:3072
	s_add_u32 s22, s46, 0x40000
	s_addc_u32 s23, s47, 0
	s_mov_b32 m0, s36
	v_lshl_add_u64 v[236:237], s[22:23], 0, v[190:191]
	ds_read_b128 v[162:165], v212 offset:32768
	ds_read_b128 v[166:169], v212 offset:33792
	ds_read_b128 v[170:173], v212 offset:34816
	ds_read_b128 v[174:177], v212 offset:35840
	ds_read_b128 v[214:217], v212 offset:36864
	ds_read_b128 v[218:221], v212 offset:37888
	ds_read_b128 v[222:225], v212 offset:38912
	ds_read_b128 v[226:229], v212 offset:39936
	global_load_lds_dwordx4 v[236:237], off
	v_lshl_add_u64 v[236:237], s[22:23], 0, v[192:193]
	s_mov_b32 m0, s37
	s_nop 0
	global_load_lds_dwordx4 v[236:237], off
	s_waitcnt vmcnt(8)
	s_waitcnt lgkmcnt(0)
	s_barrier
	s_waitcnt lgkmcnt(0)
	v_mfma_f32_16x16x32_bf16 v[126:129], v[130:133], v[162:165], v[126:129]
	v_mfma_f32_16x16x32_bf16 v[94:97], v[138:141], v[162:165], v[94:97]
	v_mfma_f32_16x16x32_bf16 v[118:121], v[130:133], v[170:173], v[118:121]
	v_mfma_f32_16x16x32_bf16 v[86:89], v[138:141], v[170:173], v[86:89]
	v_mfma_f32_16x16x32_bf16 v[110:113], v[130:133], v[214:217], v[110:113]
	v_mfma_f32_16x16x32_bf16 v[78:81], v[138:141], v[214:217], v[78:81]
	v_mfma_f32_16x16x32_bf16 v[102:105], v[130:133], v[222:225], v[102:105]
	v_mfma_f32_16x16x32_bf16 v[70:73], v[138:141], v[222:225], v[70:73]
	v_mfma_f32_16x16x32_bf16 v[126:129], v[134:137], v[166:169], v[126:129]
	v_mfma_f32_16x16x32_bf16 v[94:97], v[142:145], v[166:169], v[94:97]
	v_mfma_f32_16x16x32_bf16 v[118:121], v[134:137], v[174:177], v[118:121]
	v_mfma_f32_16x16x32_bf16 v[86:89], v[142:145], v[174:177], v[86:89]
	v_mfma_f32_16x16x32_bf16 v[110:113], v[134:137], v[218:221], v[110:113]
	v_mfma_f32_16x16x32_bf16 v[78:81], v[142:145], v[218:221], v[78:81]
	v_mfma_f32_16x16x32_bf16 v[102:105], v[134:137], v[226:229], v[102:105]
	v_mfma_f32_16x16x32_bf16 v[70:73], v[142:145], v[226:229], v[70:73]
	v_mfma_f32_16x16x32_bf16 v[122:125], v[146:149], v[162:165], v[122:125]
	v_mfma_f32_16x16x32_bf16 v[90:93], v[154:157], v[162:165], v[90:93]
	v_mfma_f32_16x16x32_bf16 v[114:117], v[146:149], v[170:173], v[114:117]
	v_mfma_f32_16x16x32_bf16 v[82:85], v[154:157], v[170:173], v[82:85]
	v_mfma_f32_16x16x32_bf16 v[106:109], v[146:149], v[214:217], v[106:109]
	v_mfma_f32_16x16x32_bf16 v[74:77], v[154:157], v[214:217], v[74:77]
	v_mfma_f32_16x16x32_bf16 v[98:101], v[146:149], v[222:225], v[98:101]
	v_mfma_f32_16x16x32_bf16 v[66:69], v[154:157], v[222:225], v[66:69]
	v_mfma_f32_16x16x32_bf16 v[122:125], v[150:153], v[166:169], v[122:125]
	v_mfma_f32_16x16x32_bf16 v[90:93], v[158:161], v[166:169], v[90:93]
	v_mfma_f32_16x16x32_bf16 v[114:117], v[150:153], v[174:177], v[114:117]
	v_mfma_f32_16x16x32_bf16 v[82:85], v[158:161], v[174:177], v[82:85]
	v_mfma_f32_16x16x32_bf16 v[106:109], v[150:153], v[218:221], v[106:109]
	v_mfma_f32_16x16x32_bf16 v[74:77], v[158:161], v[218:221], v[74:77]
	v_mfma_f32_16x16x32_bf16 v[98:101], v[150:153], v[226:229], v[98:101]
	v_mfma_f32_16x16x32_bf16 v[66:69], v[158:161], v[226:229], v[66:69]
	s_barrier
; #define PG8_STAGE(bufoff, gbase, voff) do { _Pragma("unroll") for (int _i = 0; _i < 2; ++_i) \
;         __builtin_amdgcn_global_load_lds((const unsigned*)((const char*)(gbase) + (voff)[_i]), (PG8_LAS unsigned*)(lds + (bufoff) + ldsw + _i * 8192), 16, 0, 0); } while (0)
; #define PG8_LDA(dst, b, h) do { _Pragma("unroll") for (int m = 0; m < 4; ++m) _Pragma("unroll") for (int k = 0; k < 2; ++k) dst[m][k] = *(const PG8_LAS bf16x8*)(lds + PG8_SA(b, h) + aoff + m * 2048 + k * 1024); } while (0)
; #define PG8_WAIT_V(n) asm volatile("s_waitcnt vmcnt(" #n ")" ::: "memory")
; #define PG8_WAIT_L(n) asm volatile("s_waitcnt lgkmcnt(" #n ")" ::: "memory")
; #define PG8_BAR __builtin_amdgcn_s_barrier()
; template <class Epi, class Sched, bool ALIGN_EPI = false, bool SP2 = false>
; __device__ __forceinline__ void gemm_phase(PG8_LAS unsigned char* lds, const Gemm g, const Sched& S, const Epi& E, const int wid_in) {
;     ...
;         for (int t = 0; t < nt; t += 2) {
;             const bool last = (t == nt - 2);
;             const char* a1 = cA + (size_t)(t + 1) * kstep;
;             const char* a2 = last ? nA : cA + (size_t)(t + 2) * kstep; const char* b2 = last ? nB : cB + (size_t)(t + 2) * kstep;
;             const char* a3 = a2 + kstep; const char* b3 = b2 + kstep;
;             if (last && has_next) S.a_ready(nxt);
;             if constexpr (SP2) {
;             PG8_LDB(B0, 0, 0); PG8_LDB(B1, 0, 1); PG8_SCHED; PG8_LDA(At, 0, 0); PG8_STAGE(PG8_SA(1, 1), a1 + hstep, voffA);
;             PG8_WAIT_V(8); PG8_WAIT_L(0); PG8_BAR; PG8_MMA(0, 0, At, B0); PG8_MMA(0, 1, At, B1); PG8_BAR; PG8_SCHED;
;             PG8_LDA(At, 0, 1); PG8_STAGE(PG8_SB(0, 0), b2, voffB); PG8_STAGE(PG8_SB(0, 1), b2 + hstep, voffB); PG8_STAGE(PG8_SA(0, 0), a2, voffA);
;             PG8_WAIT_V(8); PG8_WAIT_L(0); PG8_BAR; PG8_MMA(1, 0, At, B0); PG8_MMA(1, 1, At, B1); PG8_BAR; PG8_SCHED;
;             PG8_LDB(B0, 1, 0); PG8_LDB(B1, 1, 1); PG8_SCHED; PG8_LDA(At, 1, 0); PG8_STAGE(PG8_SA(0, 1), a2 + hstep, voffA);
;             PG8_WAIT_V(8); PG8_WAIT_L(0); PG8_BAR; PG8_MMA(0, 0, At, B0); PG8_MMA(0, 1, At, B1); PG8_BAR; PG8_SCHED;
;             PG8_LDA(At, 1, 1); PG8_STAGE(PG8_SB(1, 0), b3, voffB); PG8_STAGE(PG8_SB(1, 1), b3 + hstep, voffB); PG8_STAGE(PG8_SA(1, 0), a3, voffA);
;             PG8_WAIT_V(8); PG8_WAIT_L(0); PG8_BAR; PG8_MMA(1, 0, At, B0); PG8_MMA(1, 1, At, B1); PG8_BAR; PG8_SCHED;
	s_add_i32 s2, s2, s3
	v_lshl_add_u64 v[200:201], v[200:201], 0, s[64:65]
	s_mov_b32 m0, s2
	ds_read_b128 v[162:165], v212 offset:49152
	ds_read_b128 v[166:169], v212 offset:50176
	ds_read_b128 v[170:173], v212 offset:51200
	ds_read_b128 v[174:177], v212 offset:52224
	ds_read_b128 v[214:217], v212 offset:53248
	ds_read_b128 v[218:221], v212 offset:54272
	ds_read_b128 v[222:225], v212 offset:55296
	ds_read_b128 v[226:229], v212 offset:56320
	global_load_lds_dwordx4 v[200:201], off
	s_add_i32 m0, s2, 0x2000
	s_add_u32 s22, s44, 0x40080
	v_lshl_add_u64 v[200:201], v[230:231], 0, s[64:65]
	s_addc_u32 s23, s45, 0
	s_add_i32 s2, s8, s3
	global_load_lds_dwordx4 v[200:201], off
	v_lshl_add_u64 v[200:201], s[22:23], 0, v[0:1]
	s_mov_b32 m0, s2
	s_nop 0
	global_load_lds_dwordx4 v[200:201], off
	v_lshl_add_u64 v[200:201], s[22:23], 0, v[194:195]
	s_add_i32 m0, s2, 0x2000
	s_nop 0
	global_load_lds_dwordx4 v[200:201], off
	v_lshl_add_u64 v[200:201], v[232:233], 0, s[64:65]
	s_mov_b32 m0, s78
	s_nop 0
	global_load_lds_dwordx4 v[200:201], off
	v_lshl_add_u64 v[200:201], v[234:235], 0, s[64:65]
	s_mov_b32 m0, s79
	s_nop 0
	global_load_lds_dwordx4 v[200:201], off
	s_add_i32 vcc_lo, vcc_lo, 2
	s_add_u32 s42, s42, 0x100
	s_addc_u32 s43, s43, 0
	s_add_u32 s61, s61, 0x100
	s_addc_u32 s62, s62, 0
	s_add_u32 s2, s42, 0xfffc0080
	s_addc_u32 s8, s43, -1
	s_add_i32 s9, 0, 0x10000
	s_cmp_eq_u32 vcc_lo, 12
	s_cselect_b32 s47, s48, s8
	s_cselect_b32 s46, s49, s2
	s_cselect_b32 s45, s16, s62
	s_cselect_b32 s44, s59, s61
	s_add_i32 s2, 0, 0x14000
	s_cmp_gt_u32 vcc_lo, 13
	s_waitcnt vmcnt(8)
	s_waitcnt lgkmcnt(0)
	s_barrier
	s_waitcnt lgkmcnt(0)
	v_mfma_f32_16x16x32_bf16 v[62:65], v[130:133], v[162:165], v[62:65]
	v_mfma_f32_16x16x32_bf16 v[30:33], v[138:141], v[162:165], v[30:33]
	v_mfma_f32_16x16x32_bf16 v[54:57], v[130:133], v[170:173], v[54:57]
	v_mfma_f32_16x16x32_bf16 v[22:25], v[138:141], v[170:173], v[22:25]
	v_mfma_f32_16x16x32_bf16 v[46:49], v[130:133], v[214:217], v[46:49]
	v_mfma_f32_16x16x32_bf16 v[14:17], v[138:141], v[214:217], v[14:17]
	v_mfma_f32_16x16x32_bf16 v[38:41], v[130:133], v[222:225], v[38:41]
	v_mfma_f32_16x16x32_bf16 v[6:9], v[138:141], v[222:225], v[6:9]
	v_mfma_f32_16x16x32_bf16 v[62:65], v[134:137], v[166:169], v[62:65]
	v_mfma_f32_16x16x32_bf16 v[30:33], v[142:145], v[166:169], v[30:33]
	v_mfma_f32_16x16x32_bf16 v[54:57], v[134:137], v[174:177], v[54:57]
	v_mfma_f32_16x16x32_bf16 v[22:25], v[142:145], v[174:177], v[22:25]
	v_mfma_f32_16x16x32_bf16 v[46:49], v[134:137], v[218:221], v[46:49]
	v_mfma_f32_16x16x32_bf16 v[14:17], v[142:145], v[218:221], v[14:17]
	v_mfma_f32_16x16x32_bf16 v[38:41], v[134:137], v[226:229], v[38:41]
	v_mfma_f32_16x16x32_bf16 v[6:9], v[142:145], v[226:229], v[6:9]
	v_mfma_f32_16x16x32_bf16 v[58:61], v[146:149], v[162:165], v[58:61]
	v_mfma_f32_16x16x32_bf16 v[26:29], v[154:157], v[162:165], v[26:29]
	v_mfma_f32_16x16x32_bf16 v[50:53], v[146:149], v[170:173], v[50:53]
	v_mfma_f32_16x16x32_bf16 v[18:21], v[154:157], v[170:173], v[18:21]
	v_mfma_f32_16x16x32_bf16 v[42:45], v[146:149], v[214:217], v[42:45]
	v_mfma_f32_16x16x32_bf16 v[10:13], v[154:157], v[214:217], v[10:13]
	v_mfma_f32_16x16x32_bf16 v[34:37], v[146:149], v[222:225], v[34:37]
	v_mfma_f32_16x16x32_bf16 v[2:5], v[154:157], v[222:225], v[2:5]
	v_mfma_f32_16x16x32_bf16 v[58:61], v[150:153], v[166:169], v[58:61]
	v_mfma_f32_16x16x32_bf16 v[26:29], v[158:161], v[166:169], v[26:29]
	v_mfma_f32_16x16x32_bf16 v[50:53], v[150:153], v[174:177], v[50:53]
	v_mfma_f32_16x16x32_bf16 v[18:21], v[158:161], v[174:177], v[18:21]
	v_mfma_f32_16x16x32_bf16 v[42:45], v[150:153], v[218:221], v[42:45]
	v_mfma_f32_16x16x32_bf16 v[10:13], v[158:161], v[218:221], v[10:13]
	v_mfma_f32_16x16x32_bf16 v[34:37], v[150:153], v[226:229], v[34:37]
	v_mfma_f32_16x16x32_bf16 v[2:5], v[158:161], v[226:229], v[2:5]
	s_barrier
	s_cbranch_scc0 .LBB0_705
	s_setprio 0
	v_readlane_b32 s8, v243, 63
	v_readlane_b32 s9, v242, 0
	s_and_b64 vcc, exec, s[8:9]
	s_cbranch_vccz .LBB0_708
	s_barrier

; #define PG8_STAGE(bufoff, gbase, voff) do { _Pragma("unroll") for (int _i = 0; _i < 2; ++_i) \
;         __builtin_amdgcn_global_load_lds((const unsigned*)((const char*)(gbase) + (voff)[_i]), (PG8_LAS unsigned*)(lds + (bufoff) + ldsw + _i * 8192), 16, 0, 0); } while (0)
; #define PG8_LDA(dst, b, h) do { _Pragma("unroll") for (int m = 0; m < 4; ++m) _Pragma("unroll") for (int k = 0; k < 2; ++k) dst[m][k] = *(const PG8_LAS bf16x8*)(lds + PG8_SA(b, h) + aoff + m * 2048 + k * 1024); } while (0)
; #define PG8_LDB(dst, b, h) do { _Pragma("unroll") for (int n = 0; n < 2; ++n) _Pragma("unroll") for (int k = 0; k < 2; ++k) dst[n][k] = *(const PG8_LAS bf16x8*)(lds + PG8_SB(b, h) + boff + n * 2048 + k * 1024); } while (0)
; #define PG8_MMA(ai, bj, At, Bt) do { __builtin_amdgcn_s_setprio(1); _Pragma("unroll") for (int m = 0; m < 4; ++m) _Pragma("unroll") for (int n = 0; n < 2; ++n) _Pragma("unroll") for (int k = 0; k < 2; ++k) \
;         acc[ai][bj][m][n] = __builtin_amdgcn_mfma_f32_16x16x32_bf16(Bt[n][k], At[m][k], acc[ai][bj][m][n], 0, 0, 0); __builtin_amdgcn_s_setprio(0); } while (0)
; #define PG8_WAIT_V(n) asm volatile("s_waitcnt vmcnt(" #n ")" ::: "memory")
; #define PG8_WAIT_L(n) asm volatile("s_waitcnt lgkmcnt(" #n ")" ::: "memory")
; #define PG8_BAR __builtin_amdgcn_s_barrier()
; #define PG8_SCHED __builtin_amdgcn_sched_barrier(0)
; template <class Epi, class Sched, bool ALIGN_EPI = false, bool SP2 = false>
; __device__ __forceinline__ void gemm_phase(PG8_LAS unsigned char* lds, const Gemm g, const Sched& S, const Epi& E, const int wid_in) {
;     ...
;             PG8_LDB(B0, 0, 0); PG8_LDB(B1, 0, 1); PG8_SCHED; PG8_LDA(At, 0, 0); PG8_STAGE(PG8_SA(1, 1), a1 + hstep, voffA);
;             PG8_WAIT_V(8); PG8_WAIT_L(0); PG8_BAR; PG8_MMA(0, 0, At, B0); PG8_MMA(0, 1, At, B1); PG8_BAR; PG8_SCHED;
;             PG8_LDA(At, 0, 1); PG8_STAGE(PG8_SB(0, 0), b2, voffB); PG8_STAGE(PG8_SB(0, 1), b2 + hstep, voffB); PG8_STAGE(PG8_SA(0, 0), a2, voffA);
;             PG8_WAIT_V(8); PG8_WAIT_L(0); PG8_BAR; PG8_MMA(1, 0, At, B0); PG8_MMA(1, 1, At, B1); PG8_BAR; PG8_SCHED;
.Lprio_done_823:
	s_add_u32 s46, s44, 0x100
	s_addc_u32 s47, s45, 0
	s_add_i32 s2, 0, 0x10000
	s_cmp_eq_u32 s58, 40
	s_cselect_b32 s51, s41, s47
	s_cselect_b32 s50, s40, s46
	v_add_u32_e32 v140, s2, v142
	s_cselect_b32 s49, s43, s57
	s_cselect_b32 s48, s42, s16
	s_add_i32 s8, 0, 0x14000
	ds_read_b128 v[144:147], v140
	ds_read_b128 v[148:151], v140 offset:1024
	ds_read_b128 v[152:155], v140 offset:2048
	ds_read_b128 v[156:159], v140 offset:3072
	v_add_u32_e32 v140, s8, v142
	ds_read_b128 v[160:163], v140
	ds_read_b128 v[164:167], v140 offset:1024
	ds_read_b128 v[168:171], v140 offset:2048
	ds_read_b128 v[172:175], v140 offset:3072
	v_lshl_add_u64 v[140:141], s[44:45], 0, v[136:137]
	s_add_i32 m0, s4, 0xc000
	ds_read_b128 v[190:193], v143
	ds_read_b128 v[194:197], v143 offset:1024
	ds_read_b128 v[198:201], v143 offset:2048
	ds_read_b128 v[212:215], v143 offset:3072
	ds_read_b128 v[216:219], v143 offset:4096
	ds_read_b128 v[220:223], v143 offset:5120
	ds_read_b128 v[224:227], v143 offset:6144
	ds_read_b128 v[228:231], v143 offset:7168
	global_load_lds_dwordx4 v[140:141], off
	v_lshl_add_u64 v[140:141], s[44:45], 0, v[138:139]
	s_add_i32 m0, s4, 0xe000
	s_nop 0
	global_load_lds_dwordx4 v[140:141], off
	s_waitcnt vmcnt(8)
	s_waitcnt lgkmcnt(0)
	s_barrier
	s_waitcnt lgkmcnt(0)
	v_mfma_f32_16x16x32_bf16 v[126:129], v[144:147], v[190:193], 0
	v_mfma_f32_16x16x32_bf16 v[122:125], v[152:155], v[190:193], 0
	v_mfma_f32_16x16x32_bf16 v[118:121], v[144:147], v[198:201], 0
	v_mfma_f32_16x16x32_bf16 v[110:113], v[152:155], v[198:201], 0
	v_mfma_f32_16x16x32_bf16 v[102:105], v[144:147], v[216:219], 0
	v_mfma_f32_16x16x32_bf16 v[94:97], v[152:155], v[216:219], 0
	v_mfma_f32_16x16x32_bf16 v[82:85], v[144:147], v[224:227], 0
	v_mfma_f32_16x16x32_bf16 v[74:77], v[152:155], v[224:227], 0
	v_mfma_f32_16x16x32_bf16 v[126:129], v[148:151], v[194:197], v[126:129]
	v_mfma_f32_16x16x32_bf16 v[122:125], v[156:159], v[194:197], v[122:125]
	v_mfma_f32_16x16x32_bf16 v[118:121], v[148:151], v[212:215], v[118:121]
	v_mfma_f32_16x16x32_bf16 v[110:113], v[156:159], v[212:215], v[110:113]
	v_mfma_f32_16x16x32_bf16 v[102:105], v[148:151], v[220:223], v[102:105]
	v_mfma_f32_16x16x32_bf16 v[94:97], v[156:159], v[220:223], v[94:97]
	v_mfma_f32_16x16x32_bf16 v[82:85], v[148:151], v[228:231], v[82:85]
	v_mfma_f32_16x16x32_bf16 v[74:77], v[156:159], v[228:231], v[74:77]
	v_mfma_f32_16x16x32_bf16 v[114:117], v[160:163], v[190:193], 0
	v_mfma_f32_16x16x32_bf16 v[106:109], v[168:171], v[190:193], 0
	v_mfma_f32_16x16x32_bf16 v[98:101], v[160:163], v[198:201], 0
	v_mfma_f32_16x16x32_bf16 v[90:93], v[168:171], v[198:201], 0
	v_mfma_f32_16x16x32_bf16 v[86:89], v[160:163], v[216:219], 0
	v_mfma_f32_16x16x32_bf16 v[78:81], v[168:171], v[216:219], 0
	v_mfma_f32_16x16x32_bf16 v[70:73], v[160:163], v[224:227], 0
	v_mfma_f32_16x16x32_bf16 v[66:69], v[168:171], v[224:227], 0
	v_mfma_f32_16x16x32_bf16 v[114:117], v[164:167], v[194:197], v[114:117]
	v_mfma_f32_16x16x32_bf16 v[106:109], v[172:175], v[194:197], v[106:109]
	v_mfma_f32_16x16x32_bf16 v[98:101], v[164:167], v[212:215], v[98:101]
	v_mfma_f32_16x16x32_bf16 v[90:93], v[172:175], v[212:215], v[90:93]
	v_mfma_f32_16x16x32_bf16 v[86:89], v[164:167], v[220:223], v[86:89]
	v_mfma_f32_16x16x32_bf16 v[78:81], v[172:175], v[220:223], v[78:81]
	v_mfma_f32_16x16x32_bf16 v[70:73], v[164:167], v[228:231], v[70:73]
	v_mfma_f32_16x16x32_bf16 v[66:69], v[172:175], v[228:231], v[66:69]
	s_barrier
	s_add_i32 s2, s2, s3
	v_lshl_add_u64 v[140:141], s[48:49], 0, v[0:1]
	s_mov_b32 m0, s2
	ds_read_b128 v[190:193], v143 offset:16384
	ds_read_b128 v[194:197], v143 offset:17408
	ds_read_b128 v[198:201], v143 offset:18432
	ds_read_b128 v[212:215], v143 offset:19456
	ds_read_b128 v[216:219], v143 offset:20480
	ds_read_b128 v[220:223], v143 offset:21504
	ds_read_b128 v[224:227], v143 offset:22528
	ds_read_b128 v[228:231], v143 offset:23552
	global_load_lds_dwordx4 v[140:141], off
	s_add_i32 m0, s2, 0x2000
	s_add_u32 s22, s48, 0xb0000
	v_lshl_add_u64 v[176:177], s[48:49], 0, v[130:131]
	s_addc_u32 s23, s49, 0
	s_add_i32 s2, s8, s3
	global_load_lds_dwordx4 v[176:177], off
	v_lshl_add_u64 v[232:233], s[22:23], 0, v[0:1]
	s_mov_b32 m0, s2
	v_lshl_add_u64 v[234:235], s[50:51], 0, v[132:133]
	global_load_lds_dwordx4 v[232:233], off
	v_lshl_add_u64 v[232:233], s[22:23], 0, v[130:131]
	s_add_i32 m0, s2, 0x2000
	s_nop 0
	global_load_lds_dwordx4 v[232:233], off
	v_lshl_add_u64 v[232:233], s[50:51], 0, v[134:135]
	s_mov_b32 m0, s4
	s_nop 0
	global_load_lds_dwordx4 v[232:233], off
	s_mov_b32 m0, s5
	s_nop 0
	global_load_lds_dwordx4 v[234:235], off
	s_waitcnt vmcnt(8)
	s_waitcnt lgkmcnt(0)
	s_barrier
; #define PG8_STAGE(bufoff, gbase, voff) do { _Pragma("unroll") for (int _i = 0; _i < 2; ++_i) \
;         __builtin_amdgcn_global_load_lds((const unsigned*)((const char*)(gbase) + (voff)[_i]), (PG8_LAS unsigned*)(lds + (bufoff) + ldsw + _i * 8192), 16, 0, 0); } while (0)
; #define PG8_LDA(dst, b, h) do { _Pragma("unroll") for (int m = 0; m < 4; ++m) _Pragma("unroll") for (int k = 0; k < 2; ++k) dst[m][k] = *(const PG8_LAS bf16x8*)(lds + PG8_SA(b, h) + aoff + m * 2048 + k * 1024); } while (0)
; #define PG8_LDB(dst, b, h) do { _Pragma("unroll") for (int n = 0; n < 2; ++n) _Pragma("unroll") for (int k = 0; k < 2; ++k) dst[n][k] = *(const PG8_LAS bf16x8*)(lds + PG8_SB(b, h) + boff + n * 2048 + k * 1024); } while (0)
; #define PG8_MMA(ai, bj, At, Bt) do { __builtin_amdgcn_s_setprio(1); _Pragma("unroll") for (int m = 0; m < 4; ++m) _Pragma("unroll") for (int n = 0; n < 2; ++n) _Pragma("unroll") for (int k = 0; k < 2; ++k) \
;         acc[ai][bj][m][n] = __builtin_amdgcn_mfma_f32_16x16x32_bf16(Bt[n][k], At[m][k], acc[ai][bj][m][n], 0, 0, 0); __builtin_amdgcn_s_setprio(0); } while (0)
; #define PG8_WAIT_V(n) asm volatile("s_waitcnt vmcnt(" #n ")" ::: "memory")
; #define PG8_WAIT_L(n) asm volatile("s_waitcnt lgkmcnt(" #n ")" ::: "memory")
; #define PG8_BAR __builtin_amdgcn_s_barrier()
; #define PG8_SCHED __builtin_amdgcn_sched_barrier(0)
; template <class Epi, class Sched, bool ALIGN_EPI = false, bool SP2 = false>
; __device__ __forceinline__ void gemm_phase(PG8_LAS unsigned char* lds, const Gemm g, const Sched& S, const Epi& E, const int wid_in) {
;     ...
;             PG8_WAIT_V(8); PG8_WAIT_L(0); PG8_BAR; PG8_MMA(1, 0, At, B0); PG8_MMA(1, 1, At, B1); PG8_BAR; PG8_SCHED;
;             PG8_LDB(B0, 1, 0); PG8_LDB(B1, 1, 1); PG8_SCHED; PG8_LDA(At, 1, 0); PG8_STAGE(PG8_SA(0, 1), a2 + hstep, voffA);
;             PG8_WAIT_V(8); PG8_WAIT_L(0); PG8_BAR; PG8_MMA(0, 0, At, B0); PG8_MMA(0, 1, At, B1); PG8_BAR; PG8_SCHED;
	s_waitcnt lgkmcnt(0)
	v_mfma_f32_16x16x32_bf16 v[62:65], v[144:147], v[190:193], 0
	v_mfma_f32_16x16x32_bf16 v[58:61], v[152:155], v[190:193], 0
	v_mfma_f32_16x16x32_bf16 v[54:57], v[144:147], v[198:201], 0
	v_mfma_f32_16x16x32_bf16 v[46:49], v[152:155], v[198:201], 0
	v_mfma_f32_16x16x32_bf16 v[38:41], v[144:147], v[216:219], 0
	v_mfma_f32_16x16x32_bf16 v[30:33], v[152:155], v[216:219], 0
	v_mfma_f32_16x16x32_bf16 v[22:25], v[144:147], v[224:227], 0
	v_mfma_f32_16x16x32_bf16 v[14:17], v[152:155], v[224:227], 0
	v_mfma_f32_16x16x32_bf16 v[62:65], v[148:151], v[194:197], v[62:65]
	v_mfma_f32_16x16x32_bf16 v[58:61], v[156:159], v[194:197], v[58:61]
	v_mfma_f32_16x16x32_bf16 v[54:57], v[148:151], v[212:215], v[54:57]
	v_mfma_f32_16x16x32_bf16 v[46:49], v[156:159], v[212:215], v[46:49]
	v_mfma_f32_16x16x32_bf16 v[38:41], v[148:151], v[220:223], v[38:41]
	v_mfma_f32_16x16x32_bf16 v[30:33], v[156:159], v[220:223], v[30:33]
	v_mfma_f32_16x16x32_bf16 v[22:25], v[148:151], v[228:231], v[22:25]
	v_mfma_f32_16x16x32_bf16 v[14:17], v[156:159], v[228:231], v[14:17]
	v_mfma_f32_16x16x32_bf16 v[50:53], v[160:163], v[190:193], 0
	v_mfma_f32_16x16x32_bf16 v[42:45], v[168:171], v[190:193], 0
	v_mfma_f32_16x16x32_bf16 v[34:37], v[160:163], v[198:201], 0
	v_mfma_f32_16x16x32_bf16 v[26:29], v[168:171], v[198:201], 0
	v_mfma_f32_16x16x32_bf16 v[18:21], v[160:163], v[216:219], 0
	v_mfma_f32_16x16x32_bf16 v[10:13], v[168:171], v[216:219], 0
	v_mfma_f32_16x16x32_bf16 v[6:9], v[160:163], v[224:227], 0
	v_mfma_f32_16x16x32_bf16 v[2:5], v[168:171], v[224:227], 0
	v_mfma_f32_16x16x32_bf16 v[50:53], v[164:167], v[194:197], v[50:53]
	v_mfma_f32_16x16x32_bf16 v[42:45], v[172:175], v[194:197], v[42:45]
	v_mfma_f32_16x16x32_bf16 v[34:37], v[164:167], v[212:215], v[34:37]
	v_mfma_f32_16x16x32_bf16 v[26:29], v[172:175], v[212:215], v[26:29]
	v_mfma_f32_16x16x32_bf16 v[18:21], v[164:167], v[220:223], v[18:21]
	v_mfma_f32_16x16x32_bf16 v[10:13], v[172:175], v[220:223], v[10:13]
	v_mfma_f32_16x16x32_bf16 v[6:9], v[164:167], v[228:231], v[6:9]
	v_mfma_f32_16x16x32_bf16 v[2:5], v[172:175], v[228:231], v[2:5]
	s_barrier
	s_add_i32 s2, 0, 0x18000
	s_add_i32 s8, 0, 0x1c000
	v_add_u32_e32 v156, s2, v142
	v_add_u32_e32 v172, s8, v142
	ds_read_b128 v[144:147], v156
	ds_read_b128 v[148:151], v156 offset:1024
	ds_read_b128 v[152:155], v156 offset:2048
	ds_read_b128 v[156:159], v156 offset:3072
	ds_read_b128 v[160:163], v172
	ds_read_b128 v[164:167], v172 offset:1024
	ds_read_b128 v[168:171], v172 offset:2048
	ds_read_b128 v[172:175], v172 offset:3072
	s_add_u32 s22, s50, 0xb0000
	s_addc_u32 s23, s51, 0
	s_mov_b32 m0, s12
	v_lshl_add_u64 v[236:237], s[22:23], 0, v[134:135]
	ds_read_b128 v[190:193], v143 offset:32768
	ds_read_b128 v[194:197], v143 offset:33792
	ds_read_b128 v[198:201], v143 offset:34816
	ds_read_b128 v[212:215], v143 offset:35840
	ds_read_b128 v[216:219], v143 offset:36864
	ds_read_b128 v[220:223], v143 offset:37888
	ds_read_b128 v[224:227], v143 offset:38912
	ds_read_b128 v[228:231], v143 offset:39936
	global_load_lds_dwordx4 v[236:237], off
	v_lshl_add_u64 v[236:237], s[22:23], 0, v[132:133]
	s_mov_b32 m0, s13
	s_nop 0
	global_load_lds_dwordx4 v[236:237], off
	s_waitcnt vmcnt(8)
	s_waitcnt lgkmcnt(0)
	s_barrier
	s_waitcnt lgkmcnt(0)
	v_mfma_f32_16x16x32_bf16 v[126:129], v[144:147], v[190:193], v[126:129]
	v_mfma_f32_16x16x32_bf16 v[122:125], v[152:155], v[190:193], v[122:125]
	v_mfma_f32_16x16x32_bf16 v[118:121], v[144:147], v[198:201], v[118:121]
	v_mfma_f32_16x16x32_bf16 v[110:113], v[152:155], v[198:201], v[110:113]
	v_mfma_f32_16x16x32_bf16 v[102:105], v[144:147], v[216:219], v[102:105]
	v_mfma_f32_16x16x32_bf16 v[94:97], v[152:155], v[216:219], v[94:97]
	v_mfma_f32_16x16x32_bf16 v[82:85], v[144:147], v[224:227], v[82:85]
	v_mfma_f32_16x16x32_bf16 v[74:77], v[152:155], v[224:227], v[74:77]
	v_mfma_f32_16x16x32_bf16 v[126:129], v[148:151], v[194:197], v[126:129]
	v_mfma_f32_16x16x32_bf16 v[122:125], v[156:159], v[194:197], v[122:125]
	v_mfma_f32_16x16x32_bf16 v[118:121], v[148:151], v[212:215], v[118:121]
	v_mfma_f32_16x16x32_bf16 v[110:113], v[156:159], v[212:215], v[110:113]
	v_mfma_f32_16x16x32_bf16 v[102:105], v[148:151], v[220:223], v[102:105]
	v_mfma_f32_16x16x32_bf16 v[94:97], v[156:159], v[220:223], v[94:97]
	v_mfma_f32_16x16x32_bf16 v[82:85], v[148:151], v[228:231], v[82:85]
	v_mfma_f32_16x16x32_bf16 v[74:77], v[156:159], v[228:231], v[74:77]
	v_mfma_f32_16x16x32_bf16 v[114:117], v[160:163], v[190:193], v[114:117]
	v_mfma_f32_16x16x32_bf16 v[106:109], v[168:171], v[190:193], v[106:109]
	v_mfma_f32_16x16x32_bf16 v[98:101], v[160:163], v[198:201], v[98:101]
	v_mfma_f32_16x16x32_bf16 v[90:93], v[168:171], v[198:201], v[90:93]
	v_mfma_f32_16x16x32_bf16 v[86:89], v[160:163], v[216:219], v[86:89]
	v_mfma_f32_16x16x32_bf16 v[78:81], v[168:171], v[216:219], v[78:81]
	v_mfma_f32_16x16x32_bf16 v[70:73], v[160:163], v[224:227], v[70:73]
	v_mfma_f32_16x16x32_bf16 v[66:69], v[168:171], v[224:227], v[66:69]
	v_mfma_f32_16x16x32_bf16 v[114:117], v[164:167], v[194:197], v[114:117]
	v_mfma_f32_16x16x32_bf16 v[106:109], v[172:175], v[194:197], v[106:109]
	v_mfma_f32_16x16x32_bf16 v[98:101], v[164:167], v[212:215], v[98:101]
	v_mfma_f32_16x16x32_bf16 v[90:93], v[172:175], v[212:215], v[90:93]
	v_mfma_f32_16x16x32_bf16 v[86:89], v[164:167], v[220:223], v[86:89]
	v_mfma_f32_16x16x32_bf16 v[78:81], v[172:175], v[220:223], v[78:81]
	v_mfma_f32_16x16x32_bf16 v[70:73], v[164:167], v[228:231], v[70:73]
	v_mfma_f32_16x16x32_bf16 v[66:69], v[172:175], v[228:231], v[66:69]
	s_barrier
; #define PG8_STAGE(bufoff, gbase, voff) do { _Pragma("unroll") for (int _i = 0; _i < 2; ++_i) \
;         __builtin_amdgcn_global_load_lds((const unsigned*)((const char*)(gbase) + (voff)[_i]), (PG8_LAS unsigned*)(lds + (bufoff) + ldsw + _i * 8192), 16, 0, 0); } while (0)
; #define PG8_LDA(dst, b, h) do { _Pragma("unroll") for (int m = 0; m < 4; ++m) _Pragma("unroll") for (int k = 0; k < 2; ++k) dst[m][k] = *(const PG8_LAS bf16x8*)(lds + PG8_SA(b, h) + aoff + m * 2048 + k * 1024); } while (0)
; #define PG8_WAIT_V(n) asm volatile("s_waitcnt vmcnt(" #n ")" ::: "memory")
; #define PG8_WAIT_L(n) asm volatile("s_waitcnt lgkmcnt(" #n ")" ::: "memory")
; #define PG8_BAR __builtin_amdgcn_s_barrier()
; template <class Epi, class Sched, bool ALIGN_EPI = false, bool SP2 = false>
; __device__ __forceinline__ void gemm_phase(PG8_LAS unsigned char* lds, const Gemm g, const Sched& S, const Epi& E, const int wid_in) {
;     ...
;         for (int t = 0; t < nt; t += 2) {
;             const bool last = (t == nt - 2);
;             const char* a1 = cA + (size_t)(t + 1) * kstep;
;             const char* a2 = last ? nA : cA + (size_t)(t + 2) * kstep; const char* b2 = last ? nB : cB + (size_t)(t + 2) * kstep;
;             const char* a3 = a2 + kstep; const char* b3 = b2 + kstep;
;             if (last && has_next) S.a_ready(nxt);
;             if constexpr (SP2) {
;             PG8_LDB(B0, 0, 0); PG8_LDB(B1, 0, 1); PG8_SCHED; PG8_LDA(At, 0, 0); PG8_STAGE(PG8_SA(1, 1), a1 + hstep, voffA);
;             PG8_WAIT_V(8); PG8_WAIT_L(0); PG8_BAR; PG8_MMA(0, 0, At, B0); PG8_MMA(0, 1, At, B1); PG8_BAR; PG8_SCHED;
;             PG8_LDA(At, 0, 1); PG8_STAGE(PG8_SB(0, 0), b2, voffB); PG8_STAGE(PG8_SB(0, 1), b2 + hstep, voffB); PG8_STAGE(PG8_SA(0, 0), a2, voffA);
;             PG8_WAIT_V(8); PG8_WAIT_L(0); PG8_BAR; PG8_MMA(1, 0, At, B0); PG8_MMA(1, 1, At, B1); PG8_BAR; PG8_SCHED;
;             PG8_LDB(B0, 1, 0); PG8_LDB(B1, 1, 1); PG8_SCHED; PG8_LDA(At, 1, 0); PG8_STAGE(PG8_SA(0, 1), a2 + hstep, voffA);
;             PG8_WAIT_V(8); PG8_WAIT_L(0); PG8_BAR; PG8_MMA(0, 0, At, B0); PG8_MMA(0, 1, At, B1); PG8_BAR; PG8_SCHED;
;             PG8_LDA(At, 1, 1); PG8_STAGE(PG8_SB(1, 0), b3, voffB); PG8_STAGE(PG8_SB(1, 1), b3 + hstep, voffB); PG8_STAGE(PG8_SA(1, 0), a3, voffA);
;             PG8_WAIT_V(8); PG8_WAIT_L(0); PG8_BAR; PG8_MMA(1, 0, At, B0); PG8_MMA(1, 1, At, B1); PG8_BAR; PG8_SCHED;
	s_add_i32 s2, s2, s3
	v_lshl_add_u64 v[140:141], v[140:141], 0, s[64:65]
	s_mov_b32 m0, s2
	ds_read_b128 v[190:193], v143 offset:49152
	ds_read_b128 v[194:197], v143 offset:50176
	ds_read_b128 v[198:201], v143 offset:51200
	ds_read_b128 v[212:215], v143 offset:52224
	ds_read_b128 v[216:219], v143 offset:53248
	ds_read_b128 v[220:223], v143 offset:54272
	ds_read_b128 v[224:227], v143 offset:55296
	ds_read_b128 v[228:231], v143 offset:56320
	global_load_lds_dwordx4 v[140:141], off
	s_add_i32 m0, s2, 0x2000
	s_add_u32 s22, s48, 0xb0080
	v_lshl_add_u64 v[140:141], v[176:177], 0, s[64:65]
	s_addc_u32 s23, s49, 0
	s_add_i32 s2, s8, s3
	global_load_lds_dwordx4 v[140:141], off
	v_lshl_add_u64 v[140:141], s[22:23], 0, v[0:1]
	s_mov_b32 m0, s2
	s_nop 0
	global_load_lds_dwordx4 v[140:141], off
	v_lshl_add_u64 v[140:141], s[22:23], 0, v[130:131]
	s_add_i32 m0, s2, 0x2000
	s_nop 0
	global_load_lds_dwordx4 v[140:141], off
	v_lshl_add_u64 v[140:141], v[232:233], 0, s[64:65]
	s_mov_b32 m0, s36
	s_nop 0
	global_load_lds_dwordx4 v[140:141], off
	v_lshl_add_u64 v[140:141], v[234:235], 0, s[64:65]
	s_mov_b32 m0, s37
	s_nop 0
	global_load_lds_dwordx4 v[140:141], off
	s_add_i32 s58, s58, 2
	s_add_u32 s16, s16, 0x100
	s_addc_u32 s57, s57, 0
	s_mov_b64 s[44:45], s[46:47]
	s_add_u32 s46, s44, 0x100
	s_addc_u32 s47, s45, 0
	s_add_i32 s2, 0, 0x10000
	s_cmp_eq_u32 s58, 40
	s_cselect_b32 s51, s41, s47
	s_cselect_b32 s50, s40, s46
	s_cselect_b32 s49, s43, s57
	s_cselect_b32 s48, s42, s16
	s_add_i32 s8, 0, 0x14000
	s_cmp_gt_u32 s58, 41
	s_waitcnt vmcnt(8)
	s_waitcnt lgkmcnt(0)
	s_barrier
	s_waitcnt lgkmcnt(0)
	v_mfma_f32_16x16x32_bf16 v[62:65], v[144:147], v[190:193], v[62:65]
	v_mfma_f32_16x16x32_bf16 v[58:61], v[152:155], v[190:193], v[58:61]
	v_mfma_f32_16x16x32_bf16 v[54:57], v[144:147], v[198:201], v[54:57]
	v_mfma_f32_16x16x32_bf16 v[46:49], v[152:155], v[198:201], v[46:49]
	v_mfma_f32_16x16x32_bf16 v[38:41], v[144:147], v[216:219], v[38:41]
	v_mfma_f32_16x16x32_bf16 v[30:33], v[152:155], v[216:219], v[30:33]
	v_mfma_f32_16x16x32_bf16 v[22:25], v[144:147], v[224:227], v[22:25]
	v_mfma_f32_16x16x32_bf16 v[14:17], v[152:155], v[224:227], v[14:17]
	v_mfma_f32_16x16x32_bf16 v[62:65], v[148:151], v[194:197], v[62:65]
	v_mfma_f32_16x16x32_bf16 v[58:61], v[156:159], v[194:197], v[58:61]
	v_mfma_f32_16x16x32_bf16 v[54:57], v[148:151], v[212:215], v[54:57]
	v_mfma_f32_16x16x32_bf16 v[46:49], v[156:159], v[212:215], v[46:49]
	v_mfma_f32_16x16x32_bf16 v[38:41], v[148:151], v[220:223], v[38:41]
	v_mfma_f32_16x16x32_bf16 v[30:33], v[156:159], v[220:223], v[30:33]
	v_mfma_f32_16x16x32_bf16 v[22:25], v[148:151], v[228:231], v[22:25]
	v_mfma_f32_16x16x32_bf16 v[14:17], v[156:159], v[228:231], v[14:17]
	v_mfma_f32_16x16x32_bf16 v[50:53], v[160:163], v[190:193], v[50:53]
	v_mfma_f32_16x16x32_bf16 v[42:45], v[168:171], v[190:193], v[42:45]
	v_mfma_f32_16x16x32_bf16 v[34:37], v[160:163], v[198:201], v[34:37]
	v_mfma_f32_16x16x32_bf16 v[26:29], v[168:171], v[198:201], v[26:29]
	v_mfma_f32_16x16x32_bf16 v[18:21], v[160:163], v[216:219], v[18:21]
	v_mfma_f32_16x16x32_bf16 v[10:13], v[168:171], v[216:219], v[10:13]
	v_mfma_f32_16x16x32_bf16 v[6:9], v[160:163], v[224:227], v[6:9]
	v_mfma_f32_16x16x32_bf16 v[2:5], v[168:171], v[224:227], v[2:5]
	v_mfma_f32_16x16x32_bf16 v[50:53], v[164:167], v[194:197], v[50:53]
	v_mfma_f32_16x16x32_bf16 v[42:45], v[172:175], v[194:197], v[42:45]
	v_mfma_f32_16x16x32_bf16 v[34:37], v[164:167], v[212:215], v[34:37]
	v_mfma_f32_16x16x32_bf16 v[26:29], v[172:175], v[212:215], v[26:29]
	v_mfma_f32_16x16x32_bf16 v[18:21], v[164:167], v[220:223], v[18:21]
	v_mfma_f32_16x16x32_bf16 v[10:13], v[172:175], v[220:223], v[10:13]
	v_mfma_f32_16x16x32_bf16 v[6:9], v[164:167], v[228:231], v[6:9]
	v_mfma_f32_16x16x32_bf16 v[2:5], v[172:175], v[228:231], v[2:5]
	s_barrier
.LBB0_823:
	v_add_u32_e32 v140, s2, v142
	ds_read_b128 v[144:147], v140
	ds_read_b128 v[148:151], v140 offset:1024
	ds_read_b128 v[152:155], v140 offset:2048
	ds_read_b128 v[156:159], v140 offset:3072
	v_add_u32_e32 v140, s8, v142
	ds_read_b128 v[160:163], v140
	ds_read_b128 v[164:167], v140 offset:1024
	ds_read_b128 v[168:171], v140 offset:2048
	ds_read_b128 v[172:175], v140 offset:3072
	v_lshl_add_u64 v[140:141], s[44:45], 0, v[136:137]
	s_add_i32 m0, s4, 0xc000
	ds_read_b128 v[190:193], v143
	ds_read_b128 v[194:197], v143 offset:1024
	ds_read_b128 v[198:201], v143 offset:2048
	ds_read_b128 v[212:215], v143 offset:3072
	ds_read_b128 v[216:219], v143 offset:4096
	ds_read_b128 v[220:223], v143 offset:5120
	ds_read_b128 v[224:227], v143 offset:6144
	ds_read_b128 v[228:231], v143 offset:7168
	global_load_lds_dwordx4 v[140:141], off
	v_lshl_add_u64 v[140:141], s[44:45], 0, v[138:139]
	s_add_i32 m0, s4, 0xe000
	s_nop 0
	global_load_lds_dwordx4 v[140:141], off
	s_waitcnt vmcnt(8)
	s_waitcnt lgkmcnt(0)
	s_barrier
; #define PG8_STAGE(bufoff, gbase, voff) do { _Pragma("unroll") for (int _i = 0; _i < 2; ++_i) \
;         __builtin_amdgcn_global_load_lds((const unsigned*)((const char*)(gbase) + (voff)[_i]), (PG8_LAS unsigned*)(lds + (bufoff) + ldsw + _i * 8192), 16, 0, 0); } while (0)
; #define PG8_LDA(dst, b, h) do { _Pragma("unroll") for (int m = 0; m < 4; ++m) _Pragma("unroll") for (int k = 0; k < 2; ++k) dst[m][k] = *(const PG8_LAS bf16x8*)(lds + PG8_SA(b, h) + aoff + m * 2048 + k * 1024); } while (0)
; #define PG8_MMA(ai, bj, At, Bt) do { __builtin_amdgcn_s_setprio(1); _Pragma("unroll") for (int m = 0; m < 4; ++m) _Pragma("unroll") for (int n = 0; n < 2; ++n) _Pragma("unroll") for (int k = 0; k < 2; ++k) \
;         acc[ai][bj][m][n] = __builtin_amdgcn_mfma_f32_16x16x32_bf16(Bt[n][k], At[m][k], acc[ai][bj][m][n], 0, 0, 0); __builtin_amdgcn_s_setprio(0); } while (0)
; #define PG8_WAIT_V(n) asm volatile("s_waitcnt vmcnt(" #n ")" ::: "memory")
; #define PG8_WAIT_L(n) asm volatile("s_waitcnt lgkmcnt(" #n ")" ::: "memory")
; #define PG8_BAR __builtin_amdgcn_s_barrier()
; #define PG8_SCHED __builtin_amdgcn_sched_barrier(0)
; template <class Epi, class Sched, bool ALIGN_EPI = false, bool SP2 = false>
; __device__ __forceinline__ void gemm_phase(PG8_LAS unsigned char* lds, const Gemm g, const Sched& S, const Epi& E, const int wid_in) {
;     ...
;             PG8_WAIT_V(8); PG8_WAIT_L(0); PG8_BAR; PG8_MMA(0, 0, At, B0); PG8_MMA(0, 1, At, B1); PG8_BAR; PG8_SCHED;
;             PG8_LDA(At, 0, 1); PG8_STAGE(PG8_SB(0, 0), b2, voffB); PG8_STAGE(PG8_SB(0, 1), b2 + hstep, voffB); PG8_STAGE(PG8_SA(0, 0), a2, voffA);
;             PG8_WAIT_V(8); PG8_WAIT_L(0); PG8_BAR; PG8_MMA(1, 0, At, B0); PG8_MMA(1, 1, At, B1); PG8_BAR; PG8_SCHED;
	s_waitcnt lgkmcnt(0)
	v_mfma_f32_16x16x32_bf16 v[126:129], v[144:147], v[190:193], v[126:129]
	v_mfma_f32_16x16x32_bf16 v[122:125], v[152:155], v[190:193], v[122:125]
	v_mfma_f32_16x16x32_bf16 v[118:121], v[144:147], v[198:201], v[118:121]
	v_mfma_f32_16x16x32_bf16 v[110:113], v[152:155], v[198:201], v[110:113]
	v_mfma_f32_16x16x32_bf16 v[102:105], v[144:147], v[216:219], v[102:105]
	v_mfma_f32_16x16x32_bf16 v[94:97], v[152:155], v[216:219], v[94:97]
	v_mfma_f32_16x16x32_bf16 v[82:85], v[144:147], v[224:227], v[82:85]
	v_mfma_f32_16x16x32_bf16 v[74:77], v[152:155], v[224:227], v[74:77]
	v_mfma_f32_16x16x32_bf16 v[126:129], v[148:151], v[194:197], v[126:129]
	v_mfma_f32_16x16x32_bf16 v[122:125], v[156:159], v[194:197], v[122:125]
	v_mfma_f32_16x16x32_bf16 v[118:121], v[148:151], v[212:215], v[118:121]
	v_mfma_f32_16x16x32_bf16 v[110:113], v[156:159], v[212:215], v[110:113]
	v_mfma_f32_16x16x32_bf16 v[102:105], v[148:151], v[220:223], v[102:105]
	v_mfma_f32_16x16x32_bf16 v[94:97], v[156:159], v[220:223], v[94:97]
	v_mfma_f32_16x16x32_bf16 v[82:85], v[148:151], v[228:231], v[82:85]
	v_mfma_f32_16x16x32_bf16 v[74:77], v[156:159], v[228:231], v[74:77]
	v_mfma_f32_16x16x32_bf16 v[114:117], v[160:163], v[190:193], v[114:117]
	v_mfma_f32_16x16x32_bf16 v[106:109], v[168:171], v[190:193], v[106:109]
	v_mfma_f32_16x16x32_bf16 v[98:101], v[160:163], v[198:201], v[98:101]
	v_mfma_f32_16x16x32_bf16 v[90:93], v[168:171], v[198:201], v[90:93]
	v_mfma_f32_16x16x32_bf16 v[86:89], v[160:163], v[216:219], v[86:89]
	v_mfma_f32_16x16x32_bf16 v[78:81], v[168:171], v[216:219], v[78:81]
	v_mfma_f32_16x16x32_bf16 v[70:73], v[160:163], v[224:227], v[70:73]
	v_mfma_f32_16x16x32_bf16 v[66:69], v[168:171], v[224:227], v[66:69]
	v_mfma_f32_16x16x32_bf16 v[114:117], v[164:167], v[194:197], v[114:117]
	v_mfma_f32_16x16x32_bf16 v[106:109], v[172:175], v[194:197], v[106:109]
	v_mfma_f32_16x16x32_bf16 v[98:101], v[164:167], v[212:215], v[98:101]
	v_mfma_f32_16x16x32_bf16 v[90:93], v[172:175], v[212:215], v[90:93]
	v_mfma_f32_16x16x32_bf16 v[86:89], v[164:167], v[220:223], v[86:89]
	v_mfma_f32_16x16x32_bf16 v[78:81], v[172:175], v[220:223], v[78:81]
	v_mfma_f32_16x16x32_bf16 v[70:73], v[164:167], v[228:231], v[70:73]
	v_mfma_f32_16x16x32_bf16 v[66:69], v[172:175], v[228:231], v[66:69]
	s_barrier
	s_add_i32 s2, s2, s3
	v_lshl_add_u64 v[140:141], s[48:49], 0, v[0:1]
	s_mov_b32 m0, s2
	ds_read_b128 v[190:193], v143 offset:16384
	ds_read_b128 v[194:197], v143 offset:17408
	ds_read_b128 v[198:201], v143 offset:18432
	ds_read_b128 v[212:215], v143 offset:19456
	ds_read_b128 v[216:219], v143 offset:20480
	ds_read_b128 v[220:223], v143 offset:21504
	ds_read_b128 v[224:227], v143 offset:22528
	ds_read_b128 v[228:231], v143 offset:23552
	global_load_lds_dwordx4 v[140:141], off
	s_add_i32 m0, s2, 0x2000
	s_add_u32 s22, s48, 0xb0000
	v_lshl_add_u64 v[176:177], s[48:49], 0, v[130:131]
	s_addc_u32 s23, s49, 0
	s_add_i32 s2, s8, s3
	global_load_lds_dwordx4 v[176:177], off
	v_lshl_add_u64 v[232:233], s[22:23], 0, v[0:1]
	s_mov_b32 m0, s2
	v_lshl_add_u64 v[234:235], s[50:51], 0, v[132:133]
	global_load_lds_dwordx4 v[232:233], off
	v_lshl_add_u64 v[232:233], s[22:23], 0, v[130:131]
	s_add_i32 m0, s2, 0x2000
	s_nop 0
	global_load_lds_dwordx4 v[232:233], off
	v_lshl_add_u64 v[232:233], s[50:51], 0, v[134:135]
	s_mov_b32 m0, s4
	s_nop 0
	global_load_lds_dwordx4 v[232:233], off
	s_mov_b32 m0, s5
	s_nop 0
	global_load_lds_dwordx4 v[234:235], off
	s_waitcnt vmcnt(8)
	s_waitcnt lgkmcnt(0)
	s_barrier
	s_waitcnt lgkmcnt(0)
	v_mfma_f32_16x16x32_bf16 v[62:65], v[144:147], v[190:193], v[62:65]
	v_mfma_f32_16x16x32_bf16 v[58:61], v[152:155], v[190:193], v[58:61]
	v_mfma_f32_16x16x32_bf16 v[54:57], v[144:147], v[198:201], v[54:57]
	v_mfma_f32_16x16x32_bf16 v[46:49], v[152:155], v[198:201], v[46:49]
	v_mfma_f32_16x16x32_bf16 v[38:41], v[144:147], v[216:219], v[38:41]
	v_mfma_f32_16x16x32_bf16 v[30:33], v[152:155], v[216:219], v[30:33]
	v_mfma_f32_16x16x32_bf16 v[22:25], v[144:147], v[224:227], v[22:25]
	v_mfma_f32_16x16x32_bf16 v[14:17], v[152:155], v[224:227], v[14:17]
	v_mfma_f32_16x16x32_bf16 v[62:65], v[148:151], v[194:197], v[62:65]
	v_mfma_f32_16x16x32_bf16 v[58:61], v[156:159], v[194:197], v[58:61]
	v_mfma_f32_16x16x32_bf16 v[54:57], v[148:151], v[212:215], v[54:57]
	v_mfma_f32_16x16x32_bf16 v[46:49], v[156:159], v[212:215], v[46:49]
	v_mfma_f32_16x16x32_bf16 v[38:41], v[148:151], v[220:223], v[38:41]
	v_mfma_f32_16x16x32_bf16 v[30:33], v[156:159], v[220:223], v[30:33]
	v_mfma_f32_16x16x32_bf16 v[22:25], v[148:151], v[228:231], v[22:25]
	v_mfma_f32_16x16x32_bf16 v[14:17], v[156:159], v[228:231], v[14:17]
	v_mfma_f32_16x16x32_bf16 v[50:53], v[160:163], v[190:193], v[50:53]
	v_mfma_f32_16x16x32_bf16 v[42:45], v[168:171], v[190:193], v[42:45]
	v_mfma_f32_16x16x32_bf16 v[34:37], v[160:163], v[198:201], v[34:37]
	v_mfma_f32_16x16x32_bf16 v[26:29], v[168:171], v[198:201], v[26:29]
	v_mfma_f32_16x16x32_bf16 v[18:21], v[160:163], v[216:219], v[18:21]
	v_mfma_f32_16x16x32_bf16 v[10:13], v[168:171], v[216:219], v[10:13]
	v_mfma_f32_16x16x32_bf16 v[6:9], v[160:163], v[224:227], v[6:9]
	v_mfma_f32_16x16x32_bf16 v[2:5], v[168:171], v[224:227], v[2:5]
	v_mfma_f32_16x16x32_bf16 v[50:53], v[164:167], v[194:197], v[50:53]
	v_mfma_f32_16x16x32_bf16 v[42:45], v[172:175], v[194:197], v[42:45]
	v_mfma_f32_16x16x32_bf16 v[34:37], v[164:167], v[212:215], v[34:37]
	v_mfma_f32_16x16x32_bf16 v[26:29], v[172:175], v[212:215], v[26:29]
	v_mfma_f32_16x16x32_bf16 v[18:21], v[164:167], v[220:223], v[18:21]
	v_mfma_f32_16x16x32_bf16 v[10:13], v[172:175], v[220:223], v[10:13]
	v_mfma_f32_16x16x32_bf16 v[6:9], v[164:167], v[228:231], v[6:9]
	v_mfma_f32_16x16x32_bf16 v[2:5], v[172:175], v[228:231], v[2:5]
	s_barrier
; #define PG8_STAGE(bufoff, gbase, voff) do { _Pragma("unroll") for (int _i = 0; _i < 2; ++_i) \
;         __builtin_amdgcn_global_load_lds((const unsigned*)((const char*)(gbase) + (voff)[_i]), (PG8_LAS unsigned*)(lds + (bufoff) + ldsw + _i * 8192), 16, 0, 0); } while (0)
; #define PG8_LDA(dst, b, h) do { _Pragma("unroll") for (int m = 0; m < 4; ++m) _Pragma("unroll") for (int k = 0; k < 2; ++k) dst[m][k] = *(const PG8_LAS bf16x8*)(lds + PG8_SA(b, h) + aoff + m * 2048 + k * 1024); } while (0)
; #define PG8_LDB(dst, b, h) do { _Pragma("unroll") for (int n = 0; n < 2; ++n) _Pragma("unroll") for (int k = 0; k < 2; ++k) dst[n][k] = *(const PG8_LAS bf16x8*)(lds + PG8_SB(b, h) + boff + n * 2048 + k * 1024); } while (0)
; #define PG8_MMA(ai, bj, At, Bt) do { __builtin_amdgcn_s_setprio(1); _Pragma("unroll") for (int m = 0; m < 4; ++m) _Pragma("unroll") for (int n = 0; n < 2; ++n) _Pragma("unroll") for (int k = 0; k < 2; ++k) \
;         acc[ai][bj][m][n] = __builtin_amdgcn_mfma_f32_16x16x32_bf16(Bt[n][k], At[m][k], acc[ai][bj][m][n], 0, 0, 0); __builtin_amdgcn_s_setprio(0); } while (0)
; #define PG8_WAIT_V(n) asm volatile("s_waitcnt vmcnt(" #n ")" ::: "memory")
; #define PG8_WAIT_L(n) asm volatile("s_waitcnt lgkmcnt(" #n ")" ::: "memory")
; #define PG8_BAR __builtin_amdgcn_s_barrier()
; #define PG8_SCHED __builtin_amdgcn_sched_barrier(0)
; template <class Epi, class Sched, bool ALIGN_EPI = false, bool SP2 = false>
; __device__ __forceinline__ void gemm_phase(PG8_LAS unsigned char* lds, const Gemm g, const Sched& S, const Epi& E, const int wid_in) {
;     ...
;             PG8_LDB(B0, 1, 0); PG8_LDB(B1, 1, 1); PG8_SCHED; PG8_LDA(At, 1, 0); PG8_STAGE(PG8_SA(0, 1), a2 + hstep, voffA);
;             PG8_WAIT_V(8); PG8_WAIT_L(0); PG8_BAR; PG8_MMA(0, 0, At, B0); PG8_MMA(0, 1, At, B1); PG8_BAR; PG8_SCHED;
	s_add_i32 s2, 0, 0x18000
	s_add_i32 s8, 0, 0x1c000
	v_add_u32_e32 v156, s2, v142
	v_add_u32_e32 v172, s8, v142
	ds_read_b128 v[144:147], v156
	ds_read_b128 v[148:151], v156 offset:1024
	ds_read_b128 v[152:155], v156 offset:2048
	ds_read_b128 v[156:159], v156 offset:3072
	ds_read_b128 v[160:163], v172
	ds_read_b128 v[164:167], v172 offset:1024
	ds_read_b128 v[168:171], v172 offset:2048
	ds_read_b128 v[172:175], v172 offset:3072
	s_add_u32 s22, s50, 0xb0000
	s_addc_u32 s23, s51, 0
	s_mov_b32 m0, s12
	v_lshl_add_u64 v[236:237], s[22:23], 0, v[134:135]
	ds_read_b128 v[190:193], v143 offset:32768
	ds_read_b128 v[194:197], v143 offset:33792
	ds_read_b128 v[198:201], v143 offset:34816
	ds_read_b128 v[212:215], v143 offset:35840
	ds_read_b128 v[216:219], v143 offset:36864
	ds_read_b128 v[220:223], v143 offset:37888
	ds_read_b128 v[224:227], v143 offset:38912
	ds_read_b128 v[228:231], v143 offset:39936
	global_load_lds_dwordx4 v[236:237], off
	v_lshl_add_u64 v[236:237], s[22:23], 0, v[132:133]
	s_mov_b32 m0, s13
	s_nop 0
	global_load_lds_dwordx4 v[236:237], off
	s_waitcnt vmcnt(8)
	s_waitcnt lgkmcnt(0)
	s_barrier
	s_waitcnt lgkmcnt(0)
	v_mfma_f32_16x16x32_bf16 v[126:129], v[144:147], v[190:193], v[126:129]
	v_mfma_f32_16x16x32_bf16 v[122:125], v[152:155], v[190:193], v[122:125]
	v_mfma_f32_16x16x32_bf16 v[118:121], v[144:147], v[198:201], v[118:121]
	v_mfma_f32_16x16x32_bf16 v[110:113], v[152:155], v[198:201], v[110:113]
	v_mfma_f32_16x16x32_bf16 v[102:105], v[144:147], v[216:219], v[102:105]
	v_mfma_f32_16x16x32_bf16 v[94:97], v[152:155], v[216:219], v[94:97]
	v_mfma_f32_16x16x32_bf16 v[82:85], v[144:147], v[224:227], v[82:85]
	v_mfma_f32_16x16x32_bf16 v[74:77], v[152:155], v[224:227], v[74:77]
	v_mfma_f32_16x16x32_bf16 v[126:129], v[148:151], v[194:197], v[126:129]
	v_mfma_f32_16x16x32_bf16 v[122:125], v[156:159], v[194:197], v[122:125]
	v_mfma_f32_16x16x32_bf16 v[118:121], v[148:151], v[212:215], v[118:121]
	v_mfma_f32_16x16x32_bf16 v[110:113], v[156:159], v[212:215], v[110:113]
	v_mfma_f32_16x16x32_bf16 v[102:105], v[148:151], v[220:223], v[102:105]
	v_mfma_f32_16x16x32_bf16 v[94:97], v[156:159], v[220:223], v[94:97]
	v_mfma_f32_16x16x32_bf16 v[82:85], v[148:151], v[228:231], v[82:85]
	v_mfma_f32_16x16x32_bf16 v[74:77], v[156:159], v[228:231], v[74:77]
	v_mfma_f32_16x16x32_bf16 v[114:117], v[160:163], v[190:193], v[114:117]
	v_mfma_f32_16x16x32_bf16 v[106:109], v[168:171], v[190:193], v[106:109]
	v_mfma_f32_16x16x32_bf16 v[98:101], v[160:163], v[198:201], v[98:101]
	v_mfma_f32_16x16x32_bf16 v[90:93], v[168:171], v[198:201], v[90:93]
	v_mfma_f32_16x16x32_bf16 v[86:89], v[160:163], v[216:219], v[86:89]
	v_mfma_f32_16x16x32_bf16 v[78:81], v[168:171], v[216:219], v[78:81]
	v_mfma_f32_16x16x32_bf16 v[70:73], v[160:163], v[224:227], v[70:73]
	v_mfma_f32_16x16x32_bf16 v[66:69], v[168:171], v[224:227], v[66:69]
	v_mfma_f32_16x16x32_bf16 v[114:117], v[164:167], v[194:197], v[114:117]
	v_mfma_f32_16x16x32_bf16 v[106:109], v[172:175], v[194:197], v[106:109]
	v_mfma_f32_16x16x32_bf16 v[98:101], v[164:167], v[212:215], v[98:101]
	v_mfma_f32_16x16x32_bf16 v[90:93], v[172:175], v[212:215], v[90:93]
	v_mfma_f32_16x16x32_bf16 v[86:89], v[164:167], v[220:223], v[86:89]
	v_mfma_f32_16x16x32_bf16 v[78:81], v[172:175], v[220:223], v[78:81]
	v_mfma_f32_16x16x32_bf16 v[70:73], v[164:167], v[228:231], v[70:73]
	v_mfma_f32_16x16x32_bf16 v[66:69], v[172:175], v[228:231], v[66:69]
	s_barrier
; #define PG8_STAGE(bufoff, gbase, voff) do { _Pragma("unroll") for (int _i = 0; _i < 2; ++_i) \
;         __builtin_amdgcn_global_load_lds((const unsigned*)((const char*)(gbase) + (voff)[_i]), (PG8_LAS unsigned*)(lds + (bufoff) + ldsw + _i * 8192), 16, 0, 0); } while (0)
; #define PG8_LDA(dst, b, h) do { _Pragma("unroll") for (int m = 0; m < 4; ++m) _Pragma("unroll") for (int k = 0; k < 2; ++k) dst[m][k] = *(const PG8_LAS bf16x8*)(lds + PG8_SA(b, h) + aoff + m * 2048 + k * 1024); } while (0)
; #define PG8_WAIT_V(n) asm volatile("s_waitcnt vmcnt(" #n ")" ::: "memory")
; #define PG8_WAIT_L(n) asm volatile("s_waitcnt lgkmcnt(" #n ")" ::: "memory")
; #define PG8_BAR __builtin_amdgcn_s_barrier()
; template <class Epi, class Sched, bool ALIGN_EPI = false, bool SP2 = false>
; __device__ __forceinline__ void gemm_phase(PG8_LAS unsigned char* lds, const Gemm g, const Sched& S, const Epi& E, const int wid_in) {
;     ...
;         for (int t = 0; t < nt; t += 2) {
;             const bool last = (t == nt - 2);
;             const char* a1 = cA + (size_t)(t + 1) * kstep;
;             const char* a2 = last ? nA : cA + (size_t)(t + 2) * kstep; const char* b2 = last ? nB : cB + (size_t)(t + 2) * kstep;
;             const char* a3 = a2 + kstep; const char* b3 = b2 + kstep;
;             if (last && has_next) S.a_ready(nxt);
;             if constexpr (SP2) {
;             PG8_LDB(B0, 0, 0); PG8_LDB(B1, 0, 1); PG8_SCHED; PG8_LDA(At, 0, 0); PG8_STAGE(PG8_SA(1, 1), a1 + hstep, voffA);
;             PG8_WAIT_V(8); PG8_WAIT_L(0); PG8_BAR; PG8_MMA(0, 0, At, B0); PG8_MMA(0, 1, At, B1); PG8_BAR; PG8_SCHED;
;             PG8_LDA(At, 0, 1); PG8_STAGE(PG8_SB(0, 0), b2, voffB); PG8_STAGE(PG8_SB(0, 1), b2 + hstep, voffB); PG8_STAGE(PG8_SA(0, 0), a2, voffA);
;             PG8_WAIT_V(8); PG8_WAIT_L(0); PG8_BAR; PG8_MMA(1, 0, At, B0); PG8_MMA(1, 1, At, B1); PG8_BAR; PG8_SCHED;
;             PG8_LDB(B0, 1, 0); PG8_LDB(B1, 1, 1); PG8_SCHED; PG8_LDA(At, 1, 0); PG8_STAGE(PG8_SA(0, 1), a2 + hstep, voffA);
;             PG8_WAIT_V(8); PG8_WAIT_L(0); PG8_BAR; PG8_MMA(0, 0, At, B0); PG8_MMA(0, 1, At, B1); PG8_BAR; PG8_SCHED;
;             PG8_LDA(At, 1, 1); PG8_STAGE(PG8_SB(1, 0), b3, voffB); PG8_STAGE(PG8_SB(1, 1), b3 + hstep, voffB); PG8_STAGE(PG8_SA(1, 0), a3, voffA);
;             PG8_WAIT_V(8); PG8_WAIT_L(0); PG8_BAR; PG8_MMA(1, 0, At, B0); PG8_MMA(1, 1, At, B1); PG8_BAR; PG8_SCHED;
	s_add_i32 s2, s2, s3
	v_lshl_add_u64 v[140:141], v[140:141], 0, s[64:65]
	s_mov_b32 m0, s2
	ds_read_b128 v[190:193], v143 offset:49152
	ds_read_b128 v[194:197], v143 offset:50176
	ds_read_b128 v[198:201], v143 offset:51200
	ds_read_b128 v[212:215], v143 offset:52224
	ds_read_b128 v[216:219], v143 offset:53248
	ds_read_b128 v[220:223], v143 offset:54272
	ds_read_b128 v[224:227], v143 offset:55296
	ds_read_b128 v[228:231], v143 offset:56320
	global_load_lds_dwordx4 v[140:141], off
	s_add_i32 m0, s2, 0x2000
	s_add_u32 s22, s48, 0xb0080
	v_lshl_add_u64 v[140:141], v[176:177], 0, s[64:65]
	s_addc_u32 s23, s49, 0
	s_add_i32 s2, s8, s3
	global_load_lds_dwordx4 v[140:141], off
	v_lshl_add_u64 v[140:141], s[22:23], 0, v[0:1]
	s_mov_b32 m0, s2
	s_nop 0
	global_load_lds_dwordx4 v[140:141], off
	v_lshl_add_u64 v[140:141], s[22:23], 0, v[130:131]
	s_add_i32 m0, s2, 0x2000
	s_nop 0
	global_load_lds_dwordx4 v[140:141], off
	v_lshl_add_u64 v[140:141], v[232:233], 0, s[64:65]
	s_mov_b32 m0, s36
	s_nop 0
	global_load_lds_dwordx4 v[140:141], off
	v_lshl_add_u64 v[140:141], v[234:235], 0, s[64:65]
	s_mov_b32 m0, s37
	s_nop 0
	global_load_lds_dwordx4 v[140:141], off
	s_add_i32 s58, s58, 2
	s_add_u32 s16, s16, 0x100
	s_addc_u32 s57, s57, 0
	s_mov_b64 s[44:45], s[46:47]
	s_add_u32 s46, s44, 0x100
	s_addc_u32 s47, s45, 0
	s_add_i32 s2, 0, 0x10000
	s_cmp_eq_u32 s58, 40
	s_cselect_b32 s51, s41, s47
	s_cselect_b32 s50, s40, s46
	s_cselect_b32 s49, s43, s57
	s_cselect_b32 s48, s42, s16
	s_add_i32 s8, 0, 0x14000
	s_cmp_gt_u32 s58, 41
	s_waitcnt vmcnt(8)
	s_waitcnt lgkmcnt(0)
	s_barrier
	s_waitcnt lgkmcnt(0)
	v_mfma_f32_16x16x32_bf16 v[62:65], v[144:147], v[190:193], v[62:65]
	v_mfma_f32_16x16x32_bf16 v[58:61], v[152:155], v[190:193], v[58:61]
	v_mfma_f32_16x16x32_bf16 v[54:57], v[144:147], v[198:201], v[54:57]
	v_mfma_f32_16x16x32_bf16 v[46:49], v[152:155], v[198:201], v[46:49]
	v_mfma_f32_16x16x32_bf16 v[38:41], v[144:147], v[216:219], v[38:41]
	v_mfma_f32_16x16x32_bf16 v[30:33], v[152:155], v[216:219], v[30:33]
	v_mfma_f32_16x16x32_bf16 v[22:25], v[144:147], v[224:227], v[22:25]
	v_mfma_f32_16x16x32_bf16 v[14:17], v[152:155], v[224:227], v[14:17]
	v_mfma_f32_16x16x32_bf16 v[62:65], v[148:151], v[194:197], v[62:65]
	v_mfma_f32_16x16x32_bf16 v[58:61], v[156:159], v[194:197], v[58:61]
	v_mfma_f32_16x16x32_bf16 v[54:57], v[148:151], v[212:215], v[54:57]
	v_mfma_f32_16x16x32_bf16 v[46:49], v[156:159], v[212:215], v[46:49]
	v_mfma_f32_16x16x32_bf16 v[38:41], v[148:151], v[220:223], v[38:41]
	v_mfma_f32_16x16x32_bf16 v[30:33], v[156:159], v[220:223], v[30:33]
	v_mfma_f32_16x16x32_bf16 v[22:25], v[148:151], v[228:231], v[22:25]
	v_mfma_f32_16x16x32_bf16 v[14:17], v[156:159], v[228:231], v[14:17]
	v_mfma_f32_16x16x32_bf16 v[50:53], v[160:163], v[190:193], v[50:53]
	v_mfma_f32_16x16x32_bf16 v[42:45], v[168:171], v[190:193], v[42:45]
	v_mfma_f32_16x16x32_bf16 v[34:37], v[160:163], v[198:201], v[34:37]
	v_mfma_f32_16x16x32_bf16 v[26:29], v[168:171], v[198:201], v[26:29]
	v_mfma_f32_16x16x32_bf16 v[18:21], v[160:163], v[216:219], v[18:21]
	v_mfma_f32_16x16x32_bf16 v[10:13], v[168:171], v[216:219], v[10:13]
	v_mfma_f32_16x16x32_bf16 v[6:9], v[160:163], v[224:227], v[6:9]
	v_mfma_f32_16x16x32_bf16 v[2:5], v[168:171], v[224:227], v[2:5]
	v_mfma_f32_16x16x32_bf16 v[50:53], v[164:167], v[194:197], v[50:53]
	v_mfma_f32_16x16x32_bf16 v[42:45], v[172:175], v[194:197], v[42:45]
	v_mfma_f32_16x16x32_bf16 v[34:37], v[164:167], v[212:215], v[34:37]
	v_mfma_f32_16x16x32_bf16 v[26:29], v[172:175], v[212:215], v[26:29]
	v_mfma_f32_16x16x32_bf16 v[18:21], v[164:167], v[220:223], v[18:21]
	v_mfma_f32_16x16x32_bf16 v[10:13], v[172:175], v[220:223], v[10:13]
	v_mfma_f32_16x16x32_bf16 v[6:9], v[164:167], v[228:231], v[6:9]
	v_mfma_f32_16x16x32_bf16 v[2:5], v[172:175], v[228:231], v[2:5]
	s_barrier
	s_cbranch_scc0 .LBB0_823
	s_setprio 0
	v_readlane_b32 s8, v243, 63
	v_readlane_b32 s9, v242, 0
	s_and_b64 vcc, exec, s[8:9]
	s_cbranch_vccz .LBB0_826
	s_barrier
